# v9_rcp
# speedup vs baseline: 1.0406x; 1.0128x over previous
; __device__ __forceinline__ float sigmoidf_(float x) { return 1.f / (1.f + __expf(-x)); }
; __device__ void phase1(const Params& p) {
;     ...
;       char* gt = p.GT + ((size_t)((d.pm * 16 + ((d.pn - 64) & 15)) * 2 + ((d.pn - 64) >> 4))) * 131072 + tid * 16;
; #pragma unroll
;       for (int ai = 0; ai < 2; ++ai)
; #pragma unroll
;         for (int bj = 0; bj < 2; ++bj)
; #pragma unroll
;           for (int m = 0; m < 4; ++m) {
;             u32x4 o;
; #pragma unroll
;             for (int n = 0; n < 2; ++n) {
;               o[2 * n] = pack2(sigmoidf_(acc[ai][bj][m][n][0]), sigmoidf_(acc[ai][bj][m][n][1]));
;               o[2 * n + 1] = pack2(sigmoidf_(acc[ai][bj][m][n][2]), sigmoidf_(acc[ai][bj][m][n][3]));
;             }
;             __builtin_nontemporal_store(o, (u32x4*)(gt + ((ai * 2 + bj) * 4 + m) * 8192));
;           }
.LBB0_77:
	s_andn2_b64 vcc, exec, s[0:1]
	s_cbranch_vccnz .LBB0_79
	v_mul_f32_e32 v128, 0xbfb8aa3b, v16
	v_mul_f32_e32 v129, 0xbfb8aa3b, v17
	s_lshl_b32 s8, s89, 1
	v_exp_f32_e32 v128, v128
	v_exp_f32_e32 v129, v129
	s_sub_i32 s0, s89, 64
	s_lshl_b32 s1, s11, 5
	s_and_b32 s8, s8, 30
	s_or_b32 s1, s8, s1
	s_lshr_b32 s0, s0, 4
	s_add_i32 s28, s1, s0
	s_lshl_b64 s[0:1], s[28:29], 17
	v_pk_add_f32 v[128:129], v[128:129], 1.0 op_sel_hi:[1,0]
	v_lshl_add_u64 v[138:139], v[134:135], 0, s[0:1]
	v_mul_f32_e32 v124, 0xbfb8aa3b, v124
	v_mul_f32_e32 v125, 0xbfb8aa3b, v125
	v_exp_f32_e32 v124, v124
	v_rcp_f32_e32 v129, v129
	s_nop 0
	v_exp_f32_e32 v125, v125
	v_mul_f32_e32 v120, 0xbfb8aa3b, v120
	v_mul_f32_e32 v121, 0xbfb8aa3b, v121
	v_rcp_f32_e32 v128, v128
	s_nop 0
	v_cvt_pk_bf16_f32 v128, v128, v129
	v_mul_f32_e32 v129, 0xbfb8aa3b, v18
	v_exp_f32_e32 v130, v129
	v_mul_f32_e32 v129, 0xbfb8aa3b, v19
	v_exp_f32_e32 v131, v129
	v_pk_add_f32 v[124:125], v[124:125], 1.0 op_sel_hi:[1,0]
	v_exp_f32_e32 v120, v120
	v_exp_f32_e32 v121, v121
	v_pk_add_f32 v[130:131], v[130:131], 1.0 op_sel_hi:[1,0]
	v_mul_f32_e32 v116, 0xbfb8aa3b, v116
	v_pk_add_f32 v[120:121], v[120:121], 1.0 op_sel_hi:[1,0]
	v_mul_f32_e32 v117, 0xbfb8aa3b, v117
	v_exp_f32_e32 v116, v116
	v_rcp_f32_e32 v129, v131
	s_nop 0
	v_exp_f32_e32 v117, v117
	v_mul_f32_e32 v112, 0xbfb8aa3b, v112
	v_mul_f32_e32 v113, 0xbfb8aa3b, v113
	v_rcp_f32_e32 v130, v130
	s_nop 0
	v_cvt_pk_bf16_f32 v129, v130, v129
	v_mul_f32_e32 v130, 0xbfb8aa3b, v20
	v_mul_f32_e32 v131, 0xbfb8aa3b, v21
	v_exp_f32_e32 v130, v130
	v_exp_f32_e32 v131, v131
	v_pk_add_f32 v[116:117], v[116:117], 1.0 op_sel_hi:[1,0]
	v_exp_f32_e32 v112, v112
	v_exp_f32_e32 v113, v113
	v_pk_add_f32 v[130:131], v[130:131], 1.0 op_sel_hi:[1,0]
	v_mul_f32_e32 v108, 0xbfb8aa3b, v108
	v_pk_add_f32 v[112:113], v[112:113], 1.0 op_sel_hi:[1,0]
	v_mul_f32_e32 v109, 0xbfb8aa3b, v109
	v_exp_f32_e32 v108, v108
	v_rcp_f32_e32 v131, v131
	s_nop 0
	v_exp_f32_e32 v109, v109
	v_mul_f32_e32 v104, 0xbfb8aa3b, v104
	v_mul_f32_e32 v105, 0xbfb8aa3b, v105
	v_rcp_f32_e32 v130, v130
	s_nop 0
	v_cvt_pk_bf16_f32 v130, v130, v131
	v_mul_f32_e32 v131, 0xbfb8aa3b, v22
	v_exp_f32_e32 v140, v131
	v_mul_f32_e32 v131, 0xbfb8aa3b, v23
	v_exp_f32_e32 v141, v131
	v_pk_add_f32 v[108:109], v[108:109], 1.0 op_sel_hi:[1,0]
	v_exp_f32_e32 v104, v104
	v_exp_f32_e32 v105, v105
	v_pk_add_f32 v[140:141], v[140:141], 1.0 op_sel_hi:[1,0]
	v_mul_f32_e32 v100, 0xbfb8aa3b, v100
	v_pk_add_f32 v[104:105], v[104:105], 1.0 op_sel_hi:[1,0]
	v_mul_f32_e32 v101, 0xbfb8aa3b, v101
	v_exp_f32_e32 v100, v100
	v_rcp_f32_e32 v131, v141
	s_nop 0
	v_exp_f32_e32 v101, v101
	v_mul_f32_e32 v96, 0xbfb8aa3b, v96
	v_mul_f32_e32 v97, 0xbfb8aa3b, v97
	v_rcp_f32_e32 v137, v140
	s_nop 0
	v_cvt_pk_bf16_f32 v131, v137, v131
	global_store_dwordx4 v[138:139], v[128:131], off nt
	v_pk_add_f32 v[100:101], v[100:101], 1.0 op_sel_hi:[1,0]
	v_exp_f32_e32 v96, v96
	v_mul_f32_e32 v128, 0xbfb8aa3b, v24
	v_mul_f32_e32 v129, 0xbfb8aa3b, v25
	v_exp_f32_e32 v128, v128
	v_exp_f32_e32 v129, v129
	v_exp_f32_e32 v97, v97
	v_mul_f32_e32 v92, 0xbfb8aa3b, v92
	v_mul_f32_e32 v93, 0xbfb8aa3b, v93
	v_pk_add_f32 v[128:129], v[128:129], 1.0 op_sel_hi:[1,0]
	v_pk_add_f32 v[96:97], v[96:97], 1.0 op_sel_hi:[1,0]
	v_exp_f32_e32 v92, v92
	v_exp_f32_e32 v93, v93
	v_mul_f32_e32 v88, 0xbfb8aa3b, v88
	v_rcp_f32_e32 v129, v129
	s_nop 0
	v_pk_add_f32 v[92:93], v[92:93], 1.0 op_sel_hi:[1,0]
	v_mul_f32_e32 v89, 0xbfb8aa3b, v89
	v_exp_f32_e32 v88, v88
	v_rcp_f32_e32 v128, v128
	s_nop 0
	v_cvt_pk_bf16_f32 v128, v128, v129
	v_mul_f32_e32 v129, 0xbfb8aa3b, v26
	v_exp_f32_e32 v130, v129
	v_mul_f32_e32 v129, 0xbfb8aa3b, v27
	v_exp_f32_e32 v131, v129
	v_exp_f32_e32 v89, v89
	v_mul_f32_e32 v84, 0xbfb8aa3b, v84
	v_mul_f32_e32 v85, 0xbfb8aa3b, v85
	v_pk_add_f32 v[130:131], v[130:131], 1.0 op_sel_hi:[1,0]
	v_pk_add_f32 v[88:89], v[88:89], 1.0 op_sel_hi:[1,0]
	v_exp_f32_e32 v84, v84
	v_exp_f32_e32 v85, v85
	v_mul_f32_e32 v80, 0xbfb8aa3b, v80
	v_rcp_f32_e32 v129, v131
	s_nop 0
	v_pk_add_f32 v[84:85], v[84:85], 1.0 op_sel_hi:[1,0]
	v_mul_f32_e32 v81, 0xbfb8aa3b, v81
	v_exp_f32_e32 v80, v80
	v_rcp_f32_e32 v130, v130
	s_nop 0
	v_cvt_pk_bf16_f32 v129, v130, v129
	v_mul_f32_e32 v130, 0xbfb8aa3b, v28
	v_mul_f32_e32 v131, 0xbfb8aa3b, v29
	v_exp_f32_e32 v130, v130
	v_exp_f32_e32 v131, v131
	v_exp_f32_e32 v81, v81
	v_mul_f32_e32 v76, 0xbfb8aa3b, v76
	v_mul_f32_e32 v77, 0xbfb8aa3b, v77
	v_pk_add_f32 v[130:131], v[130:131], 1.0 op_sel_hi:[1,0]
	v_pk_add_f32 v[80:81], v[80:81], 1.0 op_sel_hi:[1,0]
	v_exp_f32_e32 v76, v76
	v_exp_f32_e32 v77, v77
	v_mul_f32_e32 v72, 0xbfb8aa3b, v72
	v_rcp_f32_e32 v131, v131
	s_nop 0
	v_pk_add_f32 v[76:77], v[76:77], 1.0 op_sel_hi:[1,0]
	v_mul_f32_e32 v73, 0xbfb8aa3b, v73
	v_exp_f32_e32 v72, v72
	v_rcp_f32_e32 v130, v130
	s_nop 0
	v_cvt_pk_bf16_f32 v130, v130, v131
	v_mul_f32_e32 v131, 0xbfb8aa3b, v30
	v_exp_f32_e32 v140, v131
	v_mul_f32_e32 v131, 0xbfb8aa3b, v31
	v_exp_f32_e32 v141, v131
	v_exp_f32_e32 v73, v73
	v_mul_f32_e32 v68, 0xbfb8aa3b, v68
	v_mul_f32_e32 v69, 0xbfb8aa3b, v69
	v_pk_add_f32 v[140:141], v[140:141], 1.0 op_sel_hi:[1,0]
	v_pk_add_f32 v[72:73], v[72:73], 1.0 op_sel_hi:[1,0]
	v_exp_f32_e32 v68, v68
	v_exp_f32_e32 v69, v69
	v_mul_f32_e32 v64, 0xbfb8aa3b, v64
	v_rcp_f32_e32 v131, v141
	s_nop 0
	s_movk_i32 s0, 0x2000
	v_pk_add_f32 v[68:69], v[68:69], 1.0 op_sel_hi:[1,0]
	v_mul_f32_e32 v65, 0xbfb8aa3b, v65
	v_rcp_f32_e32 v137, v140
	s_nop 0
	v_add_co_u32_e32 v140, vcc, s0, v138
	v_cvt_pk_bf16_f32 v131, v137, v131
	s_nop 0
	v_addc_co_u32_e32 v141, vcc, 0, v139, vcc
	global_store_dwordx4 v[140:141], v[128:131], off nt
	v_exp_f32_e32 v64, v64
; __device__ __forceinline__ float sigmoidf_(float x) { return 1.f / (1.f + __expf(-x)); }
; __device__ void phase1(const Params& p) {
;     ...
;       char* gt = p.GT + ((size_t)((d.pm * 16 + ((d.pn - 64) & 15)) * 2 + ((d.pn - 64) >> 4))) * 131072 + tid * 16;
; #pragma unroll
;       for (int ai = 0; ai < 2; ++ai)
; #pragma unroll
;         for (int bj = 0; bj < 2; ++bj)
; #pragma unroll
;           for (int m = 0; m < 4; ++m) {
;             u32x4 o;
; #pragma unroll
;             for (int n = 0; n < 2; ++n) {
;               o[2 * n] = pack2(sigmoidf_(acc[ai][bj][m][n][0]), sigmoidf_(acc[ai][bj][m][n][1]));
;               o[2 * n + 1] = pack2(sigmoidf_(acc[ai][bj][m][n][2]), sigmoidf_(acc[ai][bj][m][n][3]));
;             }
;             __builtin_nontemporal_store(o, (u32x4*)(gt + ((ai * 2 + bj) * 4 + m) * 8192));
;           }
	v_exp_f32_e32 v65, v65
	v_mul_f32_e32 v128, 0xbfb8aa3b, v0
	v_mul_f32_e32 v129, 0xbfb8aa3b, v1
	v_exp_f32_e32 v128, v128
	v_exp_f32_e32 v129, v129
	v_pk_add_f32 v[64:65], v[64:65], 1.0 op_sel_hi:[1,0]
	v_pk_add_f32 v[128:129], v[128:129], 1.0 op_sel_hi:[1,0]
	s_nop 0
	s_nop 0
	v_rcp_f32_e32 v129, v129
	s_nop 0
	s_nop 0
	v_rcp_f32_e32 v128, v128
	s_nop 0
	v_cvt_pk_bf16_f32 v128, v128, v129
	v_mul_f32_e32 v129, 0xbfb8aa3b, v2
	v_exp_f32_e32 v130, v129
	v_mul_f32_e32 v129, 0xbfb8aa3b, v3
	v_exp_f32_e32 v131, v129
	s_nop 0
	v_pk_add_f32 v[130:131], v[130:131], 1.0 op_sel_hi:[1,0]
	s_nop 0
	s_nop 0
	v_rcp_f32_e32 v129, v131
	s_nop 0
	s_nop 0
	v_rcp_f32_e32 v130, v130
	s_nop 0
	v_cvt_pk_bf16_f32 v129, v130, v129
	v_mul_f32_e32 v130, 0xbfb8aa3b, v8
	v_mul_f32_e32 v131, 0xbfb8aa3b, v9
	v_exp_f32_e32 v130, v130
	v_exp_f32_e32 v131, v131
	s_nop 0
	v_pk_add_f32 v[130:131], v[130:131], 1.0 op_sel_hi:[1,0]
	s_nop 0
	s_nop 0
	v_rcp_f32_e32 v131, v131
	s_nop 0
	s_nop 0
	v_rcp_f32_e32 v130, v130
	s_nop 0
	v_cvt_pk_bf16_f32 v130, v130, v131
	v_mul_f32_e32 v131, 0xbfb8aa3b, v10
	v_exp_f32_e32 v140, v131
	v_mul_f32_e32 v131, 0xbfb8aa3b, v11
	v_exp_f32_e32 v141, v131
	s_nop 0
	v_pk_add_f32 v[140:141], v[140:141], 1.0 op_sel_hi:[1,0]
	s_nop 0
	s_nop 0
	v_rcp_f32_e32 v131, v141
	s_nop 0
	s_movk_i32 s0, 0x4000
	v_rcp_f32_e32 v137, v140
	s_nop 0
	v_add_co_u32_e32 v140, vcc, s0, v138
	v_cvt_pk_bf16_f32 v131, v137, v131
	s_nop 0
	v_addc_co_u32_e32 v141, vcc, 0, v139, vcc
	global_store_dwordx4 v[140:141], v[128:131], off nt
	s_nop 1
	v_mul_f32_e32 v128, 0xbfb8aa3b, v4
	v_mul_f32_e32 v129, 0xbfb8aa3b, v5
	v_exp_f32_e32 v128, v128
	v_exp_f32_e32 v129, v129
	s_nop 0
	v_pk_add_f32 v[128:129], v[128:129], 1.0 op_sel_hi:[1,0]
	s_nop 0
	s_nop 0
	v_rcp_f32_e32 v129, v129
	s_nop 0
	s_nop 0
	v_rcp_f32_e32 v128, v128
	s_nop 0
	v_cvt_pk_bf16_f32 v128, v128, v129
	v_mul_f32_e32 v129, 0xbfb8aa3b, v6
	v_exp_f32_e32 v130, v129
	v_mul_f32_e32 v129, 0xbfb8aa3b, v7
	v_exp_f32_e32 v131, v129
	s_nop 0
	v_pk_add_f32 v[130:131], v[130:131], 1.0 op_sel_hi:[1,0]
	s_nop 0
	s_nop 0
	v_rcp_f32_e32 v129, v131
	s_nop 0
	s_nop 0
	v_rcp_f32_e32 v130, v130
	s_nop 0
	v_cvt_pk_bf16_f32 v129, v130, v129
	v_mul_f32_e32 v130, 0xbfb8aa3b, v12
	v_mul_f32_e32 v131, 0xbfb8aa3b, v13
	v_exp_f32_e32 v130, v130
	v_exp_f32_e32 v131, v131
	s_nop 0
	v_pk_add_f32 v[130:131], v[130:131], 1.0 op_sel_hi:[1,0]
	s_nop 0
	s_nop 0
	v_rcp_f32_e32 v131, v131
	s_nop 0
	s_nop 0
	v_rcp_f32_e32 v130, v130
	s_nop 0
	v_cvt_pk_bf16_f32 v130, v130, v131
	v_mul_f32_e32 v131, 0xbfb8aa3b, v14
	v_exp_f32_e32 v140, v131
	v_mul_f32_e32 v131, 0xbfb8aa3b, v15
	v_exp_f32_e32 v141, v131
	s_nop 0
	v_pk_add_f32 v[140:141], v[140:141], 1.0 op_sel_hi:[1,0]
	s_nop 0
	s_nop 0
	v_rcp_f32_e32 v131, v141
	s_nop 0
	s_movk_i32 s0, 0x6000
	v_rcp_f32_e32 v137, v140
	s_nop 0
	v_add_co_u32_e32 v140, vcc, s0, v138
	v_cvt_pk_bf16_f32 v131, v137, v131
	s_nop 0
	v_addc_co_u32_e32 v141, vcc, 0, v139, vcc
	global_store_dwordx4 v[140:141], v[128:131], off nt
	s_nop 1
	s_nop 0
	v_rcp_f32_e32 v125, v125
	s_nop 0
	s_nop 0
	v_rcp_f32_e32 v124, v124
	s_nop 0
	v_cvt_pk_bf16_f32 v124, v124, v125
	v_mul_f32_e32 v125, 0xbfb8aa3b, v126
	v_exp_f32_e32 v126, v125
	v_mul_f32_e32 v125, 0xbfb8aa3b, v127
	v_exp_f32_e32 v127, v125
	s_nop 0
	v_pk_add_f32 v[126:127], v[126:127], 1.0 op_sel_hi:[1,0]
	s_nop 0
	s_nop 0
	v_rcp_f32_e32 v125, v127
	s_nop 0
	s_nop 0
	v_rcp_f32_e32 v126, v126
	s_nop 0
	v_cvt_pk_bf16_f32 v125, v126, v125
	s_nop 0
	v_rcp_f32_e32 v121, v121
	s_nop 0
	s_nop 0
	v_rcp_f32_e32 v120, v120
	s_nop 0
	v_cvt_pk_bf16_f32 v126, v120, v121
	v_mul_f32_e32 v120, 0xbfb8aa3b, v122
	v_mul_f32_e32 v121, 0xbfb8aa3b, v123
	v_exp_f32_e32 v120, v120
	v_exp_f32_e32 v121, v121
	s_nop 0
	v_pk_add_f32 v[120:121], v[120:121], 1.0 op_sel_hi:[1,0]
	s_nop 0
	s_nop 0
	v_rcp_f32_e32 v121, v121
	s_nop 0
	s_mov_b32 s0, 0x8000
	v_rcp_f32_e32 v120, v120
	s_nop 0
	v_cvt_pk_bf16_f32 v127, v120, v121
	v_add_co_u32_e32 v120, vcc, s0, v138
	s_nop 1
	v_addc_co_u32_e32 v121, vcc, 0, v139, vcc
	global_store_dwordx4 v[120:121], v[124:127], off nt
	s_nop 0
	v_rcp_f32_e32 v117, v117
	s_nop 0
	s_nop 0
	v_rcp_f32_e32 v116, v116
	s_nop 0
	v_cvt_pk_bf16_f32 v116, v116, v117
	v_mul_f32_e32 v117, 0xbfb8aa3b, v118
	v_exp_f32_e32 v118, v117
	v_mul_f32_e32 v117, 0xbfb8aa3b, v119
	v_exp_f32_e32 v119, v117
	s_nop 0
	v_pk_add_f32 v[118:119], v[118:119], 1.0 op_sel_hi:[1,0]
	s_nop 0
	s_nop 0
	v_rcp_f32_e32 v117, v119
	s_nop 0
	s_nop 0
	v_rcp_f32_e32 v118, v118
	s_nop 0
	v_cvt_pk_bf16_f32 v117, v118, v117
	s_nop 0
	v_rcp_f32_e32 v113, v113
	s_nop 0
	s_nop 0
	v_rcp_f32_e32 v112, v112
	s_nop 0
	v_cvt_pk_bf16_f32 v118, v112, v113
	v_mul_f32_e32 v112, 0xbfb8aa3b, v114
	v_mul_f32_e32 v113, 0xbfb8aa3b, v115
	v_exp_f32_e32 v112, v112
	v_exp_f32_e32 v113, v113
	s_nop 0
	v_pk_add_f32 v[112:113], v[112:113], 1.0 op_sel_hi:[1,0]
	s_nop 0
	s_nop 0
	v_rcp_f32_e32 v113, v113
	s_nop 0
	s_mov_b32 s0, 0xa000
	v_rcp_f32_e32 v112, v112
	s_nop 0
	v_cvt_pk_bf16_f32 v119, v112, v113
	v_add_co_u32_e32 v112, vcc, s0, v138
	s_nop 1
	v_addc_co_u32_e32 v113, vcc, 0, v139, vcc
	global_store_dwordx4 v[112:113], v[116:119], off nt
	s_nop 0
	v_rcp_f32_e32 v109, v109
	s_nop 0
	s_nop 0
	v_rcp_f32_e32 v108, v108
	s_nop 0
	v_cvt_pk_bf16_f32 v108, v108, v109
	v_mul_f32_e32 v109, 0xbfb8aa3b, v110
	v_exp_f32_e32 v110, v109
	v_mul_f32_e32 v109, 0xbfb8aa3b, v111
	v_exp_f32_e32 v111, v109
	s_nop 0
	v_pk_add_f32 v[110:111], v[110:111], 1.0 op_sel_hi:[1,0]
	s_nop 0
	s_nop 0
	v_rcp_f32_e32 v109, v111
	s_nop 0
	s_nop 0
	v_rcp_f32_e32 v110, v110
	s_nop 0
	v_cvt_pk_bf16_f32 v109, v110, v109
	s_nop 0
	v_rcp_f32_e32 v105, v105
	s_nop 0
	s_nop 0
	v_rcp_f32_e32 v104, v104
; __device__ __forceinline__ float sigmoidf_(float x) { return 1.f / (1.f + __expf(-x)); }
; __device__ void phase1(const Params& p) {
;     ...
;       char* gt = p.GT + ((size_t)((d.pm * 16 + ((d.pn - 64) & 15)) * 2 + ((d.pn - 64) >> 4))) * 131072 + tid * 16;
; #pragma unroll
;       for (int ai = 0; ai < 2; ++ai)
; #pragma unroll
;         for (int bj = 0; bj < 2; ++bj)
; #pragma unroll
;           for (int m = 0; m < 4; ++m) {
;             u32x4 o;
; #pragma unroll
;             for (int n = 0; n < 2; ++n) {
;               o[2 * n] = pack2(sigmoidf_(acc[ai][bj][m][n][0]), sigmoidf_(acc[ai][bj][m][n][1]));
;               o[2 * n + 1] = pack2(sigmoidf_(acc[ai][bj][m][n][2]), sigmoidf_(acc[ai][bj][m][n][3]));
;             }
;             __builtin_nontemporal_store(o, (u32x4*)(gt + ((ai * 2 + bj) * 4 + m) * 8192));
;           }
	s_nop 0
	v_cvt_pk_bf16_f32 v110, v104, v105
	v_mul_f32_e32 v104, 0xbfb8aa3b, v106
	v_mul_f32_e32 v105, 0xbfb8aa3b, v107
	v_exp_f32_e32 v104, v104
	v_exp_f32_e32 v105, v105
	s_nop 0
	v_pk_add_f32 v[104:105], v[104:105], 1.0 op_sel_hi:[1,0]
	s_nop 0
	s_nop 0
	v_rcp_f32_e32 v105, v105
	s_nop 0
	s_mov_b32 s0, 0xc000
	v_rcp_f32_e32 v104, v104
	s_nop 0
	v_cvt_pk_bf16_f32 v111, v104, v105
	v_add_co_u32_e32 v104, vcc, s0, v138
	s_nop 1
	v_addc_co_u32_e32 v105, vcc, 0, v139, vcc
	global_store_dwordx4 v[104:105], v[108:111], off nt
	s_nop 0
	v_rcp_f32_e32 v101, v101
	s_nop 0
	s_nop 0
	v_rcp_f32_e32 v100, v100
	s_nop 0
	v_cvt_pk_bf16_f32 v100, v100, v101
	v_mul_f32_e32 v101, 0xbfb8aa3b, v102
	v_exp_f32_e32 v102, v101
	v_mul_f32_e32 v101, 0xbfb8aa3b, v103
	v_exp_f32_e32 v103, v101
	s_nop 0
	v_pk_add_f32 v[102:103], v[102:103], 1.0 op_sel_hi:[1,0]
	s_nop 0
	s_nop 0
	v_rcp_f32_e32 v101, v103
	s_nop 0
	s_nop 0
	v_rcp_f32_e32 v102, v102
	s_nop 0
	v_cvt_pk_bf16_f32 v101, v102, v101
	s_nop 0
	v_rcp_f32_e32 v97, v97
	s_nop 0
	s_nop 0
	v_rcp_f32_e32 v96, v96
	s_nop 0
	v_cvt_pk_bf16_f32 v102, v96, v97
	v_mul_f32_e32 v96, 0xbfb8aa3b, v98
	v_mul_f32_e32 v97, 0xbfb8aa3b, v99
	v_exp_f32_e32 v96, v96
	v_exp_f32_e32 v97, v97
	s_nop 0
	v_pk_add_f32 v[96:97], v[96:97], 1.0 op_sel_hi:[1,0]
	s_nop 0
	s_nop 0
	v_rcp_f32_e32 v97, v97
	s_nop 0
	s_mov_b32 s0, 0xe000
	v_rcp_f32_e32 v96, v96
	s_nop 0
	v_cvt_pk_bf16_f32 v103, v96, v97
	v_add_co_u32_e32 v96, vcc, s0, v138
	s_nop 1
	v_addc_co_u32_e32 v97, vcc, 0, v139, vcc
	global_store_dwordx4 v[96:97], v[100:103], off nt
	v_mul_f32_e32 v96, 0xbfb8aa3b, v48
	v_mul_f32_e32 v97, 0xbfb8aa3b, v49
	v_exp_f32_e32 v96, v96
	v_exp_f32_e32 v97, v97
	s_nop 0
	v_pk_add_f32 v[96:97], v[96:97], 1.0 op_sel_hi:[1,0]
	s_nop 0
	s_nop 0
	v_rcp_f32_e32 v97, v97
	s_nop 0
	s_nop 0
	v_rcp_f32_e32 v96, v96
	s_nop 0
	v_cvt_pk_bf16_f32 v96, v96, v97
	v_mul_f32_e32 v97, 0xbfb8aa3b, v50
	v_exp_f32_e32 v98, v97
	v_mul_f32_e32 v97, 0xbfb8aa3b, v51
	v_exp_f32_e32 v99, v97
	s_nop 0
	v_pk_add_f32 v[98:99], v[98:99], 1.0 op_sel_hi:[1,0]
	s_nop 0
	s_nop 0
	v_rcp_f32_e32 v97, v99
	s_nop 0
	s_nop 0
	v_rcp_f32_e32 v98, v98
	s_nop 0
	v_cvt_pk_bf16_f32 v97, v98, v97
	v_mul_f32_e32 v98, 0xbfb8aa3b, v56
	v_mul_f32_e32 v99, 0xbfb8aa3b, v57
	v_exp_f32_e32 v98, v98
	v_exp_f32_e32 v99, v99
	s_nop 0
	v_pk_add_f32 v[98:99], v[98:99], 1.0 op_sel_hi:[1,0]
	s_nop 0
	s_nop 0
	v_rcp_f32_e32 v99, v99
	s_nop 0
	s_nop 0
	v_rcp_f32_e32 v98, v98
	s_nop 0
	v_cvt_pk_bf16_f32 v98, v98, v99
	v_mul_f32_e32 v99, 0xbfb8aa3b, v58
	v_exp_f32_e32 v100, v99
	v_mul_f32_e32 v99, 0xbfb8aa3b, v59
	v_exp_f32_e32 v101, v99
	s_nop 0
	v_pk_add_f32 v[100:101], v[100:101], 1.0 op_sel_hi:[1,0]
	s_nop 0
	s_nop 0
	v_rcp_f32_e32 v99, v101
	s_nop 0
	s_nop 0
	v_rcp_f32_e32 v100, v100
	s_nop 0
	v_cvt_pk_bf16_f32 v99, v100, v99
	v_add_co_u32_e32 v100, vcc, s6, v138
	s_nop 1
	v_addc_co_u32_e32 v101, vcc, 0, v139, vcc
	global_store_dwordx4 v[100:101], v[96:99], off nt
	s_nop 1
	v_mul_f32_e32 v96, 0xbfb8aa3b, v52
	v_mul_f32_e32 v97, 0xbfb8aa3b, v53
	v_exp_f32_e32 v96, v96
	v_exp_f32_e32 v97, v97
	s_nop 0
	v_pk_add_f32 v[96:97], v[96:97], 1.0 op_sel_hi:[1,0]
	s_nop 0
	s_nop 0
	v_rcp_f32_e32 v97, v97
	s_nop 0
	s_nop 0
	v_rcp_f32_e32 v96, v96
	s_nop 0
	v_cvt_pk_bf16_f32 v96, v96, v97
	v_mul_f32_e32 v97, 0xbfb8aa3b, v54
	v_exp_f32_e32 v98, v97
	v_mul_f32_e32 v97, 0xbfb8aa3b, v55
	v_exp_f32_e32 v99, v97
	s_nop 0
	v_pk_add_f32 v[98:99], v[98:99], 1.0 op_sel_hi:[1,0]
	s_nop 0
	s_nop 0
	v_rcp_f32_e32 v97, v99
	s_nop 0
	s_nop 0
	v_rcp_f32_e32 v98, v98
	s_nop 0
	v_cvt_pk_bf16_f32 v97, v98, v97
	v_mul_f32_e32 v98, 0xbfb8aa3b, v60
	v_mul_f32_e32 v99, 0xbfb8aa3b, v61
	v_exp_f32_e32 v98, v98
	v_exp_f32_e32 v99, v99
	s_nop 0
	v_pk_add_f32 v[98:99], v[98:99], 1.0 op_sel_hi:[1,0]
	s_nop 0
	s_nop 0
	v_rcp_f32_e32 v99, v99
	s_nop 0
	s_nop 0
	v_rcp_f32_e32 v98, v98
	s_nop 0
	v_cvt_pk_bf16_f32 v98, v98, v99
	v_mul_f32_e32 v99, 0xbfb8aa3b, v62
	v_exp_f32_e32 v100, v99
	v_mul_f32_e32 v99, 0xbfb8aa3b, v63
	v_exp_f32_e32 v101, v99
	s_nop 0
	v_pk_add_f32 v[100:101], v[100:101], 1.0 op_sel_hi:[1,0]
	s_nop 0
	s_nop 0
	v_rcp_f32_e32 v99, v101
	s_nop 0
	s_mov_b32 s0, 0x12000
	v_rcp_f32_e32 v100, v100
	s_nop 0
	v_cvt_pk_bf16_f32 v99, v100, v99
	v_add_co_u32_e32 v100, vcc, s0, v138
	s_nop 1
	v_addc_co_u32_e32 v101, vcc, 0, v139, vcc
	global_store_dwordx4 v[100:101], v[96:99], off nt
	s_nop 1
	v_mul_f32_e32 v96, 0xbfb8aa3b, v32
	v_mul_f32_e32 v97, 0xbfb8aa3b, v33
	v_exp_f32_e32 v96, v96
	v_exp_f32_e32 v97, v97
	s_nop 0
	v_pk_add_f32 v[96:97], v[96:97], 1.0 op_sel_hi:[1,0]
	s_nop 0
	s_nop 0
	v_rcp_f32_e32 v97, v97
	s_nop 0
	s_nop 0
	v_rcp_f32_e32 v96, v96
	s_nop 0
	v_cvt_pk_bf16_f32 v96, v96, v97
	v_mul_f32_e32 v97, 0xbfb8aa3b, v34
	v_exp_f32_e32 v98, v97
	v_mul_f32_e32 v97, 0xbfb8aa3b, v35
	v_exp_f32_e32 v99, v97
	s_nop 0
	v_pk_add_f32 v[98:99], v[98:99], 1.0 op_sel_hi:[1,0]
	s_nop 0
	s_nop 0
	v_rcp_f32_e32 v97, v99
	s_nop 0
	s_nop 0
	v_rcp_f32_e32 v98, v98
	s_nop 0
	v_cvt_pk_bf16_f32 v97, v98, v97
	v_mul_f32_e32 v98, 0xbfb8aa3b, v40
	v_mul_f32_e32 v99, 0xbfb8aa3b, v41
	v_exp_f32_e32 v98, v98
	v_exp_f32_e32 v99, v99
	s_nop 0
	v_pk_add_f32 v[98:99], v[98:99], 1.0 op_sel_hi:[1,0]
	s_nop 0
	s_nop 0
	v_rcp_f32_e32 v99, v99
	s_nop 0
	s_nop 0
	v_rcp_f32_e32 v98, v98
	s_nop 0
	v_cvt_pk_bf16_f32 v98, v98, v99
	v_mul_f32_e32 v99, 0xbfb8aa3b, v42
	v_exp_f32_e32 v100, v99
	v_mul_f32_e32 v99, 0xbfb8aa3b, v43
	v_exp_f32_e32 v101, v99
	s_nop 0
	v_pk_add_f32 v[100:101], v[100:101], 1.0 op_sel_hi:[1,0]
	s_nop 0
	s_nop 0
	v_rcp_f32_e32 v99, v101
	s_nop 0
	s_nop 0
	v_rcp_f32_e32 v100, v100
	s_nop 0
; __device__ __forceinline__ float sigmoidf_(float x) { return 1.f / (1.f + __expf(-x)); }
; __device__ void phase1(const Params& p) {
;     ...
;       char* gt = p.GT + ((size_t)((d.pm * 16 + ((d.pn - 64) & 15)) * 2 + ((d.pn - 64) >> 4))) * 131072 + tid * 16;
; #pragma unroll
;       for (int ai = 0; ai < 2; ++ai)
; #pragma unroll
;         for (int bj = 0; bj < 2; ++bj)
; #pragma unroll
;           for (int m = 0; m < 4; ++m) {
;             u32x4 o;
; #pragma unroll
;             for (int n = 0; n < 2; ++n) {
;               o[2 * n] = pack2(sigmoidf_(acc[ai][bj][m][n][0]), sigmoidf_(acc[ai][bj][m][n][1]));
;               o[2 * n + 1] = pack2(sigmoidf_(acc[ai][bj][m][n][2]), sigmoidf_(acc[ai][bj][m][n][3]));
;             }
;             __builtin_nontemporal_store(o, (u32x4*)(gt + ((ai * 2 + bj) * 4 + m) * 8192));
;           }
	v_cvt_pk_bf16_f32 v99, v100, v99
	v_add_co_u32_e32 v100, vcc, s7, v138
	s_nop 1
	v_addc_co_u32_e32 v101, vcc, 0, v139, vcc
	global_store_dwordx4 v[100:101], v[96:99], off nt
	s_nop 1
	v_mul_f32_e32 v96, 0xbfb8aa3b, v36
	v_mul_f32_e32 v97, 0xbfb8aa3b, v37
	v_exp_f32_e32 v96, v96
	v_exp_f32_e32 v97, v97
	s_nop 0
	v_pk_add_f32 v[96:97], v[96:97], 1.0 op_sel_hi:[1,0]
	s_nop 0
	s_nop 0
	v_rcp_f32_e32 v97, v97
	s_nop 0
	s_nop 0
	v_rcp_f32_e32 v96, v96
	s_nop 0
	v_cvt_pk_bf16_f32 v96, v96, v97
	v_mul_f32_e32 v97, 0xbfb8aa3b, v38
	v_exp_f32_e32 v98, v97
	v_mul_f32_e32 v97, 0xbfb8aa3b, v39
	v_exp_f32_e32 v99, v97
	s_nop 0
	v_pk_add_f32 v[98:99], v[98:99], 1.0 op_sel_hi:[1,0]
	s_nop 0
	s_nop 0
	v_rcp_f32_e32 v97, v99
	s_nop 0
	s_nop 0
	v_rcp_f32_e32 v98, v98
	s_nop 0
	v_cvt_pk_bf16_f32 v97, v98, v97
	v_mul_f32_e32 v98, 0xbfb8aa3b, v44
	v_mul_f32_e32 v99, 0xbfb8aa3b, v45
	v_exp_f32_e32 v98, v98
	v_exp_f32_e32 v99, v99
	s_nop 0
	v_pk_add_f32 v[98:99], v[98:99], 1.0 op_sel_hi:[1,0]
	s_nop 0
	s_nop 0
	v_rcp_f32_e32 v99, v99
	s_nop 0
	s_nop 0
	v_rcp_f32_e32 v98, v98
	s_nop 0
	v_cvt_pk_bf16_f32 v98, v98, v99
	v_mul_f32_e32 v99, 0xbfb8aa3b, v46
	v_exp_f32_e32 v100, v99
	v_mul_f32_e32 v99, 0xbfb8aa3b, v47
	v_exp_f32_e32 v101, v99
	s_nop 0
	v_pk_add_f32 v[100:101], v[100:101], 1.0 op_sel_hi:[1,0]
	s_nop 0
	s_nop 0
	v_rcp_f32_e32 v99, v101
	s_nop 0
	s_mov_b32 s0, 0x16000
	v_rcp_f32_e32 v100, v100
	s_nop 0
	v_cvt_pk_bf16_f32 v99, v100, v99
	v_add_co_u32_e32 v100, vcc, s0, v138
	s_nop 1
	v_addc_co_u32_e32 v101, vcc, 0, v139, vcc
	global_store_dwordx4 v[100:101], v[96:99], off nt
	s_nop 1
	s_nop 0
	v_rcp_f32_e32 v93, v93
	s_nop 0
	s_nop 0
	v_rcp_f32_e32 v92, v92
	s_nop 0
	v_cvt_pk_bf16_f32 v92, v92, v93
	v_mul_f32_e32 v93, 0xbfb8aa3b, v94
	v_exp_f32_e32 v94, v93
	v_mul_f32_e32 v93, 0xbfb8aa3b, v95
	v_exp_f32_e32 v95, v93
	s_nop 0
	v_pk_add_f32 v[94:95], v[94:95], 1.0 op_sel_hi:[1,0]
	s_nop 0
	s_nop 0
	v_rcp_f32_e32 v93, v95
	s_nop 0
	s_nop 0
	v_rcp_f32_e32 v94, v94
	s_nop 0
	v_cvt_pk_bf16_f32 v93, v94, v93
	s_nop 0
	v_rcp_f32_e32 v89, v89
	s_nop 0
	s_nop 0
	v_rcp_f32_e32 v88, v88
	s_nop 0
	v_cvt_pk_bf16_f32 v94, v88, v89
	v_mul_f32_e32 v88, 0xbfb8aa3b, v90
	v_mul_f32_e32 v89, 0xbfb8aa3b, v91
	v_exp_f32_e32 v88, v88
	v_exp_f32_e32 v89, v89
	s_nop 0
	v_pk_add_f32 v[88:89], v[88:89], 1.0 op_sel_hi:[1,0]
	s_nop 0
	s_nop 0
	v_rcp_f32_e32 v89, v89
	s_nop 0
	s_mov_b32 s0, 0x18000
	v_rcp_f32_e32 v88, v88
	s_nop 0
	v_cvt_pk_bf16_f32 v95, v88, v89
	v_add_co_u32_e32 v88, vcc, s0, v138
	s_nop 1
	v_addc_co_u32_e32 v89, vcc, 0, v139, vcc
	global_store_dwordx4 v[88:89], v[92:95], off nt
	s_nop 0
	v_rcp_f32_e32 v85, v85
	s_nop 0
	s_nop 0
	v_rcp_f32_e32 v84, v84
	s_nop 0
	v_cvt_pk_bf16_f32 v84, v84, v85
	v_mul_f32_e32 v85, 0xbfb8aa3b, v86
	v_exp_f32_e32 v86, v85
	v_mul_f32_e32 v85, 0xbfb8aa3b, v87
	v_exp_f32_e32 v87, v85
	s_nop 0
	v_pk_add_f32 v[86:87], v[86:87], 1.0 op_sel_hi:[1,0]
	s_nop 0
	s_nop 0
	v_rcp_f32_e32 v85, v87
	s_nop 0
	s_nop 0
	v_rcp_f32_e32 v86, v86
	s_nop 0
	v_cvt_pk_bf16_f32 v85, v86, v85
	s_nop 0
	v_rcp_f32_e32 v81, v81
	s_nop 0
	s_nop 0
	v_rcp_f32_e32 v80, v80
	s_nop 0
	v_cvt_pk_bf16_f32 v86, v80, v81
	v_mul_f32_e32 v80, 0xbfb8aa3b, v82
	v_mul_f32_e32 v81, 0xbfb8aa3b, v83
	v_exp_f32_e32 v80, v80
	v_exp_f32_e32 v81, v81
	s_nop 0
	v_pk_add_f32 v[80:81], v[80:81], 1.0 op_sel_hi:[1,0]
	s_nop 0
	s_nop 0
	v_rcp_f32_e32 v81, v81
	s_nop 0
	s_mov_b32 s0, 0x1a000
	v_rcp_f32_e32 v80, v80
	s_nop 0
	v_cvt_pk_bf16_f32 v87, v80, v81
	v_add_co_u32_e32 v80, vcc, s0, v138
	s_nop 1
	v_addc_co_u32_e32 v81, vcc, 0, v139, vcc
	global_store_dwordx4 v[80:81], v[84:87], off nt
	s_nop 0
	v_rcp_f32_e32 v77, v77
	s_nop 0
	s_nop 0
	v_rcp_f32_e32 v76, v76
	s_nop 0
	v_cvt_pk_bf16_f32 v76, v76, v77
	v_mul_f32_e32 v77, 0xbfb8aa3b, v78
	v_exp_f32_e32 v78, v77
	v_mul_f32_e32 v77, 0xbfb8aa3b, v79
	v_exp_f32_e32 v79, v77
	s_nop 0
	v_pk_add_f32 v[78:79], v[78:79], 1.0 op_sel_hi:[1,0]
	s_nop 0
	s_nop 0
	v_rcp_f32_e32 v77, v79
	s_nop 0
	s_nop 0
	v_rcp_f32_e32 v78, v78
	s_nop 0
	v_cvt_pk_bf16_f32 v77, v78, v77
	s_nop 0
	v_rcp_f32_e32 v73, v73
	s_nop 0
	s_nop 0
	v_rcp_f32_e32 v72, v72
	s_nop 0
	v_cvt_pk_bf16_f32 v78, v72, v73
	v_mul_f32_e32 v72, 0xbfb8aa3b, v74
	v_mul_f32_e32 v73, 0xbfb8aa3b, v75
	v_exp_f32_e32 v72, v72
	v_exp_f32_e32 v73, v73
	s_nop 0
	v_pk_add_f32 v[72:73], v[72:73], 1.0 op_sel_hi:[1,0]
	s_nop 0
	s_nop 0
	v_rcp_f32_e32 v73, v73
	s_nop 0
	s_nop 0
	v_rcp_f32_e32 v72, v72
	s_nop 0
	v_cvt_pk_bf16_f32 v79, v72, v73
	v_add_co_u32_e32 v72, vcc, s3, v138
	s_nop 1
	v_addc_co_u32_e32 v73, vcc, 0, v139, vcc
	global_store_dwordx4 v[72:73], v[76:79], off nt
	s_nop 0
	v_rcp_f32_e32 v69, v69
	s_nop 0
	s_nop 0
	v_rcp_f32_e32 v68, v68
	s_nop 0
	v_cvt_pk_bf16_f32 v68, v68, v69
	v_mul_f32_e32 v69, 0xbfb8aa3b, v70
	v_exp_f32_e32 v70, v69
	v_mul_f32_e32 v69, 0xbfb8aa3b, v71
	v_exp_f32_e32 v71, v69
	s_nop 0
	v_pk_add_f32 v[70:71], v[70:71], 1.0 op_sel_hi:[1,0]
	s_nop 0
	s_nop 0
	v_rcp_f32_e32 v69, v71
	s_nop 0
	s_nop 0
	v_rcp_f32_e32 v70, v70
	s_nop 0
	v_cvt_pk_bf16_f32 v69, v70, v69
	s_nop 0
	v_rcp_f32_e32 v65, v65
	s_nop 0
	s_nop 0
	v_rcp_f32_e32 v64, v64
	s_nop 0
	v_cvt_pk_bf16_f32 v70, v64, v65
	v_mul_f32_e32 v64, 0xbfb8aa3b, v66
	v_mul_f32_e32 v65, 0xbfb8aa3b, v67
	v_exp_f32_e32 v64, v64
	v_exp_f32_e32 v65, v65
	s_nop 0
	v_pk_add_f32 v[64:65], v[64:65], 1.0 op_sel_hi:[1,0]
	s_nop 0
	s_nop 0
	v_rcp_f32_e32 v65, v65
	s_nop 0
	s_nop 0
	v_rcp_f32_e32 v64, v64
	s_nop 0
	v_cvt_pk_bf16_f32 v71, v64, v65
	v_add_co_u32_e32 v64, vcc, 0x1e000, v138
	s_nop 1
	v_addc_co_u32_e32 v65, vcc, 0, v139, vcc
	global_store_dwordx4 v[64:65], v[68:71], off nt

; __device__ __forceinline__ int opaque_tid() { int t = threadIdx.x; asm volatile("" : "+v"(t)); return t; }
; __device__ void gla_scan_item(const Params& p, int id) {
;   const int tid = opaque_tid(), lane = tid & 63, w = tid >> 6, fr = lane & 15, fq = lane >> 4;
;   const int ws = __builtin_amdgcn_readfirstlane(w) & 7;
;   int seq, j;
;   if (id < 32) { seq = 4; j = id; } else { seq = (id - 32) >> 5; j = (id - 32) & 31; }
;   const int h = (j & 7) >> 1, dir = j & 1, vs = (j >> 3) & 3;
;   const int start = seq_start(seq), len = seq_len(seq), nch = len >> 6, chunk0 = start >> 6;
;   const int cfirst = dir ? chunk0 + nch - 1 : chunk0, cstep = dir ? -1 : 1;
;   u16* O = (dir ? p.OB : p.OF) + h * 512 + vs * 128 + 16 * w + 4 * fq;
;   const u16* vt_base = p.VTG + ((size_t)h * 512 + vs * 128 + 16 * w + fr) * 64 + 8 * fq;
;   const char* blob_base = p.BLOBR + (size_t)(h * 2 + dir) * BLOB_BYTES + lane * 16;
;   char* lds_lane = smem + lane * 16;
;     ...
;   f32x4 st[16];
; #pragma unroll
;   for (int T = 0; T < 16; ++T) st[T] = f32x4{0.f, 0.f, 0.f, 0.f};
;   bf16x8 vfA[2], vfB[2];
;   BLOB_DMA(cfirst, 0);
;   VT_LOAD(vfA, cfirst);
;   asm volatile("s_waitcnt vmcnt(0)" ::: "memory");
;   __syncthreads();
.LBB0_423:
	s_waitcnt vmcnt(0)
	s_addk_i32 s89, 0xc0
	s_cmpk_lt_i32 s89, 0x100
	s_cbranch_scc1 .LBB0_432
	s_cmpk_gt_i32 s89, 0x13f
	s_cbranch_scc1 .LBB0_432
.LBB0_424:
	s_sub_i32 s0, s89, 64
	s_lshr_b32 s0, s0, 6
	s_cmp_gt_i32 s89, 63
	s_cselect_b32 s0, s0, 4
	s_and_b32 s8, s89, 1
	s_lshl_b32 s9, s0, 5
	s_cmp_lt_u32 s0, 4
	v_readlane_b32 s56, v255, 0
	v_mov_b32_e32 v8, v248
	s_cselect_b32 s90, 32, 0x80
	s_and_b32 s0, s89, 7
	v_readlane_b32 s57, v255, 1
	s_add_i32 s28, s9, s90
	v_ashrrev_i32_e32 v3, 6, v8
	s_mul_i32 s0, s0, 0x14000
	s_mov_b64 s[4:5], s[56:57]
	v_readfirstlane_b32 s6, v3
	s_add_u32 s0, s4, s0
	s_addc_u32 s1, s5, 0
	s_and_b32 s66, s6, 7
	s_lshr_b32 s99, s6, 2
	s_and_b32 s100, s6, 3
	s_mulk_i32 s100, 0x4c00
	s_mov_b32 s101, 0
	s_add_i32 s28, s28, -1
	v_and_b32_e32 v2, 63, v8
	s_cmp_eq_u32 s8, 0
	s_cselect_b64 s[72:73], -1, 0
	v_lshlrev_b32_e32 v152, 4, v2
	v_lshl_add_u64 v[154:155], s[0:1], 0, v[152:153]
	s_and_b64 s[0:1], s[72:73], exec
	s_cselect_b32 s6, s9, s28
	s_lshl_b32 s28, s66, 10
	v_mad_u64_u32 v[0:1], s[0:1], s6, v161, v[154:155]
	v_or_b32_e32 v6, s28, v152
	s_mov_b32 s29, s7
	v_readfirstlane_b32 s0, v6
	v_or_b32_e32 v7, 0x2000, v6
	v_lshl_add_u64 v[4:5], v[0:1], 0, s[28:29]
	s_mov_b32 m0, s0
	s_or_b32 s30, s28, 0x2000
	s_mov_b32 s31, s7
	v_readfirstlane_b32 s0, v7
	v_or_b32_e32 v7, 0x4000, v6
	global_load_lds_dwordx4 v[4:5], off
	v_lshl_add_u64 v[4:5], v[0:1], 0, s[30:31]
	s_mov_b32 m0, s0
	s_or_b32 s34, s28, 0x4000
	s_mov_b32 s35, s7
	v_readfirstlane_b32 s0, v7
	v_or_b32_e32 v7, 0x6000, v6
	global_load_lds_dwordx4 v[4:5], off
	v_lshl_add_u64 v[4:5], v[0:1], 0, s[34:35]
	s_mov_b32 m0, s0
	s_or_b32 s46, s28, 0x6000
	s_mov_b32 s47, s7
	v_readfirstlane_b32 s0, v7
	v_or_b32_e32 v7, 0x8000, v6
	v_readlane_b32 s58, v255, 2
	v_readlane_b32 s59, v255, 3
	global_load_lds_dwordx4 v[4:5], off
	v_lshl_add_u64 v[4:5], v[0:1], 0, s[46:47]
	s_mov_b32 m0, s0
	s_or_b32 s56, s28, 0x8000
	s_mov_b32 s57, s7
	v_readfirstlane_b32 s0, v7
	v_or_b32_e32 v7, 0xa000, v6
	global_load_lds_dwordx4 v[4:5], off
	v_lshl_add_u64 v[4:5], v[0:1], 0, s[56:57]
	s_mov_b32 m0, s0
	s_or_b32 s58, s28, 0xa000
	s_mov_b32 s59, s7
	v_readfirstlane_b32 s0, v7
	v_or_b32_e32 v7, 0xc000, v6
	global_load_lds_dwordx4 v[4:5], off
	v_lshl_add_u64 v[4:5], v[0:1], 0, s[58:59]
	s_mov_b32 m0, s0
	s_or_b32 s60, s28, 0xc000
	s_mov_b32 s61, s7
	v_readfirstlane_b32 s0, v7
	v_or_b32_e32 v6, 0xe000, v6
	s_or_b32 s64, s28, 0x10000
	global_load_lds_dwordx4 v[4:5], off
	v_lshl_add_u64 v[4:5], v[0:1], 0, s[60:61]
	s_mov_b32 m0, s0
	s_or_b32 s62, s28, 0xe000
	s_mov_b32 s63, s7
	v_readfirstlane_b32 s0, v6
	v_or_b32_e32 v6, s64, v152
	global_load_lds_dwordx4 v[4:5], off
	v_lshl_add_u64 v[4:5], v[0:1], 0, s[62:63]
	s_mov_b32 m0, s0
	s_mov_b32 s65, s7
	v_readfirstlane_b32 s0, v6
	global_load_lds_dwordx4 v[4:5], off
	v_lshl_add_u64 v[4:5], v[0:1], 0, s[64:65]
	s_mov_b32 m0, s0
	s_or_b32 s8, s66, 0x48
	global_load_lds_dwordx4 v[4:5], off
	s_cmpk_lt_u32 s8, 0x4a
	s_cselect_b64 s[0:1], -1, 0
	s_lshl_b32 s66, s8, 10
	s_cmpk_gt_u32 s8, 0x49
	s_mov_b32 s67, s7
	v_add_u32_e32 v162, s66, v152
	s_cbranch_scc1 .LBB0_426
	v_readfirstlane_b32 s8, v162
	v_lshl_add_u64 v[0:1], v[0:1], 0, s[66:67]
	s_mov_b32 m0, s8
	s_nop 0
	global_load_lds_dwordx4 v[0:1], off
.LBB0_426:
	s_and_b64 s[8:9], s[72:73], exec
	s_cselect_b32 s91, 1, -1
	s_cselect_b32 s72, s39, s41
	s_cselect_b32 s73, s38, s40
	s_lshl_b32 s8, s89, 8
	s_and_b32 s84, s8, 0x600
	s_lshl_b32 s8, s89, 3
	s_and_b32 s85, s8, 0x1c0
	v_and_b32_e32 v3, 3, v3
	v_lshlrev_b32_e32 v0, 4, v3
	v_ashrrev_i32_e32 v1, 31, v0
	s_or_b32 s8, s84, s85
	s_mov_b32 s9, s7
	v_lshl_add_u64 v[4:5], v[0:1], 0, s[8:9]
	s_lshl_b32 s8, s84, 1
	v_and_b32_e32 v163, 15, v8
	s_add_u32 s8, s73, s8
	v_or_b32_e32 v4, v4, v163
	s_addc_u32 s9, s72, 0
	s_lshl_b32 s72, s85, 1
	v_lshlrev_b64 v[4:5], 7, v[4:5]
	s_add_u32 s8, s8, s72
	v_lshrrev_b32_e32 v9, 4, v2
	s_addc_u32 s9, s9, 0
	v_lshl_add_u64 v[4:5], s[96:97], 0, v[4:5]
	v_and_b32_e32 v10, 48, v2
	v_mov_b32_e32 v11, v153
	v_lshl_add_u64 v[0:1], v[0:1], 1, s[8:9]
	v_lshlrev_b32_e32 v6, 3, v9
	v_mov_b32_e32 v7, v153
	v_lshl_add_u64 v[158:159], v[4:5], 0, v[10:11]
	s_lshl_b64 s[8:9], s[6:7], 18
	v_lshl_add_u64 v[156:157], v[0:1], 0, v[6:7]
	v_lshl_add_u64 v[0:1], v[158:159], 0, s[8:9]
	global_load_dwordx4 v[4:7], v[0:1], off
	s_nop 0
	global_load_dwordx4 v[0:3], v[0:1], off offset:64
	v_mul_u32_u24_e32 v12, 0x108, v163
	v_and_b32_e32 v13, 7, v8
	v_lshlrev_b32_e32 v12, 1, v12
	v_bitop3_b32 v8, v9, v8, 7 bitop3:0x78
	v_bitop3_b32 v9, v9, v13, 4 bitop3:0x36
	v_add_u32_e32 v164, v12, v10
	v_lshlrev_b32_e32 v13, 7, v163
	v_lshlrev_b32_e32 v9, 4, v9
	v_mad_i32_i24 v12, v163, s3, v12
	v_lshlrev_b32_e32 v8, 4, v8
	s_waitcnt vmcnt(0)
; __device__ void gla_scan_item(const Params& p, int id) {
;     ...
;   f32x4 st[16];
; #pragma unroll
;   for (int T = 0; T < 16; ++T) st[T] = f32x4{0.f, 0.f, 0.f, 0.f};
;   bf16x8 vfA[2], vfB[2];
;   BLOB_DMA(cfirst, 0);
;   VT_LOAD(vfA, cfirst);
;   asm volatile("s_waitcnt vmcnt(0)" ::: "memory");
;   __syncthreads();
	v_add_u32_e32 v14, 0x10400, v13
	v_add_u32_e32 v166, v12, v9
	v_add_u32_e32 v168, v12, v8
	v_add_u32_e32 v12, 0x24400, v13
	v_add_u32_e32 v13, 0x1c400, v13
	v_or_b32_e32 v11, 0x14000, v152
	v_or_b32_e32 v167, v14, v8
	v_or_b32_e32 v173, v12, v8
	v_or_b32_e32 v174, v13, v8
	v_mov_b32_e32 v16, 0
	v_cndmask_b32_e64 v8, 0, 1, s[0:1]
	v_add_u32_e32 v186, s28, v152
	v_or_b32_e32 v165, v14, v9
	v_or_b32_e32 v169, 0x12400, v10
	v_add_u32_e32 v170, 0x14000, v164
	v_or_b32_e32 v171, v12, v9
	v_or_b32_e32 v172, v13, v9
	v_or_b32_e32 v175, 0x26400, v10
	s_lshl_b32 s92, s6, 6
	s_lshl_b32 s93, s91, 7
	v_lshl_or_b32 v176, s91, 6, v163
	s_add_i32 s72, s6, s91
	s_lshl_b32 s6, s91, 1
	s_mov_b32 s94, 2
	v_add_u32_e32 v177, s28, v11
	v_add_u32_e32 v178, s30, v11
	v_add_u32_e32 v179, s34, v11
	v_add_u32_e32 v180, s46, v11
	v_add_u32_e32 v181, s56, v11
	v_add_u32_e32 v182, s58, v11
	v_add_u32_e32 v183, s60, v11
	v_add_u32_e32 v184, s62, v11
	v_add_u32_e32 v185, s64, v11
	v_add_u32_e32 v187, 0x2000, v186
	v_or_b32_e32 v188, 0x4000, v186
	v_add_u32_e32 v189, 0x6000, v186
	v_or_b32_e32 v190, 0x8000, v186
	v_add_u32_e32 v191, 0xa000, v186
	v_or_b32_e32 v192, 0xc000, v186
	v_add_u32_e32 v193, 0xe000, v186
	v_add_u32_e32 v152, s64, v152
	v_cmp_ne_u32_e64 s[0:1], 1, v8
	v_add_u32_e32 v194, s66, v11
	v_mov_b32_e32 v17, v16
	v_mov_b32_e32 v18, v16
	v_mov_b32_e32 v19, v16
	v_mov_b32_e32 v68, v16
	v_mov_b32_e32 v69, v16
	v_mov_b32_e32 v70, v16
	v_mov_b32_e32 v71, v16
	v_mov_b32_e32 v76, v16
	v_mov_b32_e32 v77, v16
	v_mov_b32_e32 v78, v16
	v_mov_b32_e32 v79, v16
	v_mov_b32_e32 v72, v16
	v_mov_b32_e32 v73, v16
	v_mov_b32_e32 v74, v16
	v_mov_b32_e32 v75, v16
	v_mov_b32_e32 v56, v16
	v_mov_b32_e32 v57, v16
	v_mov_b32_e32 v58, v16
	v_mov_b32_e32 v59, v16
	v_mov_b32_e32 v52, v16
	v_mov_b32_e32 v53, v16
	v_mov_b32_e32 v54, v16
	v_mov_b32_e32 v55, v16
	v_mov_b32_e32 v64, v16
	v_mov_b32_e32 v65, v16
	v_mov_b32_e32 v66, v16
	v_mov_b32_e32 v67, v16
	v_mov_b32_e32 v60, v16
	v_mov_b32_e32 v61, v16
	v_mov_b32_e32 v62, v16
	v_mov_b32_e32 v63, v16
	v_mov_b32_e32 v48, v16
	v_mov_b32_e32 v49, v16
	v_mov_b32_e32 v50, v16
	v_mov_b32_e32 v51, v16
	v_mov_b32_e32 v44, v16
	v_mov_b32_e32 v45, v16
	v_mov_b32_e32 v46, v16
	v_mov_b32_e32 v47, v16
	v_mov_b32_e32 v40, v16
	v_mov_b32_e32 v41, v16
	v_mov_b32_e32 v42, v16
	v_mov_b32_e32 v43, v16
	v_mov_b32_e32 v36, v16
	v_mov_b32_e32 v37, v16
	v_mov_b32_e32 v38, v16
	v_mov_b32_e32 v39, v16
	v_mov_b32_e32 v32, v16
	v_mov_b32_e32 v33, v16
	v_mov_b32_e32 v34, v16
	v_mov_b32_e32 v35, v16
	v_mov_b32_e32 v28, v16
	v_mov_b32_e32 v29, v16
	v_mov_b32_e32 v30, v16
	v_mov_b32_e32 v31, v16
	v_mov_b32_e32 v24, v16
	v_mov_b32_e32 v25, v16
	v_mov_b32_e32 v26, v16
	v_mov_b32_e32 v27, v16
	v_mov_b32_e32 v20, v16
	v_mov_b32_e32 v21, v16
	v_mov_b32_e32 v22, v16
	v_mov_b32_e32 v23, v16
	s_cmp_eq_u32 s99, 0
	s_cbranch_scc1 .Lld_pro_done
	v_lshl_add_u64 v[196:197], v[154:155], 0, s[100:101]
	v_and_b32_e32 v216, 63, v248
	v_add_co_u32_e32 v198, vcc, 0x1000, v196
	v_lshlrev_b32_e32 v216, 4, v216
	v_addc_co_u32_e32 v199, vcc, 0, v197, vcc
	v_add_co_u32_e32 v200, vcc, 0x2000, v196
	v_add_u32_e32 v216, s100, v216
	v_addc_co_u32_e32 v201, vcc, 0, v197, vcc
	v_add_co_u32_e32 v202, vcc, 0x3000, v196
	v_add_u32_e32 v217, 0x14000, v216
	v_addc_co_u32_e32 v203, vcc, 0, v197, vcc
	v_add_co_u32_e32 v204, vcc, 0x4000, v196
	s_nop 1
	v_addc_co_u32_e32 v205, vcc, 0, v197, vcc
	v_mad_i64_i32 v[206:207], s[8:9], s72, v161, v[196:197]
	v_mad_i64_i32 v[208:209], s[8:9], s72, v161, v[198:199]
	v_mad_i64_i32 v[210:211], s[8:9], s72, v161, v[200:201]
	v_mad_i64_i32 v[212:213], s[8:9], s72, v161, v[202:203]
	v_mad_i64_i32 v[214:215], s[8:9], s72, v161, v[204:205]
	global_load_dwordx4 v[76:79], v[206:207], off
	global_load_dwordx4 v[80:83], v[206:207], off offset:1024
	global_load_dwordx4 v[84:87], v[206:207], off offset:2048
	global_load_dwordx4 v[88:91], v[206:207], off offset:3072
	global_load_dwordx4 v[92:95], v[208:209], off
	global_load_dwordx4 v[96:99], v[208:209], off offset:1024
	global_load_dwordx4 v[100:103], v[208:209], off offset:2048
	global_load_dwordx4 v[104:107], v[208:209], off offset:3072
	global_load_dwordx4 v[108:111], v[210:211], off
	global_load_dwordx4 v[112:115], v[210:211], off offset:1024
	global_load_dwordx4 v[116:119], v[210:211], off offset:2048
	global_load_dwordx4 v[120:123], v[210:211], off offset:3072
	global_load_dwordx4 v[124:127], v[212:213], off
	global_load_dwordx4 v[128:131], v[212:213], off offset:1024
	global_load_dwordx4 v[132:135], v[212:213], off offset:2048
	global_load_dwordx4 v[136:139], v[212:213], off offset:3072
	global_load_dwordx4 v[140:143], v[214:215], off
	global_load_dwordx4 v[144:147], v[214:215], off offset:1024
	global_load_dwordx4 v[148:151], v[214:215], off offset:2048
.Lld_pro_done:
	s_waitcnt vmcnt(0) lgkmcnt(0)
	s_barrier
	s_branch .LBB0_428
; __device__ __forceinline__ void scan_compute(const char* cur, const bf16x8 (&vf)[2], f32x4 (&st)[16],
;                                              u16* O, const int fr, const int fq) {
;     ...
;   {
;     f32x4 oacc[4];
;     u32x4 qf[3][4];
;     bf16x8 af[2][4];
; #pragma unroll
;     for (int qt = 0; qt < 4; ++qt) oacc[qt] = f32x4{0.f, 0.f, 0.f, 0.f};
;     LOADQ(0, 0);
;     LOADQ(1, 1);
; #pragma unroll
;     for (int s = 0; s < 8; ++s) {
;       if (s < 6) { LOADQ((s + 2) % 3, s + 2); }
;       else if (s == 6) {
; #pragma unroll
;         for (int qt = 0; qt < 4; ++qt) af[0][qt] = *(const bf16x8*)(AMl0 + (16 * qt) * 64);
;       } else {
; #pragma unroll
;         for (int qt = 0; qt < 4; ++qt) af[1][qt] = *(const bf16x8*)(AMl1 + (16 * qt) * 64);
;       }
;       u32x4 sw;
;       sw[0] = pack2(st[2 * s][0], st[2 * s][1]);
;       sw[1] = pack2(st[2 * s][2], st[2 * s][3]);
;       sw[2] = pack2(st[2 * s + 1][0], st[2 * s + 1][1]);
;       sw[3] = pack2(st[2 * s + 1][2], st[2 * s + 1][3]);
;       bf16x8 sf = __builtin_bit_cast(bf16x8, sw);
;       __builtin_amdgcn_sched_barrier(0);
; #pragma unroll
;       for (int qt = 0; qt < 4; ++qt)
;         oacc[qt] = __builtin_amdgcn_mfma_f32_16x16x32_bf16(sf, __builtin_bit_cast(bf16x8, qf[s % 3][qt]), oacc[qt], 0, 0, 0);
;       __builtin_amdgcn_sched_barrier(0);
;     }
; #pragma unroll
;     for (int qt = 0; qt < 4; ++qt)
;       oacc[qt] = __builtin_amdgcn_mfma_f32_16x16x32_bf16(vf[0], af[0][qt], oacc[qt], 0, 0, 0);
;     __builtin_amdgcn_sched_barrier(0);
; #pragma unroll
;     for (int qt = 0; qt < 4; ++qt)
;       oacc[qt] = __builtin_amdgcn_mfma_f32_16x16x32_bf16(vf[1], af[1][qt], oacc[qt], 0, 0, 0);
;     __builtin_amdgcn_sched_barrier(0);
; #pragma unroll
;     for (int qt = 0; qt < 4; ++qt) {
;       u32x2 ov;
;       ov[0] = pack2(oacc[qt][0], oacc[qt][1]);
;       ov[1] = pack2(oacc[qt][2], oacc[qt][3]);
;       *(u32x2*)(O + (size_t)(16 * qt) * 2048) = ov;
;     }
; __device__ void gla_scan_item(const Params& p, int id) {
;     ...
;   for (int n = 0; n < nch; n += 2) {
;     const int nc0 = cfirst + cstep * n, nc1 = nc0 + cstep;
;     const int nc2 = (n + 2 < nch) ? nc1 + cstep : nc1;
;     BLOB_DMA(nc1, BLOB_BYTES);
;     VT_LOAD(vfB, nc1);
;     __builtin_amdgcn_sched_barrier(0);
;     scan_compute(smem, vfA, st, O + (size_t)(nc0 * 64 + fr) * 2048, fr, fq);
.LBB0_427:
	s_cmp_lg_u32 s99, 0
	s_cbranch_scc1 .Lld_halfB
	s_ashr_i32 s87, s86, 31
	s_lshl_b64 s[8:9], s[86:87], 18
	v_lshl_add_u64 v[0:1], v[158:159], 0, s[8:9]
	global_load_dwordx4 v[4:7], v[0:1], off
	s_nop 0
	global_load_dwordx4 v[0:3], v[0:1], off offset:64
	v_pk_mul_f32 v[74:75], v[94:95], v[34:35]
	v_pk_mul_f32 v[72:73], v[92:93], v[32:33]
	v_pk_mul_f32 v[78:79], v[90:91], v[30:31]
	v_pk_mul_f32 v[76:77], v[88:89], v[28:29]
	v_pk_mul_f32 v[30:31], v[102:103], v[42:43]
	v_pk_mul_f32 v[28:29], v[100:101], v[40:41]
	v_pk_mul_f32 v[34:35], v[98:99], v[38:39]
	v_pk_mul_f32 v[32:33], v[96:97], v[36:37]
	v_pk_mul_f32 v[38:39], v[26:27], v[50:51]
	v_pk_mul_f32 v[36:37], v[24:25], v[48:49]
	v_pk_mul_f32 v[42:43], v[22:23], v[46:47]
	v_pk_mul_f32 v[40:41], v[20:21], v[44:45]
	v_pk_mul_f32 v[46:47], v[118:119], v[66:67]
	v_pk_mul_f32 v[44:45], v[116:117], v[64:65]
	v_pk_mul_f32 v[50:51], v[114:115], v[62:63]
	v_pk_mul_f32 v[48:49], v[112:113], v[60:61]
	v_pk_mul_f32 v[62:63], v[126:127], v[58:59]
	v_pk_mul_f32 v[60:61], v[124:125], v[56:57]
	v_pk_mul_f32 v[66:67], v[122:123], v[54:55]
	v_pk_mul_f32 v[64:65], v[120:121], v[52:53]
	v_pk_mul_f32 v[54:55], v[134:135], v[150:151]
	v_pk_mul_f32 v[52:53], v[132:133], v[148:149]
	v_pk_mul_f32 v[58:59], v[130:131], v[146:147]
	v_pk_mul_f32 v[56:57], v[128:129], v[144:145]
	v_pk_mul_f32 v[18:19], v[142:143], v[18:19]
	v_pk_mul_f32 v[16:17], v[140:141], v[16:17]
	v_pk_mul_f32 v[70:71], v[138:139], v[70:71]
	v_pk_mul_f32 v[68:69], v[136:137], v[68:69]
	v_pk_mul_f32 v[86:87], v[86:87], v[110:111]
	v_pk_mul_f32 v[84:85], v[84:85], v[108:109]
	v_pk_mul_f32 v[82:83], v[82:83], v[106:107]
	v_pk_mul_f32 v[80:81], v[80:81], v[104:105]
	v_add_u32_e32 v20, s92, v176
	v_ashrrev_i32_e32 v21, 31, v20
	v_lshlrev_b64 v[20:21], 12, v[20:21]
	v_lshl_add_u64 v[196:197], v[156:157], 0, v[20:21]
	ds_read_b128 v[20:23], v170
	ds_read_b128 v[24:27], v170 offset:64
	ds_read_b128 v[88:91], v170 offset:16896
	ds_read_b128 v[92:95], v170 offset:16960
	ds_read_b128 v[96:99], v170 offset:8448
	ds_read_b128 v[100:103], v170 offset:128
	ds_read_b128 v[104:107], v170 offset:8512
	ds_read_b128 v[108:111], v170 offset:8576
	ds_read_b128 v[112:115], v170 offset:25344
	ds_read_b128 v[116:119], v170 offset:17024
	ds_read_b128 v[120:123], v170 offset:25408
	ds_read_b128 v[124:127], v170 offset:25472
	v_cvt_pk_bf16_f32 v128, v84, v85
	v_cvt_pk_bf16_f32 v129, v86, v87
	v_cvt_pk_bf16_f32 v130, v80, v81
	v_cvt_pk_bf16_f32 v131, v82, v83
	s_waitcnt lgkmcnt(0)
	s_nop 0
	v_mfma_f32_16x16x32_bf16 v[20:23], v[128:131], v[20:23], 0
	v_mfma_f32_16x16x32_bf16 v[96:99], v[128:131], v[96:99], 0
	v_mfma_f32_16x16x32_bf16 v[88:91], v[128:131], v[88:91], 0
	v_mfma_f32_16x16x32_bf16 v[112:115], v[128:131], v[112:115], 0
	ds_read_b128 v[128:131], v170 offset:192
	ds_read_b128 v[132:135], v170 offset:8640
	ds_read_b128 v[136:139], v170 offset:17088
	ds_read_b128 v[140:143], v170 offset:25536
	v_cvt_pk_bf16_f32 v144, v72, v73
	v_cvt_pk_bf16_f32 v145, v74, v75
	v_cvt_pk_bf16_f32 v146, v76, v77
	v_cvt_pk_bf16_f32 v147, v78, v79
	s_nop 1
	v_mfma_f32_16x16x32_bf16 v[20:23], v[144:147], v[24:27], v[20:23]
	v_mfma_f32_16x16x32_bf16 v[24:27], v[144:147], v[104:107], v[96:99]
	v_mfma_f32_16x16x32_bf16 v[88:91], v[144:147], v[92:95], v[88:91]
	v_mfma_f32_16x16x32_bf16 v[92:95], v[144:147], v[120:123], v[112:115]
	s_nop 0
	ds_read_b128 v[96:99], v170 offset:256
	ds_read_b128 v[104:107], v170 offset:8704
	ds_read_b128 v[112:115], v170 offset:17152
	ds_read_b128 v[120:123], v170 offset:25600
	v_cvt_pk_bf16_f32 v144, v28, v29
	v_cvt_pk_bf16_f32 v145, v30, v31
	v_cvt_pk_bf16_f32 v146, v32, v33
	v_cvt_pk_bf16_f32 v147, v34, v35
	s_nop 1
	v_mfma_f32_16x16x32_bf16 v[20:23], v[144:147], v[100:103], v[20:23]
	v_mfma_f32_16x16x32_bf16 v[24:27], v[144:147], v[108:111], v[24:27]
	v_mfma_f32_16x16x32_bf16 v[88:91], v[144:147], v[116:119], v[88:91]
	v_mfma_f32_16x16x32_bf16 v[92:95], v[144:147], v[124:127], v[92:95]
	ds_read_b128 v[100:103], v170 offset:320
	ds_read_b128 v[108:111], v170 offset:8768
	ds_read_b128 v[116:119], v170 offset:17216
	ds_read_b128 v[124:127], v170 offset:25664
	v_cvt_pk_bf16_f32 v144, v36, v37
	v_cvt_pk_bf16_f32 v145, v38, v39
	v_cvt_pk_bf16_f32 v146, v40, v41
	v_cvt_pk_bf16_f32 v147, v42, v43
	s_waitcnt lgkmcnt(0)
	s_nop 0
	v_mfma_f32_16x16x32_bf16 v[20:23], v[144:147], v[128:131], v[20:23]
	v_mfma_f32_16x16x32_bf16 v[24:27], v[144:147], v[132:135], v[24:27]
	v_mfma_f32_16x16x32_bf16 v[88:91], v[144:147], v[136:139], v[88:91]
	v_mfma_f32_16x16x32_bf16 v[92:95], v[144:147], v[140:143], v[92:95]
	ds_read_b128 v[128:131], v170 offset:384
	ds_read_b128 v[132:135], v170 offset:8832
	ds_read_b128 v[136:139], v170 offset:17280
	ds_read_b128 v[140:143], v170 offset:25728
	v_cvt_pk_bf16_f32 v144, v44, v45
	v_cvt_pk_bf16_f32 v145, v46, v47
	v_cvt_pk_bf16_f32 v146, v48, v49
	v_cvt_pk_bf16_f32 v147, v50, v51
	s_nop 1
	v_mfma_f32_16x16x32_bf16 v[20:23], v[144:147], v[96:99], v[20:23]
	v_mfma_f32_16x16x32_bf16 v[24:27], v[144:147], v[104:107], v[24:27]
	v_mfma_f32_16x16x32_bf16 v[88:91], v[144:147], v[112:115], v[88:91]
	v_mfma_f32_16x16x32_bf16 v[92:95], v[144:147], v[120:123], v[92:95]
	ds_read_b128 v[96:99], v170 offset:448
	ds_read_b128 v[104:107], v170 offset:8896
	ds_read_b128 v[112:115], v170 offset:17344
	ds_read_b128 v[120:123], v170 offset:25792
	v_cvt_pk_bf16_f32 v144, v60, v61
	v_cvt_pk_bf16_f32 v145, v62, v63
	v_cvt_pk_bf16_f32 v146, v64, v65
	v_cvt_pk_bf16_f32 v147, v66, v67
	s_nop 1
	v_mfma_f32_16x16x32_bf16 v[20:23], v[144:147], v[100:103], v[20:23]
	v_mfma_f32_16x16x32_bf16 v[24:27], v[144:147], v[108:111], v[24:27]
	v_mfma_f32_16x16x32_bf16 v[88:91], v[144:147], v[116:119], v[88:91]
	v_mfma_f32_16x16x32_bf16 v[92:95], v[144:147], v[124:127], v[92:95]
	ds_read_b128 v[100:103], v173
	ds_read_b128 v[108:111], v173 offset:2048
	ds_read_b128 v[116:119], v173 offset:4096
	ds_read_b128 v[124:127], v173 offset:6144
	v_cvt_pk_bf16_f32 v144, v52, v53
	v_cvt_pk_bf16_f32 v145, v54, v55
	v_cvt_pk_bf16_f32 v146, v56, v57
	v_cvt_pk_bf16_f32 v147, v58, v59
	s_waitcnt lgkmcnt(0)
; __device__ __forceinline__ void scan_compute(const char* cur, const bf16x8 (&vf)[2], f32x4 (&st)[16],
;                                              u16* O, const int fr, const int fq) {
;     ...
; #pragma unroll
;     for (int qt = 0; qt < 4; ++qt)
;       oacc[qt] = __builtin_amdgcn_mfma_f32_16x16x32_bf16(vf[0], af[0][qt], oacc[qt], 0, 0, 0);
;     __builtin_amdgcn_sched_barrier(0);
; #pragma unroll
;     for (int qt = 0; qt < 4; ++qt)
;       oacc[qt] = __builtin_amdgcn_mfma_f32_16x16x32_bf16(vf[1], af[1][qt], oacc[qt], 0, 0, 0);
;     __builtin_amdgcn_sched_barrier(0);
; #pragma unroll
;     for (int qt = 0; qt < 4; ++qt) {
;       u32x2 ov;
;       ov[0] = pack2(oacc[qt][0], oacc[qt][1]);
;       ov[1] = pack2(oacc[qt][2], oacc[qt][3]);
;       *(u32x2*)(O + (size_t)(16 * qt) * 2048) = ov;
;     }
;   }
;     ...
;   {
;     bf16x8 kf[3][2][2];
;     f32x4 eb[4][2];
;     ...
;     LOADK(0, 0, 0);
;     LOADK(1, 1, 1);
; #pragma unroll
;     for (int g = 0; g < 8; ++g) {
;       if (g < 6) { LOADK((g + 2) % 3, (g + 2) & 3, g + 2); }
;       __builtin_amdgcn_sched_barrier(0);
; #pragma unroll
;       for (int u = 0; u < 2; ++u) {
;         st[2 * g + u] = __builtin_amdgcn_mfma_f32_16x16x32_bf16(kf[g % 3][u][0], vf[0], st[2 * g + u], 0, 0, 0);
;       }
; #pragma unroll
;       for (int u = 0; u < 2; ++u) {
;         st[2 * g + u] = __builtin_amdgcn_mfma_f32_16x16x32_bf16(kf[g % 3][u][1], vf[1], st[2 * g + u], 0, 0, 0);
;       }
;       if (g > 0) { st[2 * g - 2] *= eb[(g - 1) & 3][0]; st[2 * g - 1] *= eb[(g - 1) & 3][1]; }
;       __builtin_amdgcn_sched_barrier(0);
;     }
;     st[14] *= eb[7 & 3][0];
;     st[15] *= eb[7 & 3][1];
	s_nop 0
	v_mfma_f32_16x16x32_bf16 v[20:23], v[144:147], v[128:131], v[20:23]
	v_mfma_f32_16x16x32_bf16 v[24:27], v[144:147], v[132:135], v[24:27]
	v_mfma_f32_16x16x32_bf16 v[88:91], v[144:147], v[136:139], v[88:91]
	v_mfma_f32_16x16x32_bf16 v[92:95], v[144:147], v[140:143], v[92:95]
	ds_read_b128 v[128:131], v171 offset:6144
	ds_read_b128 v[132:135], v171 offset:4096
	ds_read_b128 v[136:139], v171 offset:2048
	ds_read_b128 v[140:143], v171
	v_cvt_pk_bf16_f32 v144, v16, v17
	v_cvt_pk_bf16_f32 v145, v18, v19
	v_cvt_pk_bf16_f32 v146, v68, v69
	v_cvt_pk_bf16_f32 v147, v70, v71
	s_nop 1
	v_mfma_f32_16x16x32_bf16 v[20:23], v[144:147], v[96:99], v[20:23]
	v_mfma_f32_16x16x32_bf16 v[24:27], v[144:147], v[104:107], v[24:27]
	v_mfma_f32_16x16x32_bf16 v[88:91], v[144:147], v[112:115], v[88:91]
	v_mfma_f32_16x16x32_bf16 v[92:95], v[144:147], v[120:123], v[92:95]
	v_mfma_f32_16x16x32_bf16 v[20:23], v[12:15], v[100:103], v[20:23]
	v_mfma_f32_16x16x32_bf16 v[24:27], v[12:15], v[108:111], v[24:27]
	v_mfma_f32_16x16x32_bf16 v[88:91], v[12:15], v[116:119], v[88:91]
	v_mfma_f32_16x16x32_bf16 v[92:95], v[12:15], v[124:127], v[92:95]
	s_waitcnt lgkmcnt(0)
	v_mfma_f32_16x16x32_bf16 v[20:23], v[8:11], v[140:143], v[20:23]
	v_mfma_f32_16x16x32_bf16 v[24:27], v[8:11], v[136:139], v[24:27]
	v_mfma_f32_16x16x32_bf16 v[88:91], v[8:11], v[132:135], v[88:91]
	v_mfma_f32_16x16x32_bf16 v[92:95], v[8:11], v[128:131], v[92:95]
	s_nop 4
	v_cvt_pk_bf16_f32 v20, v20, v21
	v_cvt_pk_bf16_f32 v21, v22, v23
	v_add_co_u32_e32 v22, vcc, s2, v196
	global_store_dwordx2 v[196:197], v[20:21], off
	v_cvt_pk_bf16_f32 v20, v24, v25
	v_cvt_pk_bf16_f32 v21, v26, v27
	v_addc_co_u32_e32 v23, vcc, 0, v197, vcc
	global_store_dwordx2 v[22:23], v[20:21], off
	v_add_co_u32_e32 v22, vcc, s11, v196
	v_cvt_pk_bf16_f32 v20, v88, v89
	v_cvt_pk_bf16_f32 v21, v90, v91
	v_addc_co_u32_e32 v23, vcc, 0, v197, vcc
	global_store_dwordx2 v[22:23], v[20:21], off
	v_cvt_pk_bf16_f32 v198, v92, v93
	v_cvt_pk_bf16_f32 v199, v94, v95
	ds_read_b128 v[20:23], v174
	ds_read_b128 v[24:27], v174 offset:2048
	ds_read_b128 v[88:91], v172
	ds_read_b128 v[92:95], v172 offset:2048
	ds_read_b128 v[96:99], v175
	ds_read_b128 v[100:103], v175 offset:64
	ds_read_b128 v[104:107], v174 offset:4096
	ds_read_b128 v[108:111], v174 offset:6144
	ds_read_b128 v[112:115], v172 offset:4096
	ds_read_b128 v[116:119], v172 offset:6144
	ds_read_b128 v[120:123], v175 offset:128
	ds_read_b128 v[124:127], v175 offset:192
	ds_read_b128 v[128:131], v174 offset:8192
	ds_read_b128 v[132:135], v174 offset:10240
	ds_read_b128 v[136:139], v172 offset:8192
	ds_read_b128 v[140:143], v172 offset:10240
	ds_read_b128 v[144:147], v175 offset:256
	ds_read_b128 v[148:151], v175 offset:320
	v_add_co_u32_e32 v196, vcc, s88, v196
	s_nop 1
	v_addc_co_u32_e32 v197, vcc, 0, v197, vcc
	global_store_dwordx2 v[196:197], v[198:199], off
	s_waitcnt lgkmcnt(0)
	v_mfma_f32_16x16x32_bf16 v[20:23], v[20:23], v[12:15], v[84:87]
	v_mfma_f32_16x16x32_bf16 v[24:27], v[24:27], v[12:15], v[80:83]
	v_mfma_f32_16x16x32_bf16 v[20:23], v[88:91], v[8:11], v[20:23]
	v_mfma_f32_16x16x32_bf16 v[24:27], v[92:95], v[8:11], v[24:27]
	s_nop 0
	ds_read_b128 v[80:83], v174 offset:12288
	ds_read_b128 v[84:87], v174 offset:14336
	ds_read_b128 v[88:91], v172 offset:12288
	ds_read_b128 v[92:95], v172 offset:14336
	ds_read_b128 v[196:199], v175 offset:384
	ds_read_b128 v[200:203], v175 offset:448
	v_mfma_f32_16x16x32_bf16 v[72:75], v[104:107], v[12:15], v[72:75]
	v_mul_f32_e64 v22, v98, v22
	v_mul_f32_e64 v23, v99, v23
	v_pk_mul_f32 v[20:21], v[96:97], v[20:21]
	v_pk_mul_f32 v[26:27], v[102:103], v[26:27]
	v_mfma_f32_16x16x32_bf16 v[76:79], v[108:111], v[12:15], v[76:79]
	v_mul_f32_e64 v24, v100, v24
	v_mul_f32_e64 v25, v101, v25
	v_mfma_f32_16x16x32_bf16 v[72:75], v[112:115], v[8:11], v[72:75]
	v_mfma_f32_16x16x32_bf16 v[76:79], v[116:119], v[8:11], v[76:79]
	ds_read_b128 v[96:99], v174 offset:16384
	ds_read_b128 v[100:103], v174 offset:18432
	ds_read_b128 v[104:107], v172 offset:16384
	ds_read_b128 v[108:111], v172 offset:18432
	ds_read_b128 v[112:115], v175 offset:512
	ds_read_b128 v[116:119], v175 offset:576
	v_mfma_f32_16x16x32_bf16 v[28:31], v[128:131], v[12:15], v[28:31]
	v_mfma_f32_16x16x32_bf16 v[128:131], v[132:135], v[12:15], v[32:35]
	v_mfma_f32_16x16x32_bf16 v[132:135], v[136:139], v[8:11], v[28:31]
	s_nop 1
	v_mul_f32_e64 v34, v126, v78
	v_mul_f32_e64 v35, v127, v79
	v_pk_mul_f32 v[32:33], v[124:125], v[76:77]
	s_nop 0
	v_pk_mul_f32 v[30:31], v[122:123], v[74:75]
	v_pk_mul_f32 v[28:29], v[120:121], v[72:73]
	v_mfma_f32_16x16x32_bf16 v[72:75], v[140:143], v[8:11], v[128:131]
	ds_read_b128 v[76:79], v174 offset:20480
	ds_read_b128 v[120:123], v174 offset:22528
	ds_read_b128 v[124:127], v172 offset:20480
	ds_read_b128 v[128:131], v172 offset:22528
	ds_read_b128 v[136:139], v175 offset:640
	ds_read_b128 v[140:143], v175 offset:704
	s_waitcnt lgkmcnt(0)
; __device__ __forceinline__ void scan_compute(const char* cur, const bf16x8 (&vf)[2], f32x4 (&st)[16],
;                                              u16* O, const int fr, const int fq) {
;     ...
;     for (int g = 0; g < 8; ++g) {
;       if (g < 6) { LOADK((g + 2) % 3, (g + 2) & 3, g + 2); }
;       __builtin_amdgcn_sched_barrier(0);
; #pragma unroll
;       for (int u = 0; u < 2; ++u) {
;         st[2 * g + u] = __builtin_amdgcn_mfma_f32_16x16x32_bf16(kf[g % 3][u][0], vf[0], st[2 * g + u], 0, 0, 0);
;       }
; #pragma unroll
;       for (int u = 0; u < 2; ++u) {
;         st[2 * g + u] = __builtin_amdgcn_mfma_f32_16x16x32_bf16(kf[g % 3][u][1], vf[1], st[2 * g + u], 0, 0, 0);
;       }
;       if (g > 0) { st[2 * g - 2] *= eb[(g - 1) & 3][0]; st[2 * g - 1] *= eb[(g - 1) & 3][1]; }
;       __builtin_amdgcn_sched_barrier(0);
;     }
;     st[14] *= eb[7 & 3][0];
;     st[15] *= eb[7 & 3][1];
; __device__ void gla_scan_item(const Params& p, int id) {
;     ...
;     asm volatile("s_waitcnt vmcnt(0)" ::: "memory");
;     __syncthreads();
;     BLOB_DMA(nc2, 0);
;     VT_LOAD(vfA, nc2);
;     __builtin_amdgcn_sched_barrier(0);
;     scan_compute(smem + BLOB_BYTES, vfB, st, O + (size_t)(nc1 * 64 + fr) * 2048, fr, fq);
;     asm volatile("s_waitcnt vmcnt(0)" ::: "memory");
;     __syncthreads();
	v_mfma_f32_16x16x32_bf16 v[36:39], v[80:83], v[12:15], v[36:39]
	v_mfma_f32_16x16x32_bf16 v[80:83], v[84:87], v[12:15], v[40:43]
	s_nop 2
	v_mul_f32_e64 v42, v150, v74
	v_mul_f32_e64 v43, v151, v75
	v_pk_mul_f32 v[40:41], v[148:149], v[72:73]
	v_mfma_f32_16x16x32_bf16 v[72:75], v[92:95], v[8:11], v[80:83]
	v_mfma_f32_16x16x32_bf16 v[84:87], v[88:91], v[8:11], v[36:39]
	s_nop 2
	v_mul_f32_e64 v38, v146, v134
	v_mul_f32_e64 v39, v147, v135
	v_pk_mul_f32 v[36:37], v[144:145], v[132:133]
	ds_read_b128 v[80:83], v174 offset:24576
	ds_read_b128 v[88:91], v174 offset:26624
	ds_read_b128 v[92:95], v172 offset:24576
	ds_read_b128 v[132:135], v172 offset:26624
	ds_read_b128 v[144:147], v175 offset:768
	ds_read_b128 v[148:151], v175 offset:832
	v_mfma_f32_16x16x32_bf16 v[44:47], v[96:99], v[12:15], v[44:47]
	v_mfma_f32_16x16x32_bf16 v[96:99], v[100:103], v[12:15], v[48:51]
	s_nop 2
	v_mul_f32_e64 v50, v202, v74
	v_mul_f32_e64 v51, v203, v75
	v_pk_mul_f32 v[48:49], v[200:201], v[72:73]
	v_mfma_f32_16x16x32_bf16 v[72:75], v[108:111], v[8:11], v[96:99]
	v_mfma_f32_16x16x32_bf16 v[100:103], v[104:107], v[8:11], v[44:47]
	s_nop 2
	v_mul_f32_e64 v46, v198, v86
	v_mul_f32_e64 v47, v199, v87
	v_pk_mul_f32 v[44:45], v[196:197], v[84:85]
	ds_read_b128 v[84:87], v174 offset:28672
	ds_read_b128 v[96:99], v174 offset:30720
	ds_read_b128 v[104:107], v172 offset:28672
	ds_read_b128 v[108:111], v172 offset:30720
	ds_read_b128 v[196:199], v175 offset:896
	ds_read_b128 v[200:203], v175 offset:960
	v_mfma_f32_16x16x32_bf16 v[60:63], v[76:79], v[12:15], v[60:63]
	v_mfma_f32_16x16x32_bf16 v[76:79], v[120:123], v[12:15], v[64:67]
	s_nop 2
	v_mul_f32_e64 v66, v118, v74
	v_mul_f32_e64 v67, v119, v75
	v_pk_mul_f32 v[64:65], v[116:117], v[72:73]
	v_mfma_f32_16x16x32_bf16 v[72:75], v[128:131], v[8:11], v[76:79]
	v_mfma_f32_16x16x32_bf16 v[120:123], v[124:127], v[8:11], v[60:63]
	s_nop 2
	v_mul_f32_e64 v62, v114, v102
	v_mul_f32_e64 v63, v115, v103
	v_pk_mul_f32 v[60:61], v[112:113], v[100:101]
	s_waitcnt lgkmcnt(0)
	v_mfma_f32_16x16x32_bf16 v[76:79], v[88:91], v[12:15], v[56:59]
	v_mfma_f32_16x16x32_bf16 v[52:55], v[80:83], v[12:15], v[52:55]
	s_nop 1
	v_mul_f32_e64 v58, v142, v74
	v_mul_f32_e64 v59, v143, v75
	v_pk_mul_f32 v[56:57], v[140:141], v[72:73]
	v_mfma_f32_16x16x32_bf16 v[76:79], v[132:135], v[8:11], v[76:79]
	v_mfma_f32_16x16x32_bf16 v[80:83], v[92:95], v[8:11], v[52:55]
	s_nop 2
	v_mul_f32_e64 v54, v138, v122
	v_mul_f32_e64 v55, v139, v123
	v_pk_mul_f32 v[52:53], v[136:137], v[120:121]
	v_mfma_f32_16x16x32_bf16 v[16:19], v[84:87], v[12:15], v[16:19]
	s_nop 0
	v_mul_f32_e64 v74, v146, v82
	v_mul_f32_e64 v75, v147, v83
	v_pk_mul_f32 v[72:73], v[144:145], v[80:81]
	v_pk_mul_f32 v[78:79], v[150:151], v[78:79]
	v_mfma_f32_16x16x32_bf16 v[12:15], v[96:99], v[12:15], v[68:71]
	v_mul_f32_e64 v76, v148, v76
	v_mul_f32_e64 v77, v149, v77
	v_mfma_f32_16x16x32_bf16 v[16:19], v[104:107], v[8:11], v[16:19]
	v_mfma_f32_16x16x32_bf16 v[8:11], v[108:111], v[8:11], v[12:15]
	s_waitcnt vmcnt(4)
	s_nop 6
	v_mul_f32_e64 v70, v198, v18
	v_mul_f32_e64 v71, v199, v19
	v_pk_mul_f32 v[68:69], v[196:197], v[16:17]
	v_pk_mul_f32 v[18:19], v[202:203], v[10:11]
	v_pk_mul_f32 v[16:17], v[200:201], v[8:9]
.Lld_joinB:
	s_add_i32 s94, s94, 2
	s_add_i32 s92, s92, s93
	s_andn2_b64 vcc, exec, s[84:85]
	s_add_i32 s72, s72, s6
	s_barrier
	s_cbranch_vccz .LBB0_423
.LBB0_428:
	s_cmp_lg_u32 s99, 0
	s_cbranch_scc1 .Lld_halfA
	s_branch .LBB0_430
.Lld_halfA:
	s_cmp_ge_u32 s94, s90
	s_cselect_b64 s[84:85], -1, 0
	s_cmp_lt_u32 s94, s90
	s_cselect_b32 s86, s91, 0
	s_add_i32 s86, s86, s72
	v_mad_i64_i32 v[206:207], s[8:9], s86, v161, v[196:197]
	v_mad_i64_i32 v[208:209], s[8:9], s86, v161, v[198:199]
	v_mad_i64_i32 v[210:211], s[8:9], s86, v161, v[200:201]
	v_mad_i64_i32 v[212:213], s[8:9], s86, v161, v[202:203]
	v_mad_i64_i32 v[214:215], s[8:9], s86, v161, v[204:205]
	global_load_dwordx4 v[0:3], v[206:207], off
	global_load_dwordx4 v[4:7], v[206:207], off offset:1024
	global_load_dwordx4 v[8:11], v[206:207], off offset:2048
	global_load_dwordx4 v[12:15], v[206:207], off offset:3072
	global_load_dwordx4 v[16:19], v[208:209], off
	global_load_dwordx4 v[20:23], v[208:209], off offset:1024
	global_load_dwordx4 v[24:27], v[208:209], off offset:2048
	global_load_dwordx4 v[28:31], v[208:209], off offset:3072
	global_load_dwordx4 v[32:35], v[210:211], off
	global_load_dwordx4 v[36:39], v[210:211], off offset:1024
	global_load_dwordx4 v[40:43], v[210:211], off offset:2048
	global_load_dwordx4 v[44:47], v[210:211], off offset:3072
	global_load_dwordx4 v[48:51], v[212:213], off
	global_load_dwordx4 v[52:55], v[212:213], off offset:1024
	global_load_dwordx4 v[56:59], v[212:213], off offset:2048
	global_load_dwordx4 v[60:63], v[212:213], off offset:3072
	global_load_dwordx4 v[64:67], v[214:215], off
	global_load_dwordx4 v[68:71], v[214:215], off offset:1024
	global_load_dwordx4 v[72:75], v[214:215], off offset:2048
	s_waitcnt vmcnt(19)
	ds_write_b128 v217, v[76:79]
	ds_write_b128 v217, v[80:83] offset:1024
	ds_write_b128 v217, v[84:87] offset:2048
	ds_write_b128 v217, v[88:91] offset:3072
	ds_write_b128 v217, v[92:95] offset:4096
	ds_write_b128 v217, v[96:99] offset:5120
	ds_write_b128 v217, v[100:103] offset:6144
	ds_write_b128 v217, v[104:107] offset:7168
	ds_write_b128 v217, v[108:111] offset:8192
	ds_write_b128 v217, v[112:115] offset:9216
	ds_write_b128 v217, v[116:119] offset:10240
	ds_write_b128 v217, v[120:123] offset:11264
	ds_write_b128 v217, v[124:127] offset:12288
	ds_write_b128 v217, v[128:131] offset:13312
	ds_write_b128 v217, v[132:135] offset:14336
	ds_write_b128 v217, v[136:139] offset:15360
	ds_write_b128 v217, v[140:143] offset:16384
	ds_write_b128 v217, v[144:147] offset:17408
	ds_write_b128 v217, v[148:151] offset:18432
	s_waitcnt lgkmcnt(0)
	s_branch .Lld_joinA
; #define LOADQ(buf, s_)                                                                   \
;   _Pragma("unroll") for (int qt = 0; qt < 4; ++qt)                                        \
;     qf[buf][qt] = *(const u32x4*)(QEl + (16 * qt) * 264 + 32 * (s_));
; __device__ __forceinline__ void scan_compute(const char* cur, const bf16x8 (&vf)[2], f32x4 (&st)[16],
;                                              u16* O, const int fr, const int fq) {
;     ...
;     for (int s = 0; s < 8; ++s) {
;       if (s < 6) { LOADQ((s + 2) % 3, s + 2); }
;       else if (s == 6) {
; #pragma unroll
;         for (int qt = 0; qt < 4; ++qt) af[0][qt] = *(const bf16x8*)(AMl0 + (16 * qt) * 64);
;       } else {
; #pragma unroll
;         for (int qt = 0; qt < 4; ++qt) af[1][qt] = *(const bf16x8*)(AMl1 + (16 * qt) * 64);
;       }
;       u32x4 sw;
;       sw[0] = pack2(st[2 * s][0], st[2 * s][1]);
;       sw[1] = pack2(st[2 * s][2], st[2 * s][3]);
;       sw[2] = pack2(st[2 * s + 1][0], st[2 * s + 1][1]);
;       sw[3] = pack2(st[2 * s + 1][2], st[2 * s + 1][3]);
;       bf16x8 sf = __builtin_bit_cast(bf16x8, sw);
;       __builtin_amdgcn_sched_barrier(0);
; #pragma unroll
;       for (int qt = 0; qt < 4; ++qt)
;         oacc[qt] = __builtin_amdgcn_mfma_f32_16x16x32_bf16(sf, __builtin_bit_cast(bf16x8, qf[s % 3][qt]), oacc[qt], 0, 0, 0);
;       __builtin_amdgcn_sched_barrier(0);
;     }
.Lld_halfB:
	s_cmp_lt_u32 s94, s90
	s_cselect_b32 s87, s6, 0
	s_add_i32 s87, s87, s72
	v_mad_i64_i32 v[206:207], s[8:9], s87, v161, v[196:197]
	v_mad_i64_i32 v[208:209], s[8:9], s87, v161, v[198:199]
	v_mad_i64_i32 v[210:211], s[8:9], s87, v161, v[200:201]
	v_mad_i64_i32 v[212:213], s[8:9], s87, v161, v[202:203]
	v_mad_i64_i32 v[214:215], s[8:9], s87, v161, v[204:205]
	global_load_dwordx4 v[76:79], v[206:207], off
	global_load_dwordx4 v[80:83], v[206:207], off offset:1024
	global_load_dwordx4 v[84:87], v[206:207], off offset:2048
	global_load_dwordx4 v[88:91], v[206:207], off offset:3072
	global_load_dwordx4 v[92:95], v[208:209], off
	global_load_dwordx4 v[96:99], v[208:209], off offset:1024
	global_load_dwordx4 v[100:103], v[208:209], off offset:2048
	global_load_dwordx4 v[104:107], v[208:209], off offset:3072
	global_load_dwordx4 v[108:111], v[210:211], off
	global_load_dwordx4 v[112:115], v[210:211], off offset:1024
	global_load_dwordx4 v[116:119], v[210:211], off offset:2048
	global_load_dwordx4 v[120:123], v[210:211], off offset:3072
	global_load_dwordx4 v[124:127], v[212:213], off
	global_load_dwordx4 v[128:131], v[212:213], off offset:1024
	global_load_dwordx4 v[132:135], v[212:213], off offset:2048
	global_load_dwordx4 v[136:139], v[212:213], off offset:3072
	global_load_dwordx4 v[140:143], v[214:215], off
	global_load_dwordx4 v[144:147], v[214:215], off offset:1024
	global_load_dwordx4 v[148:151], v[214:215], off offset:2048
	s_waitcnt vmcnt(19)
	ds_write_b128 v216, v[0:3]
	ds_write_b128 v216, v[4:7] offset:1024
	ds_write_b128 v216, v[8:11] offset:2048
	ds_write_b128 v216, v[12:15] offset:3072
	ds_write_b128 v216, v[16:19] offset:4096
	ds_write_b128 v216, v[20:23] offset:5120
	ds_write_b128 v216, v[24:27] offset:6144
	ds_write_b128 v216, v[28:31] offset:7168
	ds_write_b128 v216, v[32:35] offset:8192
	ds_write_b128 v216, v[36:39] offset:9216
	ds_write_b128 v216, v[40:43] offset:10240
	ds_write_b128 v216, v[44:47] offset:11264
	ds_write_b128 v216, v[48:51] offset:12288
	ds_write_b128 v216, v[52:55] offset:13312
	ds_write_b128 v216, v[56:59] offset:14336
	ds_write_b128 v216, v[60:63] offset:15360
	ds_write_b128 v216, v[64:67] offset:16384
	ds_write_b128 v216, v[68:71] offset:17408
	ds_write_b128 v216, v[72:75] offset:18432
	s_waitcnt lgkmcnt(0)
	s_branch .Lld_joinB
.LBB0_430:
	s_ashr_i32 s73, s72, 31
	s_cmp_ge_u32 s94, s90
	s_cselect_b64 s[84:85], -1, 0
	s_cmp_lt_u32 s94, s90
	s_cselect_b32 s86, s91, 0
	s_lshl_b64 s[8:9], s[72:73], 18
	v_lshl_add_u64 v[8:9], v[158:159], 0, s[8:9]
	global_load_dwordx4 v[12:15], v[8:9], off
	s_nop 0
	global_load_dwordx4 v[8:11], v[8:9], off offset:64
	s_add_i32 s86, s86, s72
	v_add_u32_e32 v80, s92, v163
	v_ashrrev_i32_e32 v81, 31, v80
	v_lshlrev_b64 v[80:81], 12, v[80:81]
	v_lshl_add_u64 v[196:197], v[156:157], 0, v[80:81]
	ds_read_b128 v[80:83], v164
	ds_read_b128 v[84:87], v164 offset:64
	ds_read_b128 v[88:91], v164 offset:16896
	ds_read_b128 v[92:95], v164 offset:16960
	ds_read_b128 v[96:99], v164 offset:8448
	ds_read_b128 v[100:103], v164 offset:128
	ds_read_b128 v[104:107], v164 offset:8512
	ds_read_b128 v[108:111], v164 offset:8576
	ds_read_b128 v[112:115], v164 offset:25344
	ds_read_b128 v[116:119], v164 offset:17024
	ds_read_b128 v[120:123], v164 offset:25408
	ds_read_b128 v[124:127], v164 offset:25472
	v_cvt_pk_bf16_f32 v128, v20, v21
	v_cvt_pk_bf16_f32 v129, v22, v23
	v_cvt_pk_bf16_f32 v130, v24, v25
	v_cvt_pk_bf16_f32 v131, v26, v27
	s_waitcnt lgkmcnt(0)
	s_nop 0
	v_mfma_f32_16x16x32_bf16 v[80:83], v[128:131], v[80:83], 0
	v_mfma_f32_16x16x32_bf16 v[96:99], v[128:131], v[96:99], 0
	v_mfma_f32_16x16x32_bf16 v[88:91], v[128:131], v[88:91], 0
	v_mfma_f32_16x16x32_bf16 v[112:115], v[128:131], v[112:115], 0
	ds_read_b128 v[128:131], v164 offset:192
	ds_read_b128 v[132:135], v164 offset:8640
	ds_read_b128 v[136:139], v164 offset:17088
	ds_read_b128 v[140:143], v164 offset:25536
	v_cvt_pk_bf16_f32 v144, v28, v29
	v_cvt_pk_bf16_f32 v145, v30, v31
	v_cvt_pk_bf16_f32 v146, v32, v33
	v_cvt_pk_bf16_f32 v147, v34, v35
	s_nop 1
	v_mfma_f32_16x16x32_bf16 v[80:83], v[144:147], v[84:87], v[80:83]
	v_mfma_f32_16x16x32_bf16 v[84:87], v[144:147], v[104:107], v[96:99]
	v_mfma_f32_16x16x32_bf16 v[88:91], v[144:147], v[92:95], v[88:91]
	v_mfma_f32_16x16x32_bf16 v[92:95], v[144:147], v[120:123], v[112:115]
	s_nop 0
	ds_read_b128 v[96:99], v164 offset:256
	ds_read_b128 v[104:107], v164 offset:8704
	ds_read_b128 v[112:115], v164 offset:17152
	ds_read_b128 v[120:123], v164 offset:25600
	v_cvt_pk_bf16_f32 v144, v36, v37
	v_cvt_pk_bf16_f32 v145, v38, v39
	v_cvt_pk_bf16_f32 v146, v40, v41
	v_cvt_pk_bf16_f32 v147, v42, v43
	s_nop 1
	v_mfma_f32_16x16x32_bf16 v[80:83], v[144:147], v[100:103], v[80:83]
	v_mfma_f32_16x16x32_bf16 v[84:87], v[144:147], v[108:111], v[84:87]
	v_mfma_f32_16x16x32_bf16 v[88:91], v[144:147], v[116:119], v[88:91]
	v_mfma_f32_16x16x32_bf16 v[92:95], v[144:147], v[124:127], v[92:95]
	ds_read_b128 v[100:103], v164 offset:320
	ds_read_b128 v[108:111], v164 offset:8768
	ds_read_b128 v[116:119], v164 offset:17216
	ds_read_b128 v[124:127], v164 offset:25664
	v_cvt_pk_bf16_f32 v144, v44, v45
	v_cvt_pk_bf16_f32 v145, v46, v47
	v_cvt_pk_bf16_f32 v146, v48, v49
	v_cvt_pk_bf16_f32 v147, v50, v51
	s_waitcnt lgkmcnt(0)
; __device__ __forceinline__ void scan_compute(const char* cur, const bf16x8 (&vf)[2], f32x4 (&st)[16],
;                                              u16* O, const int fr, const int fq) {
;     ...
; #pragma unroll
;     for (int qt = 0; qt < 4; ++qt)
;       oacc[qt] = __builtin_amdgcn_mfma_f32_16x16x32_bf16(vf[0], af[0][qt], oacc[qt], 0, 0, 0);
;     __builtin_amdgcn_sched_barrier(0);
; #pragma unroll
;     for (int qt = 0; qt < 4; ++qt)
;       oacc[qt] = __builtin_amdgcn_mfma_f32_16x16x32_bf16(vf[1], af[1][qt], oacc[qt], 0, 0, 0);
;     __builtin_amdgcn_sched_barrier(0);
; #pragma unroll
;     for (int qt = 0; qt < 4; ++qt) {
;       u32x2 ov;
;       ov[0] = pack2(oacc[qt][0], oacc[qt][1]);
;       ov[1] = pack2(oacc[qt][2], oacc[qt][3]);
;       *(u32x2*)(O + (size_t)(16 * qt) * 2048) = ov;
;     }
;   }
;     ...
;   {
;     bf16x8 kf[3][2][2];
;     f32x4 eb[4][2];
;     ...
;     LOADK(0, 0, 0);
;     LOADK(1, 1, 1);
; #pragma unroll
;     for (int g = 0; g < 8; ++g) {
;       if (g < 6) { LOADK((g + 2) % 3, (g + 2) & 3, g + 2); }
;       __builtin_amdgcn_sched_barrier(0);
; #pragma unroll
;       for (int u = 0; u < 2; ++u) {
;         st[2 * g + u] = __builtin_amdgcn_mfma_f32_16x16x32_bf16(kf[g % 3][u][0], vf[0], st[2 * g + u], 0, 0, 0);
	s_nop 0
	v_mfma_f32_16x16x32_bf16 v[80:83], v[144:147], v[128:131], v[80:83]
	v_mfma_f32_16x16x32_bf16 v[84:87], v[144:147], v[132:135], v[84:87]
	v_mfma_f32_16x16x32_bf16 v[88:91], v[144:147], v[136:139], v[88:91]
	v_mfma_f32_16x16x32_bf16 v[92:95], v[144:147], v[140:143], v[92:95]
	ds_read_b128 v[128:131], v164 offset:384
	ds_read_b128 v[132:135], v164 offset:8832
	ds_read_b128 v[136:139], v164 offset:17280
	ds_read_b128 v[140:143], v164 offset:25728
	v_cvt_pk_bf16_f32 v144, v60, v61
	v_cvt_pk_bf16_f32 v145, v62, v63
	v_cvt_pk_bf16_f32 v146, v64, v65
	v_cvt_pk_bf16_f32 v147, v66, v67
	s_nop 1
	v_mfma_f32_16x16x32_bf16 v[80:83], v[144:147], v[96:99], v[80:83]
	v_mfma_f32_16x16x32_bf16 v[84:87], v[144:147], v[104:107], v[84:87]
	v_mfma_f32_16x16x32_bf16 v[88:91], v[144:147], v[112:115], v[88:91]
	v_mfma_f32_16x16x32_bf16 v[92:95], v[144:147], v[120:123], v[92:95]
	ds_read_b128 v[96:99], v164 offset:448
	ds_read_b128 v[104:107], v164 offset:8896
	ds_read_b128 v[112:115], v164 offset:17344
	ds_read_b128 v[120:123], v164 offset:25792
	v_cvt_pk_bf16_f32 v144, v52, v53
	v_cvt_pk_bf16_f32 v145, v54, v55
	v_cvt_pk_bf16_f32 v146, v56, v57
	v_cvt_pk_bf16_f32 v147, v58, v59
	s_nop 1
	v_mfma_f32_16x16x32_bf16 v[80:83], v[144:147], v[100:103], v[80:83]
	v_mfma_f32_16x16x32_bf16 v[84:87], v[144:147], v[108:111], v[84:87]
	v_mfma_f32_16x16x32_bf16 v[88:91], v[144:147], v[116:119], v[88:91]
	v_mfma_f32_16x16x32_bf16 v[92:95], v[144:147], v[124:127], v[92:95]
	ds_read_b128 v[100:103], v167
	ds_read_b128 v[108:111], v167 offset:2048
	ds_read_b128 v[116:119], v167 offset:4096
	ds_read_b128 v[124:127], v167 offset:6144
	v_cvt_pk_bf16_f32 v144, v72, v73
	v_cvt_pk_bf16_f32 v145, v74, v75
	v_cvt_pk_bf16_f32 v146, v76, v77
	v_cvt_pk_bf16_f32 v147, v78, v79
	s_waitcnt lgkmcnt(0)
	s_nop 0
	v_mfma_f32_16x16x32_bf16 v[80:83], v[144:147], v[128:131], v[80:83]
	v_mfma_f32_16x16x32_bf16 v[84:87], v[144:147], v[132:135], v[84:87]
	v_mfma_f32_16x16x32_bf16 v[88:91], v[144:147], v[136:139], v[88:91]
	v_mfma_f32_16x16x32_bf16 v[92:95], v[144:147], v[140:143], v[92:95]
	ds_read_b128 v[128:131], v165 offset:6144
	ds_read_b128 v[132:135], v165 offset:4096
	ds_read_b128 v[136:139], v165 offset:2048
	ds_read_b128 v[140:143], v165
	v_cvt_pk_bf16_f32 v144, v68, v69
	v_cvt_pk_bf16_f32 v145, v70, v71
	v_cvt_pk_bf16_f32 v146, v16, v17
	v_cvt_pk_bf16_f32 v147, v18, v19
	s_nop 1
	v_mfma_f32_16x16x32_bf16 v[80:83], v[144:147], v[96:99], v[80:83]
	v_mfma_f32_16x16x32_bf16 v[84:87], v[144:147], v[104:107], v[84:87]
	v_mfma_f32_16x16x32_bf16 v[88:91], v[144:147], v[112:115], v[88:91]
	v_mfma_f32_16x16x32_bf16 v[92:95], v[144:147], v[120:123], v[92:95]
	v_mfma_f32_16x16x32_bf16 v[80:83], v[4:7], v[100:103], v[80:83]
	v_mfma_f32_16x16x32_bf16 v[84:87], v[4:7], v[108:111], v[84:87]
	v_mfma_f32_16x16x32_bf16 v[88:91], v[4:7], v[116:119], v[88:91]
	v_mfma_f32_16x16x32_bf16 v[92:95], v[4:7], v[124:127], v[92:95]
	s_waitcnt lgkmcnt(0)
	v_mfma_f32_16x16x32_bf16 v[80:83], v[0:3], v[140:143], v[80:83]
	v_mfma_f32_16x16x32_bf16 v[84:87], v[0:3], v[136:139], v[84:87]
	v_mfma_f32_16x16x32_bf16 v[88:91], v[0:3], v[132:135], v[88:91]
	v_mfma_f32_16x16x32_bf16 v[92:95], v[0:3], v[128:131], v[92:95]
	s_nop 4
	v_cvt_pk_bf16_f32 v80, v80, v81
	v_cvt_pk_bf16_f32 v81, v82, v83
	v_add_co_u32_e32 v82, vcc, s2, v196
	global_store_dwordx2 v[196:197], v[80:81], off
	v_cvt_pk_bf16_f32 v80, v84, v85
	v_cvt_pk_bf16_f32 v81, v86, v87
	v_addc_co_u32_e32 v83, vcc, 0, v197, vcc
	global_store_dwordx2 v[82:83], v[80:81], off
	v_add_co_u32_e32 v82, vcc, s11, v196
	v_cvt_pk_bf16_f32 v80, v88, v89
	v_cvt_pk_bf16_f32 v81, v90, v91
	v_addc_co_u32_e32 v83, vcc, 0, v197, vcc
	global_store_dwordx2 v[82:83], v[80:81], off
	v_cvt_pk_bf16_f32 v198, v92, v93
	v_cvt_pk_bf16_f32 v199, v94, v95
	ds_read_b128 v[104:107], v168 offset:33792
	ds_read_b128 v[108:111], v168 offset:35840
	ds_read_b128 v[112:115], v166 offset:33792
	ds_read_b128 v[116:119], v166 offset:35840
	ds_read_b128 v[84:87], v169
	ds_read_b128 v[80:83], v169 offset:64
	ds_read_b128 v[120:123], v168 offset:37888
	ds_read_b128 v[124:127], v168 offset:39936
	ds_read_b128 v[128:131], v166 offset:37888
	ds_read_b128 v[132:135], v166 offset:39936
	ds_read_b128 v[92:95], v169 offset:128
	ds_read_b128 v[88:91], v169 offset:192
	ds_read_b128 v[136:139], v168 offset:41984
	ds_read_b128 v[140:143], v168 offset:44032
	ds_read_b128 v[144:147], v166 offset:41984
	ds_read_b128 v[148:151], v166 offset:44032
	ds_read_b128 v[100:103], v169 offset:256
	ds_read_b128 v[96:99], v169 offset:320
	v_add_co_u32_e32 v196, vcc, s88, v196
	s_nop 1
	v_addc_co_u32_e32 v197, vcc, 0, v197, vcc
	global_store_dwordx2 v[196:197], v[198:199], off
	s_waitcnt lgkmcnt(0)
; __device__ __forceinline__ void scan_compute(const char* cur, const bf16x8 (&vf)[2], f32x4 (&st)[16],
;                                              u16* O, const int fr, const int fq) {
;     ...
;     for (int g = 0; g < 8; ++g) {
;       if (g < 6) { LOADK((g + 2) % 3, (g + 2) & 3, g + 2); }
;       __builtin_amdgcn_sched_barrier(0);
; #pragma unroll
;       for (int u = 0; u < 2; ++u) {
;         st[2 * g + u] = __builtin_amdgcn_mfma_f32_16x16x32_bf16(kf[g % 3][u][0], vf[0], st[2 * g + u], 0, 0, 0);
;       }
; #pragma unroll
;       for (int u = 0; u < 2; ++u) {
;         st[2 * g + u] = __builtin_amdgcn_mfma_f32_16x16x32_bf16(kf[g % 3][u][1], vf[1], st[2 * g + u], 0, 0, 0);
;       }
;       if (g > 0) { st[2 * g - 2] *= eb[(g - 1) & 3][0]; st[2 * g - 1] *= eb[(g - 1) & 3][1]; }
;       __builtin_amdgcn_sched_barrier(0);
;     }
;     st[14] *= eb[7 & 3][0];
;     st[15] *= eb[7 & 3][1];
; __device__ void gla_scan_item(const Params& p, int id) {
;     ...
;     asm volatile("s_waitcnt vmcnt(0)" ::: "memory");
;     __syncthreads();
;   }
	v_mfma_f32_16x16x32_bf16 v[20:23], v[104:107], v[4:7], v[20:23]
	v_mfma_f32_16x16x32_bf16 v[24:27], v[108:111], v[4:7], v[24:27]
	v_mfma_f32_16x16x32_bf16 v[108:111], v[112:115], v[0:3], v[20:23]
	v_mfma_f32_16x16x32_bf16 v[104:107], v[116:119], v[0:3], v[24:27]
	ds_read_b128 v[196:199], v168 offset:46080
	ds_read_b128 v[200:203], v168 offset:48128
	ds_read_b128 v[204:207], v166 offset:46080
	ds_read_b128 v[208:211], v166 offset:48128
	s_nop 1
	ds_read_b128 v[24:27], v169 offset:384
	ds_read_b128 v[20:23], v169 offset:448
	v_mfma_f32_16x16x32_bf16 v[28:31], v[120:123], v[4:7], v[28:31]
	v_mfma_f32_16x16x32_bf16 v[112:115], v[124:127], v[4:7], v[32:35]
	v_mfma_f32_16x16x32_bf16 v[32:35], v[128:131], v[0:3], v[28:31]
	v_mfma_f32_16x16x32_bf16 v[28:31], v[132:135], v[0:3], v[112:115]
	ds_read_b128 v[212:215], v168 offset:50176
	ds_read_b128 v[216:219], v168 offset:52224
	ds_read_b128 v[220:223], v166 offset:50176
	ds_read_b128 v[224:227], v166 offset:52224
	ds_read_b128 v[116:119], v169 offset:512
	s_nop 0
	ds_read_b128 v[112:115], v169 offset:576
	v_mfma_f32_16x16x32_bf16 v[36:39], v[136:139], v[4:7], v[36:39]
	v_mfma_f32_16x16x32_bf16 v[120:123], v[140:143], v[4:7], v[40:43]
	v_mfma_f32_16x16x32_bf16 v[40:43], v[144:147], v[0:3], v[36:39]
	v_mfma_f32_16x16x32_bf16 v[36:39], v[148:151], v[0:3], v[120:123]
	ds_read_b128 v[144:147], v168 offset:54272
	ds_read_b128 v[148:151], v168 offset:56320
	ds_read_b128 v[228:231], v166 offset:54272
	ds_read_b128 v[232:235], v166 offset:56320
	ds_read_b128 v[124:127], v169 offset:640
	s_nop 0
	ds_read_b128 v[120:123], v169 offset:704
	s_waitcnt lgkmcnt(0)
	v_mfma_f32_16x16x32_bf16 v[44:47], v[196:199], v[4:7], v[44:47]
	v_mfma_f32_16x16x32_bf16 v[128:131], v[200:203], v[4:7], v[48:51]
	v_mfma_f32_16x16x32_bf16 v[48:51], v[204:207], v[0:3], v[44:47]
	v_mfma_f32_16x16x32_bf16 v[44:47], v[208:211], v[0:3], v[128:131]
	ds_read_b128 v[196:199], v168 offset:58368
	ds_read_b128 v[200:203], v168 offset:60416
	ds_read_b128 v[204:207], v166 offset:58368
	ds_read_b128 v[208:211], v166 offset:60416
	ds_read_b128 v[132:135], v169 offset:768
	s_nop 0
	ds_read_b128 v[128:131], v169 offset:832
	v_mfma_f32_16x16x32_bf16 v[60:63], v[212:215], v[4:7], v[60:63]
	v_mfma_f32_16x16x32_bf16 v[136:139], v[216:219], v[4:7], v[64:67]
	v_mfma_f32_16x16x32_bf16 v[64:67], v[220:223], v[0:3], v[60:63]
	v_mfma_f32_16x16x32_bf16 v[60:63], v[224:227], v[0:3], v[136:139]
	ds_read_b128 v[212:215], v168 offset:62464
	ds_read_b128 v[216:219], v168 offset:64512
	ds_read_b128 v[220:223], v166 offset:62464
	ds_read_b128 v[224:227], v166 offset:64512
	ds_read_b128 v[140:143], v169 offset:896
	s_nop 0
	ds_read_b128 v[136:139], v169 offset:960
	v_mfma_f32_16x16x32_bf16 v[52:55], v[144:147], v[4:7], v[52:55]
	v_mfma_f32_16x16x32_bf16 v[144:147], v[148:151], v[4:7], v[56:59]
	v_mfma_f32_16x16x32_bf16 v[56:59], v[228:231], v[0:3], v[52:55]
	v_mfma_f32_16x16x32_bf16 v[52:55], v[232:235], v[0:3], v[144:147]
	s_waitcnt lgkmcnt(0)
	v_mfma_f32_16x16x32_bf16 v[72:75], v[196:199], v[4:7], v[72:75]
	v_mfma_f32_16x16x32_bf16 v[76:79], v[200:203], v[4:7], v[76:79]
	v_mfma_f32_16x16x32_bf16 v[148:151], v[204:207], v[0:3], v[72:75]
	v_mfma_f32_16x16x32_bf16 v[144:147], v[208:211], v[0:3], v[76:79]
	v_mfma_f32_16x16x32_bf16 v[68:71], v[212:215], v[4:7], v[68:71]
	v_mfma_f32_16x16x32_bf16 v[4:7], v[216:219], v[4:7], v[16:19]
	v_mfma_f32_16x16x32_bf16 v[16:19], v[220:223], v[0:3], v[68:71]
	v_mfma_f32_16x16x32_bf16 v[68:71], v[224:227], v[0:3], v[4:7]
	s_waitcnt vmcnt(4)
.Lld_joinA:
	s_barrier
	s_branch .LBB0_427

; __device__ void attn_item(const Params& p, int id) {
;     ...
;     for (int k = 0; k < 8; ++k) *(u32x4*)(KL + (8 * kb + k) * 136 + c8 * 8) = kr[k];
;     transpose8x8(vr, vo);
; #pragma unroll
;     for (int j = 0; j < 8; ++j) *(u32x4*)(VT + (c8 * 8 + j) * 264 + ((kb ^ (c8 & 7)) << 3)) = vo[j];
;   }
;   const int uq = u0 + 16 * w + fr;
;   const int tokq = start + r + d * uq;
;   bf16x8 qf[4];
; #pragma unroll
;   for (int ks = 0; ks < 4; ++ks) qf[ks] = *(const bf16x8*)(base + (size_t)tokq * NP + 32 * ks + 8 * fq);
;   __syncthreads();
;   f32x4 s[9];
; #pragma unroll
;   for (int a = 0; a < 9; ++a) {
;     s[a] = f32x4{0.f, 0.f, 0.f, 0.f};
; #pragma unroll
;     for (int ks = 0; ks < 4; ++ks) {
;       bf16x8 kf = *(const bf16x8*)(KL + (16 * w + 16 * a + fr) * 136 + 32 * ks + 8 * fq);
;       s[a] = __builtin_amdgcn_mfma_f32_16x16x32_bf16(kf, qf[ks], s[a], 0, 0, 0);
;     }
;   }
.LBB0_472:
	s_or_b64 exec, exec, s[4:5]
	v_mul_lo_u32 v64, v81, s11
	v_lshl_add_u32 v64, v80, 4, v64
	s_waitcnt vmcnt(1)
	ds_write_b128 v64, v[16:19]
	ds_write_b128 v64, v[28:31] offset:272
	ds_write_b128 v64, v[32:35] offset:544
	ds_write_b128 v64, v[44:47] offset:816
	ds_write_b128 v64, v[48:51] offset:1088
	ds_write_b128 v64, v[52:55] offset:1360
	ds_write_b128 v64, v[56:59] offset:1632
	ds_write_b128 v64, v[60:63] offset:1904
	s_waitcnt vmcnt(0)
	v_and_b32_e32 v16, 0xffff, v4
	v_lshrrev_b32_e32 v4, 16, v4
	v_and_or_b32 v44, v0, s15, v4
	v_ashrrev_i32_e32 v4, 2, v79
	v_and_b32_e32 v30, -16, v4
	v_add_u32_e32 v4, s7, v30
	v_or_b32_e32 v32, v4, v80
	v_lshlrev_b32_e32 v4, s6, v32
	v_add_u32_e32 v28, s58, v4
	v_ashrrev_i32_e32 v29, 31, v28
	v_bfe_u32 v66, v79, 4, 2
	v_lshlrev_b64 v[34:35], 15, v[28:29]
	v_lshl_add_u64 v[34:35], s[0:1], 0, v[34:35]
	v_lshlrev_b32_e32 v98, 4, v66
	v_mov_b32_e32 v99, v65
	v_lshl_add_u64 v[82:83], v[34:35], 0, v[98:99]
	global_load_dwordx4 v[48:51], v[82:83], off
	global_load_dwordx4 v[56:59], v[82:83], off offset:64
	global_load_dwordx4 v[60:63], v[82:83], off offset:128
	v_lshl_or_b32 v16, v0, 16, v16
	global_load_dwordx4 v[82:85], v[82:83], off offset:192
	v_lshrrev_b32_e32 v0, 16, v12
	v_and_or_b32 v45, v8, s15, v0
	v_lshrrev_b32_e32 v0, 16, v24
	v_and_or_b32 v46, v20, s15, v0
	v_lshrrev_b32_e32 v0, 16, v40
	v_and_or_b32 v47, v36, s15, v0
	v_and_b32_e32 v0, 0xffff, v5
	v_lshl_or_b32 v52, v1, 16, v0
	v_and_b32_e32 v0, 0xffff, v13
	v_lshl_or_b32 v53, v9, 16, v0
	v_and_b32_e32 v0, 0xffff, v25
	v_lshl_or_b32 v54, v21, 16, v0
	v_and_b32_e32 v0, 0xffff, v41
	v_lshl_or_b32 v55, v37, 16, v0
	v_lshrrev_b32_e32 v0, 16, v5
	v_and_or_b32 v34, v1, s15, v0
	v_lshrrev_b32_e32 v0, 16, v13
	v_and_b32_e32 v19, 0xffff, v40
	v_and_or_b32 v35, v9, s15, v0
	v_lshrrev_b32_e32 v0, 16, v25
	v_lshl_or_b32 v19, v36, 16, v19
	v_and_or_b32 v36, v21, s15, v0
	v_lshrrev_b32_e32 v0, 16, v41
	v_and_or_b32 v37, v37, s15, v0
	v_and_b32_e32 v0, 0xffff, v6
	v_lshl_or_b32 v86, v2, 16, v0
	v_and_b32_e32 v0, 0xffff, v14
	v_lshl_or_b32 v87, v10, 16, v0
	v_and_b32_e32 v0, 0xffff, v26
	v_lshl_or_b32 v88, v22, 16, v0
	v_and_b32_e32 v0, 0xffff, v42
	v_lshl_or_b32 v89, v38, 16, v0
	v_lshrrev_b32_e32 v0, 16, v6
	v_and_or_b32 v90, v2, s15, v0
	v_lshrrev_b32_e32 v0, 16, v14
	v_and_or_b32 v91, v10, s15, v0
	v_lshrrev_b32_e32 v0, 16, v26
	v_and_or_b32 v92, v22, s15, v0
	v_lshrrev_b32_e32 v0, 16, v42
	v_and_or_b32 v93, v38, s15, v0
	v_and_b32_e32 v0, 0xffff, v7
	v_lshl_or_b32 v94, v3, 16, v0
	v_and_b32_e32 v0, 0xffff, v15
	v_lshl_or_b32 v95, v11, 16, v0
	v_and_b32_e32 v0, 0xffff, v27
	v_lshl_or_b32 v96, v23, 16, v0
	v_and_b32_e32 v0, 0xffff, v43
	v_bitop3_b32 v4, v81, v79, 7 bitop3:0x78
	v_and_b32_e32 v17, 0xffff, v12
	v_and_b32_e32 v18, 0xffff, v24
	v_lshl_or_b32 v97, v39, 16, v0
	v_lshrrev_b32_e32 v0, 16, v7
	v_lshlrev_b32_e32 v4, 4, v4
	v_mul_u32_u24_e32 v5, 0x1080, v80
	v_lshl_or_b32 v17, v8, 16, v17
	v_lshl_or_b32 v18, v20, 16, v18
	v_and_or_b32 v0, v3, s15, v0
	v_lshrrev_b32_e32 v1, 16, v15
	v_lshrrev_b32_e32 v2, 16, v27
	v_lshrrev_b32_e32 v3, 16, v43
	v_add3_u32 v4, v4, v5, s16
	v_and_or_b32 v1, v11, s15, v1
	v_and_or_b32 v2, v23, s15, v2
	v_and_or_b32 v3, v39, s15, v3
	ds_write_b128 v4, v[16:19]
	ds_write_b128 v4, v[44:47] offset:528
	ds_write_b128 v4, v[52:55] offset:1056
	ds_write_b128 v4, v[34:37] offset:1584
	ds_write_b128 v4, v[86:89] offset:2112
	ds_write_b128 v4, v[90:93] offset:2640
	ds_write_b128 v4, v[94:97] offset:3168
	ds_write_b128 v4, v[0:3] offset:3696
	v_or_b32_e32 v0, v30, v80
	v_mad_u64_u32 v[34:35], s[0:1], v0, s17, v[98:99]
	s_waitcnt lgkmcnt(0)
	s_barrier
	ds_read_b128 v[0:3], v34
	ds_read_b128 v[4:7], v34 offset:64
	s_waitcnt vmcnt(3) lgkmcnt(1)
	v_mfma_f32_16x16x32_bf16 v[0:3], v[0:3], v[48:51], 0
	ds_read_b128 v[8:11], v34 offset:128
	ds_read_b128 v[12:15], v34 offset:13184
	ds_read_b128 v[16:19], v34 offset:17536
	s_waitcnt vmcnt(2) lgkmcnt(3)
	v_mfma_f32_16x16x32_bf16 v[0:3], v[4:7], v[56:59], v[0:3]
	ds_read_b128 v[4:7], v34 offset:192
	ds_read_b128 v[20:23], v34 offset:21888
	ds_read_b128 v[24:27], v34 offset:26240
	s_waitcnt vmcnt(1) lgkmcnt(5)
	v_mfma_f32_16x16x32_bf16 v[0:3], v[8:11], v[60:63], v[0:3]
	ds_read_b128 v[8:11], v34 offset:4352
	ds_read_b128 v[44:47], v34 offset:30592
	s_add_i32 s1, s47, 1
	s_waitcnt vmcnt(0) lgkmcnt(4)
	v_mfma_f32_16x16x32_bf16 v[36:39], v[4:7], v[82:85], v[0:3]
	v_lshlrev_b32_e32 v31, 2, v66
	v_sub_u32_e32 v35, v31, v80
	v_add_u32_e32 v33, 1, v35
	ds_read_b128 v[0:3], v34 offset:4416
	s_waitcnt lgkmcnt(2)
	v_mfma_f32_16x16x32_bf16 v[4:7], v[8:11], v[48:51], 0
	ds_read_b128 v[8:11], v34 offset:4480
	s_lshl_b32 s0, 1, s6
	v_and_b32_e32 v31, 8, v31
	s_waitcnt lgkmcnt(1)
	v_mfma_f32_16x16x32_bf16 v[0:3], v[0:3], v[56:59], v[4:7]
	s_nop 2
	ds_read_b128 v[4:7], v34 offset:4544
	v_lshlrev_b32_e32 v64, 3, v66
	s_waitcnt lgkmcnt(1)
	v_mfma_f32_16x16x32_bf16 v[0:3], v[8:11], v[60:63], v[0:3]
	ds_read_b128 v[8:11], v34 offset:8704
	s_waitcnt lgkmcnt(1)
	v_mfma_f32_16x16x32_bf16 v[40:43], v[4:7], v[82:85], v[0:3]
	s_nop 4
	ds_read_b128 v[0:3], v34 offset:8768
	s_waitcnt lgkmcnt(1)
	v_mfma_f32_16x16x32_bf16 v[4:7], v[8:11], v[48:51], 0
	ds_read_b128 v[8:11], v34 offset:8832
	s_waitcnt lgkmcnt(1)
	v_mfma_f32_16x16x32_bf16 v[0:3], v[0:3], v[56:59], v[4:7]
	s_nop 4
	ds_read_b128 v[4:7], v34 offset:8896
	s_waitcnt lgkmcnt(1)
	v_mfma_f32_16x16x32_bf16 v[0:3], v[8:11], v[60:63], v[0:3]
	ds_read_b128 v[8:11], v34 offset:13056
	s_waitcnt lgkmcnt(1)
	v_mfma_f32_16x16x32_bf16 v[0:3], v[4:7], v[82:85], v[0:3]
	ds_read_b128 v[4:7], v34 offset:13120
	s_waitcnt lgkmcnt(1)
; __device__ void attn_item(const Params& p, int id) {
;     ...
; #pragma unroll
;   for (int a = 0; a < 9; ++a) {
;     s[a] = f32x4{0.f, 0.f, 0.f, 0.f};
; #pragma unroll
;     for (int ks = 0; ks < 4; ++ks) {
;       bf16x8 kf = *(const bf16x8*)(KL + (16 * w + 16 * a + fr) * 136 + 32 * ks + 8 * fq);
;       s[a] = __builtin_amdgcn_mfma_f32_16x16x32_bf16(kf, qf[ks], s[a], 0, 0, 0);
;     }
;   }
;   const float slope = exp2f(-(float)(h + 1)) * (float)d;
;   const float scale = 0.08838834764831845f;
;   float mx = -1e30f;
; #pragma unroll
;   for (int a = 0; a < 9; ++a)
; #pragma unroll
;     for (int jj = 0; jj < 4; ++jj) {
;       int delta = 16 * a + 4 * fq + jj - 64 - fr;
;       int uk = uq + delta;
;       int ad = delta < 0 ? -delta : delta;
;       bool valid = (ad <= 64) && (uk >= 0) && (uk < L);
;       float v = valid ? s[a][jj] * scale - slope * (float)ad : -1e30f;
;       s[a][jj] = v;
;       mx = fmaxf(mx, v);
	v_mfma_f32_16x16x32_bf16 v[8:11], v[8:11], v[48:51], 0
	s_waitcnt lgkmcnt(0)
	v_mfma_f32_16x16x32_bf16 v[4:7], v[4:7], v[56:59], v[8:11]
	s_nop 5
	ds_read_b128 v[8:11], v34 offset:13248
	v_mfma_f32_16x16x32_bf16 v[4:7], v[12:15], v[60:63], v[4:7]
	ds_read_b128 v[12:15], v34 offset:17408
	s_waitcnt lgkmcnt(1)
	v_mfma_f32_16x16x32_bf16 v[4:7], v[8:11], v[82:85], v[4:7]
	ds_read_b128 v[8:11], v34 offset:17472
	s_waitcnt lgkmcnt(1)
	v_mfma_f32_16x16x32_bf16 v[12:15], v[12:15], v[48:51], 0
	s_waitcnt lgkmcnt(0)
	v_mfma_f32_16x16x32_bf16 v[8:11], v[8:11], v[56:59], v[12:15]
	s_nop 5
	ds_read_b128 v[12:15], v34 offset:17600
	v_mfma_f32_16x16x32_bf16 v[8:11], v[16:19], v[60:63], v[8:11]
	ds_read_b128 v[16:19], v34 offset:21760
	s_waitcnt lgkmcnt(1)
	v_mfma_f32_16x16x32_bf16 v[8:11], v[12:15], v[82:85], v[8:11]
	ds_read_b128 v[12:15], v34 offset:21824
	s_waitcnt lgkmcnt(1)
	v_mfma_f32_16x16x32_bf16 v[16:19], v[16:19], v[48:51], 0
	s_waitcnt lgkmcnt(0)
	v_mfma_f32_16x16x32_bf16 v[12:15], v[12:15], v[56:59], v[16:19]
	s_nop 5
	ds_read_b128 v[16:19], v34 offset:21952
	v_mfma_f32_16x16x32_bf16 v[12:15], v[20:23], v[60:63], v[12:15]
	ds_read_b128 v[20:23], v34 offset:26112
	s_waitcnt lgkmcnt(1)
	v_mfma_f32_16x16x32_bf16 v[12:15], v[16:19], v[82:85], v[12:15]
	ds_read_b128 v[16:19], v34 offset:26176
	s_waitcnt lgkmcnt(1)
	v_mfma_f32_16x16x32_bf16 v[20:23], v[20:23], v[48:51], 0
	s_waitcnt lgkmcnt(0)
	v_mfma_f32_16x16x32_bf16 v[16:19], v[16:19], v[56:59], v[20:23]
	s_nop 5
	ds_read_b128 v[20:23], v34 offset:26304
	v_mfma_f32_16x16x32_bf16 v[16:19], v[24:27], v[60:63], v[16:19]
	ds_read_b128 v[24:27], v34 offset:30464
	s_waitcnt lgkmcnt(1)
	v_mfma_f32_16x16x32_bf16 v[16:19], v[20:23], v[82:85], v[16:19]
	ds_read_b128 v[20:23], v34 offset:30528
	s_waitcnt lgkmcnt(1)
	v_mfma_f32_16x16x32_bf16 v[24:27], v[24:27], v[48:51], 0
	s_waitcnt lgkmcnt(0)
	v_mfma_f32_16x16x32_bf16 v[20:23], v[20:23], v[56:59], v[24:27]
	s_nop 5
	ds_read_b128 v[24:27], v34 offset:30656
	v_mfma_f32_16x16x32_bf16 v[20:23], v[44:47], v[60:63], v[20:23]
	ds_read_b128 v[44:47], v34 offset:34816
	s_waitcnt lgkmcnt(1)
	v_mfma_f32_16x16x32_bf16 v[20:23], v[24:27], v[82:85], v[20:23]
	ds_read_b128 v[24:27], v34 offset:34880
	s_waitcnt lgkmcnt(1)
	v_mfma_f32_16x16x32_bf16 v[44:47], v[44:47], v[48:51], 0
	ds_read_b128 v[48:51], v34 offset:34944
	s_waitcnt lgkmcnt(1)
	v_mfma_f32_16x16x32_bf16 v[24:27], v[24:27], v[56:59], v[44:47]
	s_nop 4
	ds_read_b128 v[44:47], v34 offset:35008
	s_waitcnt lgkmcnt(1)
	v_mfma_f32_16x16x32_bf16 v[24:27], v[48:51], v[60:63], v[24:27]
	v_add_u32_e32 v48, v35, v32
	v_subrev_u32_e32 v49, 45, v48
	v_subrev_u32_e32 v50, 46, v48
	s_waitcnt lgkmcnt(0)
	v_mfma_f32_16x16x32_bf16 v[44:47], v[44:47], v[82:85], v[24:27]
	s_nop 2
	v_cvt_f32_ubyte0_e32 v24, s1
	v_cmp_lt_f32_e32 vcc, s18, v24
	v_sub_u32_e32 v26, 0, v33
	v_max_i32_e32 v27, v33, v26
	v_cndmask_b32_e32 v25, 0, v69, vcc
	v_sub_f32_e32 v24, v25, v24
	v_exp_f32_e32 v24, v24
	v_cvt_f32_u32_e32 v25, s0
	v_sub_u32_e32 v26, 0, v35
	s_and_b64 s[0:1], vcc, exec
	v_max_i32_e32 v26, v35, v26
	s_cselect_b32 s0, 0xffffffc0, 0
	v_cvt_f32_u32_e32 v26, v26
	v_cvt_f32_u32_e32 v27, v27
	v_ldexp_f32 v24, v24, s0
	v_cmp_lt_i32_e32 vcc, v189, v250
	v_mul_f32_e32 v24, v24, v25
	v_add_u32_e32 v33, v33, v32
	v_cndmask_b32_e32 v25, v249, v189, vcc
	v_lshlrev_b32_e32 v25, 2, v25
	v_pk_mul_f32 v[26:27], v[24:25], v[26:27] op_sel_hi:[0,1]
	v_pk_fma_f32 v[8:9], v[8:9], s[14:15], v[26:27] op_sel_hi:[1,0,1] neg_lo:[0,0,1] neg_hi:[0,0,1]
	v_cmp_gt_u32_e32 vcc, s57, v33
	v_sub_u32_e32 v26, 45, v35
	v_cvt_f32_u32_e32 v27, v26
	v_cndmask_b32_e32 v33, v70, v9, vcc
	v_sub_u32_e32 v9, 46, v35
	v_cvt_f32_u32_e32 v26, v9
	v_cmp_gt_u32_e32 vcc, s57, v48
	s_nop 1
	v_cndmask_b32_e32 v34, v70, v8, vcc
	v_pk_mul_f32 v[8:9], v[24:25], v[26:27] op_sel_hi:[0,1]
	v_pk_fma_f32 v[8:9], v[42:43], s[14:15], v[8:9] op_sel_hi:[1,0,1] neg_lo:[0,0,1] neg_hi:[0,0,1]
	v_cmp_gt_u32_e32 vcc, s57, v49
	v_sub_u32_e32 v26, 47, v35
	v_cvt_f32_u32_e32 v27, v26
	v_cndmask_b32_e32 v42, v70, v9, vcc
	v_sub_u32_e32 v9, 48, v35
	v_cvt_f32_u32_e32 v26, v9
	v_cmp_gt_u32_e32 vcc, s57, v50
	v_subrev_u32_e32 v49, 47, v48
	v_subrev_u32_e32 v50, 48, v48
	v_cndmask_b32_e32 v43, v70, v8, vcc
	v_pk_mul_f32 v[8:9], v[24:25], v[26:27] op_sel_hi:[0,1]
	v_pk_fma_f32 v[8:9], v[40:41], s[14:15], v[8:9] op_sel_hi:[1,0,1] neg_lo:[0,0,1] neg_hi:[0,0,1]
	v_cmp_gt_u32_e32 vcc, s57, v49
	v_sub_u32_e32 v49, 62, v35
	v_subrev_u32_e32 v27, 61, v48
	v_cndmask_b32_e32 v40, v70, v9, vcc
	v_cmp_gt_u32_e32 vcc, s57, v50
	v_subrev_u32_e32 v26, 62, v48
	v_cmp_gt_u32_e64 s[4:5], s57, v27
	v_cndmask_b32_e32 v41, v70, v8, vcc
	v_sub_u32_e32 v8, 61, v35
	v_cmp_gt_u32_e32 vcc, s29, v8
	v_cvt_f32_u32_e32 v9, v8
	v_cvt_f32_u32_e32 v8, v49
	v_cmp_gt_u32_e64 s[0:1], s29, v49
	v_cmp_gt_u32_e64 s[6:7], s57, v26
	s_and_b64 vcc, vcc, s[4:5]
	v_pk_mul_f32 v[8:9], v[24:25], v[8:9] op_sel_hi:[0,1]
	v_pk_fma_f32 v[8:9], v[38:39], s[14:15], v[8:9] op_sel_hi:[1,0,1] neg_lo:[0,0,1] neg_hi:[0,0,1]
	v_sub_u32_e32 v38, 64, v35
	v_cndmask_b32_e32 v49, v70, v9, vcc
	s_and_b64 vcc, s[0:1], s[6:7]
	v_cndmask_b32_e32 v50, v70, v8, vcc
	v_sub_u32_e32 v8, 63, v35
	v_cmp_gt_u32_e32 vcc, s29, v8
	v_cvt_f32_u32_e32 v9, v8
	v_cvt_f32_u32_e32 v8, v38
	v_subrev_u32_e32 v27, 63, v48
	v_subrev_u32_e32 v26, 64, v48
	v_cmp_gt_u32_e64 s[4:5], s57, v27
	v_pk_mul_f32 v[8:9], v[24:25], v[8:9] op_sel_hi:[0,1]
	v_cmp_gt_u32_e64 s[0:1], s29, v38
	v_cmp_gt_u32_e64 s[6:7], s57, v26
	v_pk_fma_f32 v[8:9], v[36:37], s[14:15], v[8:9] op_sel_hi:[1,0,1] neg_lo:[0,0,1] neg_hi:[0,0,1]
	s_and_b64 vcc, vcc, s[4:5]
	v_cndmask_b32_e32 v51, v70, v9, vcc
	s_and_b64 vcc, s[0:1], s[6:7]
; __device__ void attn_item(const Params& p, int id) {
;     ...
; #pragma unroll
;   for (int a = 0; a < 9; ++a)
; #pragma unroll
;     for (int jj = 0; jj < 4; ++jj) {
;       int delta = 16 * a + 4 * fq + jj - 64 - fr;
;       int uk = uq + delta;
;       int ad = delta < 0 ? -delta : delta;
;       bool valid = (ad <= 64) && (uk >= 0) && (uk < L);
;       float v = valid ? s[a][jj] * scale - slope * (float)ad : -1e30f;
;       s[a][jj] = v;
;       mx = fmaxf(mx, v);
;     }
;   mx = fmaxf(mx, __shfl_xor(mx, 16));
;   mx = fmaxf(mx, __shfl_xor(mx, 32));
	v_cndmask_b32_e32 v52, v70, v8, vcc
	v_max3_f32 v8, v52, s19, v51
	v_max3_f32 v8, v8, v50, v49
	v_max3_f32 v8, v8, v41, v40
	v_max3_f32 v53, v8, v43, v42
	v_add_u32_e32 v8, 0x43, v35
	v_add_u32_e32 v26, 0x42, v35
	v_add_u32_e32 v36, v8, v32
	v_cmp_gt_u32_e32 vcc, s29, v8
	v_cvt_f32_u32_e32 v9, v8
	v_cvt_f32_u32_e32 v8, v26
	v_add_u32_e32 v27, v26, v32
	v_cmp_gt_u32_e64 s[4:5], s57, v36
	v_cmp_gt_u32_e64 s[0:1], s29, v26
	v_pk_mul_f32 v[8:9], v[24:25], v[8:9] op_sel_hi:[0,1]
	v_cmp_gt_u32_e64 s[6:7], s57, v27
	v_pk_fma_f32 v[26:27], v[46:47], s[14:15], v[8:9] op_sel_hi:[1,0,1] neg_lo:[0,0,1] neg_hi:[0,0,1]
	s_and_b64 vcc, vcc, s[4:5]
	v_cndmask_b32_e32 v8, v70, v27, vcc
	s_and_b64 vcc, s[0:1], s[6:7]
	v_cndmask_b32_e32 v9, v70, v26, vcc
	v_add_u32_e32 v26, 0x41, v35
	v_add_u32_e32 v36, 64, v35
	v_add_u32_e32 v38, v26, v32
	v_cvt_f32_u32_e32 v27, v26
	v_cvt_f32_u32_e32 v26, v36
	v_add_u32_e32 v37, v36, v32
	v_cmp_lt_u32_e32 vcc, s30, v35
	v_cmp_gt_u32_e64 s[4:5], s57, v38
	v_pk_mul_f32 v[26:27], v[24:25], v[26:27] op_sel_hi:[0,1]
	v_cmp_gt_u32_e64 s[0:1], s29, v36
	v_cmp_gt_u32_e64 s[6:7], s57, v37
	v_pk_fma_f32 v[36:37], v[44:45], s[14:15], v[26:27] op_sel_hi:[1,0,1] neg_lo:[0,0,1] neg_hi:[0,0,1]
	s_and_b64 vcc, vcc, s[4:5]
	v_cndmask_b32_e32 v26, v70, v37, vcc
	v_add_u32_e32 v37, 50, v35
	v_add_u32_e32 v44, 51, v35
	v_cvt_f32_u32_e32 v39, v44
	v_cvt_f32_u32_e32 v38, v37
	s_and_b64 vcc, s[0:1], s[6:7]
	v_cndmask_b32_e32 v27, v70, v36, vcc
	v_add_u32_e32 v44, v44, v32
	v_add_u32_e32 v45, v37, v32
	v_pk_mul_f32 v[36:37], v[24:25], v[38:39] op_sel_hi:[0,1]
	v_pk_fma_f32 v[36:37], v[22:23], s[14:15], v[36:37] op_sel_hi:[1,0,1] neg_lo:[0,0,1] neg_hi:[0,0,1]
	v_cmp_gt_u32_e32 vcc, s57, v44
	v_add_u32_e32 v44, 49, v35
	v_cvt_f32_u32_e32 v39, v44
	v_cndmask_b32_e32 v22, v70, v37, vcc
	v_add_u32_e32 v37, 48, v35
	v_cvt_f32_u32_e32 v38, v37
	v_cmp_gt_u32_e32 vcc, s57, v45
	v_add_u32_e32 v45, v37, v32
	v_add_u32_e32 v44, v44, v32
	v_cndmask_b32_e32 v23, v70, v36, vcc
	v_pk_mul_f32 v[36:37], v[24:25], v[38:39] op_sel_hi:[0,1]
	v_add_u32_e32 v38, 34, v35
	v_add_u32_e32 v39, 35, v35
	v_pk_fma_f32 v[20:21], v[20:21], s[14:15], v[36:37] op_sel_hi:[1,0,1] neg_lo:[0,0,1] neg_hi:[0,0,1]
	v_cvt_f32_u32_e32 v37, v39
	v_cvt_f32_u32_e32 v36, v38
	v_cmp_gt_u32_e32 vcc, s57, v44
	v_add_u32_e32 v39, v39, v32
	v_add_u32_e32 v44, 33, v35
	v_cndmask_b32_e32 v21, v70, v21, vcc
	v_cmp_gt_u32_e32 vcc, s57, v45
	v_pk_mul_f32 v[36:37], v[24:25], v[36:37] op_sel_hi:[0,1]
	v_pk_fma_f32 v[18:19], v[18:19], s[14:15], v[36:37] op_sel_hi:[1,0,1] neg_lo:[0,0,1] neg_hi:[0,0,1]
	v_cndmask_b32_e32 v20, v70, v20, vcc
	v_cmp_gt_u32_e32 vcc, s57, v39
	v_add_u32_e32 v39, 32, v35
	v_cvt_f32_u32_e32 v37, v44
	v_cvt_f32_u32_e32 v36, v39
	v_add_u32_e32 v38, v38, v32
	v_cndmask_b32_e32 v19, v70, v19, vcc
	v_cmp_gt_u32_e32 vcc, s57, v38
	v_add_u32_e32 v38, v44, v32
	v_pk_mul_f32 v[36:37], v[24:25], v[36:37] op_sel_hi:[0,1]
	v_cndmask_b32_e32 v18, v70, v18, vcc
	v_pk_fma_f32 v[16:17], v[16:17], s[14:15], v[36:37] op_sel_hi:[1,0,1] neg_lo:[0,0,1] neg_hi:[0,0,1]
	v_cmp_gt_u32_e32 vcc, s57, v38
	v_add_u32_e32 v44, 19, v35
	v_cvt_f32_u32_e32 v37, v44
	v_cndmask_b32_e32 v38, v70, v17, vcc
	v_add_u32_e32 v17, 18, v35
	v_cvt_f32_u32_e32 v36, v17
	v_add_u32_e32 v39, v39, v32
	v_cmp_gt_u32_e32 vcc, s57, v39
	v_add_u32_e32 v44, v44, v32
	v_add_u32_e32 v45, v17, v32
	v_cndmask_b32_e32 v39, v70, v16, vcc
	v_pk_mul_f32 v[16:17], v[24:25], v[36:37] op_sel_hi:[0,1]
	v_pk_fma_f32 v[14:15], v[14:15], s[14:15], v[16:17] op_sel_hi:[1,0,1] neg_lo:[0,0,1] neg_hi:[0,0,1]
	v_cmp_gt_u32_e32 vcc, s57, v44
	v_add_u32_e32 v37, 17, v35
	v_cvt_f32_u32_e32 v17, v37
	v_cndmask_b32_e32 v36, v70, v15, vcc
	v_add_u32_e32 v15, 16, v35
	v_cvt_f32_u32_e32 v16, v15
	v_cmp_gt_u32_e32 vcc, s57, v45
	v_add_u32_e32 v37, v37, v32
	v_add_u32_e32 v45, v15, v32
	v_cndmask_b32_e32 v44, v70, v14, vcc
	v_pk_mul_f32 v[14:15], v[24:25], v[16:17] op_sel_hi:[0,1]
	v_pk_fma_f32 v[12:13], v[12:13], s[14:15], v[14:15] op_sel_hi:[1,0,1] neg_lo:[0,0,1] neg_hi:[0,0,1]
	v_cmp_gt_u32_e32 vcc, s57, v37
	v_add_u32_e32 v17, 3, v35
	v_sub_u32_e32 v15, 0, v17
	v_cndmask_b32_e32 v16, v70, v13, vcc
	v_add_u32_e32 v13, 2, v35
	v_sub_u32_e32 v14, 0, v13
	v_max_i32_e32 v14, v13, v14
	v_max_i32_e32 v15, v17, v15
	v_cvt_f32_u32_e32 v15, v15
	v_cvt_f32_u32_e32 v14, v14
	v_cmp_gt_u32_e32 vcc, s57, v45
	v_add_u32_e32 v17, v17, v32
	v_add_u32_e32 v32, v13, v32
	v_cndmask_b32_e32 v37, v70, v12, vcc
	v_pk_mul_f32 v[12:13], v[24:25], v[14:15] op_sel_hi:[0,1]
	v_pk_fma_f32 v[10:11], v[10:11], s[14:15], v[12:13] op_sel_hi:[1,0,1] neg_lo:[0,0,1] neg_hi:[0,0,1]
	v_cmp_gt_u32_e32 vcc, s57, v17
	v_sub_u32_e32 v12, 13, v35
	v_cvt_f32_u32_e32 v13, v12
	v_cndmask_b32_e32 v14, v70, v11, vcc
	v_sub_u32_e32 v11, 14, v35
	v_cvt_f32_u32_e32 v12, v11
	v_cmp_gt_u32_e32 vcc, s57, v32
	v_add_u32_e32 v17, -13, v48
	v_add_u32_e32 v32, -14, v48
	v_cndmask_b32_e32 v15, v70, v10, vcc
	v_pk_mul_f32 v[10:11], v[24:25], v[12:13] op_sel_hi:[0,1]
	v_pk_fma_f32 v[6:7], v[6:7], s[14:15], v[10:11] op_sel_hi:[1,0,1] neg_lo:[0,0,1] neg_hi:[0,0,1]
	v_cmp_gt_u32_e32 vcc, s57, v17
	v_sub_u32_e32 v10, 15, v35
	v_cvt_f32_u32_e32 v11, v10
	v_cndmask_b32_e32 v12, v70, v7, vcc
	v_sub_u32_e32 v7, 16, v35
	v_cvt_f32_u32_e32 v10, v7
	v_cmp_gt_u32_e32 vcc, s57, v32
	v_add_u32_e32 v17, -15, v48
	v_add_u32_e32 v32, -16, v48
	v_cndmask_b32_e32 v13, v70, v6, vcc
	v_pk_mul_f32 v[6:7], v[24:25], v[10:11] op_sel_hi:[0,1]
	v_pk_fma_f32 v[4:5], v[4:5], s[14:15], v[6:7] op_sel_hi:[1,0,1] neg_lo:[0,0,1] neg_hi:[0,0,1]
	v_cmp_gt_u32_e32 vcc, s57, v17
	v_sub_u32_e32 v6, 29, v35
	v_cvt_f32_u32_e32 v7, v6
	v_cndmask_b32_e32 v10, v70, v5, vcc
; __device__ void attn_item(const Params& p, int id) {
;     ...
;       mx = fmaxf(mx, v);
;     }
;   mx = fmaxf(mx, __shfl_xor(mx, 16));
;   mx = fmaxf(mx, __shfl_xor(mx, 32));
;   float l = 0.f;
; #pragma unroll
;   for (int a = 0; a < 9; ++a)
; #pragma unroll
;     for (int jj = 0; jj < 4; ++jj) {
;       float e = s[a][jj] > -1e29f ? __expf(s[a][jj] - mx) : 0.f;
;       s[a][jj] = e;
;       l += e;
;     }
;   l += __shfl_xor(l, 16);
;   l += __shfl_xor(l, 32);
	v_sub_u32_e32 v5, 30, v35
	v_cvt_f32_u32_e32 v6, v5
	v_cmp_gt_u32_e32 vcc, s57, v32
	v_subrev_u32_e32 v17, 29, v48
	v_subrev_u32_e32 v32, 30, v48
	v_cndmask_b32_e32 v11, v70, v4, vcc
	v_pk_mul_f32 v[4:5], v[24:25], v[6:7] op_sel_hi:[0,1]
	v_pk_fma_f32 v[2:3], v[2:3], s[14:15], v[4:5] op_sel_hi:[1,0,1] neg_lo:[0,0,1] neg_hi:[0,0,1]
	v_cmp_gt_u32_e32 vcc, s57, v17
	v_sub_u32_e32 v4, 31, v35
	v_cvt_f32_u32_e32 v5, v4
	v_cndmask_b32_e32 v6, v70, v3, vcc
	v_sub_u32_e32 v3, 32, v35
	v_cvt_f32_u32_e32 v4, v3
	v_cmp_gt_u32_e32 vcc, s57, v32
	v_subrev_u32_e32 v17, 31, v48
	v_subrev_u32_e32 v32, 32, v48
	v_cndmask_b32_e32 v7, v70, v2, vcc
	v_pk_mul_f32 v[2:3], v[24:25], v[4:5] op_sel_hi:[0,1]
	v_pk_fma_f32 v[0:1], v[0:1], s[14:15], v[2:3] op_sel_hi:[1,0,1] neg_lo:[0,0,1] neg_hi:[0,0,1]
	v_cmp_gt_u32_e32 vcc, s57, v17
	s_nop 1
	v_cndmask_b32_e32 v1, v70, v1, vcc
	v_cmp_gt_u32_e32 vcc, s57, v32
	s_nop 1
	v_cndmask_b32_e32 v3, v70, v0, vcc
	v_max3_f32 v0, v53, v3, v1
	v_max3_f32 v0, v0, v7, v6
	v_max3_f32 v0, v0, v11, v10
	v_max3_f32 v0, v0, v13, v12
	v_max3_f32 v0, v0, v34, v33
	v_max3_f32 v0, v0, v15, v14
	v_max3_f32 v0, v0, v37, v16
	v_max3_f32 v0, v0, v44, v36
	v_max3_f32 v0, v0, v39, v38
	v_max3_f32 v0, v0, v18, v19
	v_max3_f32 v0, v0, v20, v21
	v_max3_f32 v0, v0, v23, v22
	v_max3_f32 v0, v0, v27, v26
	v_max3_f32 v2, v0, v9, v8
	ds_bpermute_b32 v4, v25, v2
	v_cmp_lt_i32_e32 vcc, v251, v250
	s_waitcnt lgkmcnt(0)
	v_max_f32_e32 v4, v4, v4
	v_cndmask_b32_e32 v0, v249, v251, vcc
	v_lshlrev_b32_e32 v0, 2, v0
	v_max_f32_e32 v2, v2, v4
	ds_bpermute_b32 v4, v0, v2
	v_cmp_lt_f32_e32 vcc, s28, v51
	s_waitcnt lgkmcnt(0)
	v_max_f32_e32 v4, v4, v4
	v_max_f32_e32 v2, v2, v4
	v_sub_f32_e32 v5, v51, v2
	v_sub_f32_e32 v4, v52, v2
	v_mul_f32_e32 v5, 0x3fb8aa3b, v5
	v_exp_f32_e32 v5, v5
	v_mul_f32_e32 v4, 0x3fb8aa3b, v4
	v_sub_f32_e32 v32, v49, v2
	v_exp_f32_e32 v4, v4
	v_sub_f32_e32 v17, v50, v2
	v_mul_f32_e32 v32, 0x3fb8aa3b, v32
	v_exp_f32_e32 v32, v32
	v_mul_f32_e32 v17, 0x3fb8aa3b, v17
	v_exp_f32_e32 v17, v17
	v_cndmask_b32_e32 v5, 0, v5, vcc
	v_cmp_lt_f32_e32 vcc, s28, v52
	s_nop 1
	v_cndmask_b32_e32 v24, 0, v4, vcc
	v_cmp_lt_f32_e32 vcc, s28, v49
	v_add_f32_e32 v4, 0, v24
	v_add_f32_e32 v4, v5, v4
	v_cndmask_b32_e32 v35, 0, v32, vcc
	v_cmp_lt_f32_e32 vcc, s28, v50
	v_sub_f32_e32 v32, v40, v2
	v_mul_f32_e32 v32, 0x3fb8aa3b, v32
	v_cndmask_b32_e32 v45, 0, v17, vcc
	v_sub_f32_e32 v17, v41, v2
	v_exp_f32_e32 v32, v32
	v_mul_f32_e32 v17, 0x3fb8aa3b, v17
	v_exp_f32_e32 v17, v17
	v_cmp_lt_f32_e32 vcc, s28, v40
	v_add_f32_e32 v4, v45, v4
	v_add_f32_e32 v4, v35, v4
	v_cndmask_b32_e32 v40, 0, v32, vcc
	v_cmp_lt_f32_e32 vcc, s28, v41
	v_sub_f32_e32 v32, v42, v2
	v_mul_f32_e32 v32, 0x3fb8aa3b, v32
	v_cndmask_b32_e32 v41, 0, v17, vcc
	v_sub_f32_e32 v17, v43, v2
	v_exp_f32_e32 v32, v32
	v_mul_f32_e32 v17, 0x3fb8aa3b, v17
	v_exp_f32_e32 v17, v17
	v_cmp_lt_f32_e32 vcc, s28, v42
	v_add_f32_e32 v4, v41, v4
	v_add_f32_e32 v4, v40, v4
	v_cndmask_b32_e32 v42, 0, v32, vcc
	v_cmp_lt_f32_e32 vcc, s28, v43
	v_sub_f32_e32 v32, v1, v2
	v_mul_f32_e32 v32, 0x3fb8aa3b, v32
	v_cndmask_b32_e32 v43, 0, v17, vcc
	v_sub_f32_e32 v17, v3, v2
	v_exp_f32_e32 v32, v32
	v_mul_f32_e32 v17, 0x3fb8aa3b, v17
	v_exp_f32_e32 v17, v17
	v_cmp_lt_f32_e32 vcc, s28, v1
	v_add_f32_e32 v4, v43, v4
	v_add_f32_e32 v4, v42, v4
	v_cndmask_b32_e32 v67, 0, v32, vcc
	v_cmp_lt_f32_e32 vcc, s28, v3
	v_sub_f32_e32 v3, v7, v2
	v_mul_f32_e32 v3, 0x3fb8aa3b, v3
	v_cndmask_b32_e32 v84, 0, v17, vcc
	v_add_f32_e32 v1, v84, v4
	v_sub_f32_e32 v4, v6, v2
	v_mul_f32_e32 v4, 0x3fb8aa3b, v4
	v_exp_f32_e32 v4, v4
	v_exp_f32_e32 v3, v3
	v_cmp_lt_f32_e32 vcc, s28, v6
	v_add_f32_e32 v1, v67, v1
	v_cvt_pk_bf16_f32 v32, v24, v5
	v_cndmask_b32_e32 v85, 0, v4, vcc
	v_cmp_lt_f32_e32 vcc, s28, v7
	v_sub_f32_e32 v4, v10, v2
	v_mul_f32_e32 v4, 0x3fb8aa3b, v4
	v_cndmask_b32_e32 v86, 0, v3, vcc
	v_sub_f32_e32 v3, v11, v2
	v_exp_f32_e32 v4, v4
	v_mul_f32_e32 v3, 0x3fb8aa3b, v3
	v_exp_f32_e32 v3, v3
	v_cmp_lt_f32_e32 vcc, s28, v10
	v_add_f32_e32 v1, v86, v1
	v_add_f32_e32 v1, v85, v1
	v_cndmask_b32_e32 v92, 0, v4, vcc
	v_cmp_lt_f32_e32 vcc, s28, v11
	v_sub_f32_e32 v4, v12, v2
	v_mul_f32_e32 v4, 0x3fb8aa3b, v4
	v_cndmask_b32_e32 v93, 0, v3, vcc
	v_sub_f32_e32 v3, v13, v2
	v_exp_f32_e32 v4, v4
	v_mul_f32_e32 v3, 0x3fb8aa3b, v3
	v_exp_f32_e32 v3, v3
	v_cmp_lt_f32_e32 vcc, s28, v12
	v_add_f32_e32 v1, v93, v1
	v_add_f32_e32 v1, v92, v1
	v_cndmask_b32_e32 v94, 0, v4, vcc
	v_cmp_lt_f32_e32 vcc, s28, v13
	v_sub_f32_e32 v4, v33, v2
	v_mul_f32_e32 v4, 0x3fb8aa3b, v4
	v_cndmask_b32_e32 v95, 0, v3, vcc
	v_sub_f32_e32 v3, v34, v2
	v_exp_f32_e32 v4, v4
	v_mul_f32_e32 v3, 0x3fb8aa3b, v3
	v_exp_f32_e32 v3, v3
	v_cmp_lt_f32_e32 vcc, s28, v33
	v_add_f32_e32 v1, v95, v1
	v_add_f32_e32 v1, v94, v1
	v_cndmask_b32_e32 v104, 0, v4, vcc
	v_cmp_lt_f32_e32 vcc, s28, v34
	v_sub_f32_e32 v4, v14, v2
	v_mul_f32_e32 v4, 0x3fb8aa3b, v4
	v_cndmask_b32_e32 v105, 0, v3, vcc
	v_sub_f32_e32 v3, v15, v2
	v_exp_f32_e32 v4, v4
	v_mul_f32_e32 v3, 0x3fb8aa3b, v3
	v_exp_f32_e32 v3, v3
	v_cmp_lt_f32_e32 vcc, s28, v14
	v_add_f32_e32 v1, v105, v1
	v_add_f32_e32 v1, v104, v1
	v_cndmask_b32_e32 v106, 0, v4, vcc
	v_cmp_lt_f32_e32 vcc, s28, v15
	v_sub_f32_e32 v4, v16, v2
	v_mul_f32_e32 v4, 0x3fb8aa3b, v4
	v_cndmask_b32_e32 v107, 0, v3, vcc
	v_sub_f32_e32 v3, v37, v2
	v_exp_f32_e32 v4, v4
	v_mul_f32_e32 v3, 0x3fb8aa3b, v3
	v_exp_f32_e32 v3, v3
	v_cmp_lt_f32_e32 vcc, s28, v16
	v_add_f32_e32 v1, v107, v1
	v_add_f32_e32 v1, v106, v1
	v_cndmask_b32_e32 v108, 0, v4, vcc
	v_cmp_lt_f32_e32 vcc, s28, v37
	v_sub_f32_e32 v4, v36, v2
	v_mul_f32_e32 v4, 0x3fb8aa3b, v4
	v_cndmask_b32_e32 v109, 0, v3, vcc
; __device__ void attn_item(const Params& p, int id) {
;     ...
;       float e = s[a][jj] > -1e29f ? __expf(s[a][jj] - mx) : 0.f;
;       s[a][jj] = e;
;       l += e;
;     }
;   l += __shfl_xor(l, 16);
;   l += __shfl_xor(l, 32);
;   f32x4 o[8];
; #pragma unroll
;   for (int ct = 0; ct < 8; ++ct) o[ct] = f32x4{0.f, 0.f, 0.f, 0.f};
; #pragma unroll
;   for (int s2 = 0; s2 < 5; ++s2) {
;     const int a0 = 2 * s2, a1 = (s2 < 4) ? 2 * s2 + 1 : 2 * s2;
;     u32x4 pw;
;     pw[0] = pack2(s[a0][0], s[a0][1]);
;     pw[1] = pack2(s[a0][2], s[a0][3]);
;     if (s2 < 4) { pw[2] = pack2(s[a1][0], s[a1][1]); pw[3] = pack2(s[a1][2], s[a1][3]); }
;     else { pw[2] = 0u; pw[3] = 0u; }
;     bf16x8 pf = __builtin_bit_cast(bf16x8, pw);
;     const int key0 = 16 * w + 16 * a0 + 4 * fq, key1 = 16 * w + 16 * a1 + 4 * fq;
; #pragma unroll
;     for (int ct = 0; ct < 8; ++ct) {
;       const int c = 16 * ct + fr;
;       const int sw = (c >> 3) & 7;
;       u32x2 lo = *(const u32x2*)(VT + c * 264 + ((((key0 >> 3) ^ sw) << 3) | (key0 & 7)));
;       u32x2 hi = *(const u32x2*)(VT + c * 264 + ((((key1 >> 3) ^ sw) << 3) | (key1 & 7)));
;       u32x4 vw = {lo[0], lo[1], hi[0], hi[1]};
;       o[ct] = __builtin_amdgcn_mfma_f32_16x16x32_bf16(__builtin_bit_cast(bf16x8, vw), pf, o[ct], 0, 0, 0);
;     }
	v_sub_f32_e32 v3, v44, v2
	v_exp_f32_e32 v4, v4
	v_mul_f32_e32 v3, 0x3fb8aa3b, v3
	v_exp_f32_e32 v3, v3
	v_cmp_lt_f32_e32 vcc, s28, v36
	v_add_f32_e32 v1, v109, v1
	v_add_f32_e32 v1, v108, v1
	v_cndmask_b32_e32 v110, 0, v4, vcc
	v_cmp_lt_f32_e32 vcc, s28, v44
	v_sub_f32_e32 v4, v38, v2
	v_mul_f32_e32 v4, 0x3fb8aa3b, v4
	v_cndmask_b32_e32 v111, 0, v3, vcc
	v_sub_f32_e32 v3, v39, v2
	v_exp_f32_e32 v4, v4
	v_mul_f32_e32 v3, 0x3fb8aa3b, v3
	v_exp_f32_e32 v3, v3
	v_cmp_lt_f32_e32 vcc, s28, v38
	v_add_f32_e32 v1, v111, v1
	v_add_f32_e32 v1, v110, v1
	v_cndmask_b32_e32 v16, 0, v4, vcc
	v_cmp_lt_f32_e32 vcc, s28, v39
	v_or_b32_e32 v4, v31, v30
	v_add_u32_e32 v24, 16, v4
	v_cndmask_b32_e32 v17, 0, v3, vcc
	v_add_f32_e32 v11, v17, v1
	v_and_b32_e32 v1, 8, v79
	v_mad_u32_u24 v3, v80, s31, v71
	v_bitop3_b32 v1, v31, v1, v30 bitop3:0x36
	v_lshl_add_u32 v5, v1, 1, v3
	v_and_b32_e32 v1, 8, v64
	v_or_b32_e32 v5, v5, v1
	ds_read2st64_b64 v[12:15], v5 offset1:66
	v_bitop3_b32 v5, v24, v79, 8 bitop3:0x78
	v_lshl_add_u32 v5, v5, 1, v3
	v_or_b32_e32 v6, 16, v80
	v_bitop3_b32 v7, v80, 24, 16 bitop3:0xc8
	v_or_b32_e32 v5, v5, v1
	v_bitop3_b32 v7, v31, v7, v30 bitop3:0x36
	v_bitop3_b32 v10, v24, v6, 24 bitop3:0x78
	ds_read2st64_b64 v[36:39], v5 offset1:66
	v_mad_u32_u24 v5, v80, s31, v72
	v_lshlrev_b32_e32 v56, 1, v7
	v_lshlrev_b32_e32 v57, 1, v10
	v_add_u32_e32 v7, v5, v56
	v_add_u32_e32 v10, v5, v57
	v_or_b32_e32 v7, v7, v1
	v_or_b32_e32 v10, v10, v1
	v_cvt_pk_bf16_f32 v33, v45, v35
	v_cvt_pk_bf16_f32 v34, v41, v40
	s_waitcnt lgkmcnt(1)
	v_mov_b32_e32 v40, v12
	ds_read_b64 v[44:45], v7
	ds_read_b64 v[46:47], v10
	v_or_b32_e32 v10, 32, v80
	v_bitop3_b32 v12, v80, 40, 32 bitop3:0xc8
	v_mov_b32_e32 v41, v13
	v_bitop3_b32 v12, v31, v12, v30 bitop3:0x36
	v_bitop3_b32 v13, v24, v10, 40 bitop3:0x78
	v_mad_u32_u24 v7, v80, s31, v73
	v_lshlrev_b32_e32 v60, 1, v12
	v_lshlrev_b32_e32 v61, 1, v13
	v_add_u32_e32 v12, v7, v60
	v_add_u32_e32 v13, v7, v61
	v_or_b32_e32 v12, v12, v1
	v_or_b32_e32 v13, v13, v1
	v_cvt_pk_bf16_f32 v35, v43, v42
	s_waitcnt lgkmcnt(2)
	v_mov_b32_e32 v42, v36
	ds_read_b64 v[48:49], v12
	ds_read_b64 v[50:51], v13
	v_sub_f32_e32 v12, v19, v2
	v_or_b32_e32 v13, 48, v80
	v_bitop3_b32 v36, v80, 56, 48 bitop3:0xc8
	v_mul_f32_e32 v12, 0x3fb8aa3b, v12
	v_bitop3_b32 v30, v31, v36, v30 bitop3:0x36
	v_bitop3_b32 v24, v24, v13, 56 bitop3:0x78
	v_exp_f32_e32 v62, v12
	v_mad_u32_u24 v12, v80, s31, v74
	v_lshlrev_b32_e32 v30, 1, v30
	v_lshlrev_b32_e32 v24, 1, v24
	v_add_u32_e32 v31, v12, v30
	v_add_u32_e32 v36, v12, v24
	v_mov_b32_e32 v43, v37
	v_or_b32_e32 v31, v31, v1
	v_or_b32_e32 v36, v36, v1
	v_mov_b32_e32 v37, v15
	v_mad_u32_u24 v15, v80, s31, v75
	v_add_f32_e32 v87, v16, v11
	v_sub_f32_e32 v11, v18, v2
	ds_read_b64 v[52:53], v31
	ds_read_b64 v[54:55], v36
	v_mov_b32_e32 v36, v14
	v_add_u32_e32 v14, v15, v56
	v_add_u32_e32 v31, v15, v57
	v_mul_f32_e32 v11, 0x3fb8aa3b, v11
	v_or_b32_e32 v14, v14, v1
	v_or_b32_e32 v31, v31, v1
	ds_read_b64 v[56:57], v14
	ds_read_b64 v[58:59], v31
	v_exp_f32_e32 v31, v11
	v_mad_u32_u24 v11, v80, s31, v76
	v_add_u32_e32 v14, v11, v60
	v_cmp_lt_f32_e32 vcc, s28, v19
	v_or_b32_e32 v14, v14, v1
	v_add_u32_e32 v19, v11, v61
	v_cndmask_b32_e32 v112, 0, v62, vcc
	v_or_b32_e32 v19, v19, v1
	ds_read_b64 v[60:61], v14
	ds_read_b64 v[62:63], v19
	v_mad_u32_u24 v14, v80, s31, v77
	v_add_u32_e32 v19, v14, v30
	v_or_b32_e32 v19, v19, v1
	v_add_u32_e32 v24, v14, v24
	v_or_b32_e32 v24, v24, v1
	ds_read_b64 v[80:81], v19
	ds_read_b64 v[82:83], v24
	v_cmp_lt_f32_e32 vcc, s28, v18
	v_mfma_f32_16x16x32_bf16 v[40:43], v[40:43], v[32:35], 0
	v_sub_f32_e32 v19, v20, v2
	v_cndmask_b32_e32 v24, 0, v31, vcc
	v_add_f32_e32 v18, v24, v87
	s_waitcnt lgkmcnt(10)
	v_mfma_f32_16x16x32_bf16 v[44:47], v[44:47], v[32:35], 0
	v_cmp_lt_f32_e32 vcc, s28, v21
	v_mul_f32_e32 v19, 0x3fb8aa3b, v19
	v_exp_f32_e32 v19, v19
	s_waitcnt lgkmcnt(8)
	v_mfma_f32_16x16x32_bf16 v[48:51], v[48:51], v[32:35], 0
	v_add_f32_e32 v18, v112, v18
	s_waitcnt lgkmcnt(6)
	v_mfma_f32_16x16x32_bf16 v[52:55], v[52:55], v[32:35], 0
	v_mfma_f32_16x16x32_bf16 v[36:39], v[36:39], v[32:35], 0
	s_waitcnt lgkmcnt(4)
	v_mfma_f32_16x16x32_bf16 v[56:59], v[56:59], v[32:35], 0
	s_waitcnt lgkmcnt(2)
	v_mfma_f32_16x16x32_bf16 v[60:63], v[60:63], v[32:35], 0
	s_waitcnt lgkmcnt(0)
	v_mfma_f32_16x16x32_bf16 v[30:33], v[80:83], v[32:35], 0
	v_add_u32_e32 v34, 32, v4
	v_cvt_pk_bf16_f32 v80, v84, v67
	v_bitop3_b32 v67, v34, v79, 8 bitop3:0x78
	v_lshl_add_u32 v67, v67, 1, v3
	v_add_u32_e32 v35, 48, v4
	v_or_b32_e32 v67, v67, v1
	v_cvt_pk_bf16_f32 v81, v86, v85
	ds_read2st64_b64 v[84:87], v67 offset1:66
	v_bitop3_b32 v67, v35, v79, 8 bitop3:0x78
	v_lshl_add_u32 v67, v67, 1, v3
	v_or_b32_e32 v67, v67, v1
	ds_read2st64_b64 v[88:91], v67 offset1:66
	v_bitop3_b32 v67, v34, v6, 24 bitop3:0x78
	v_cvt_pk_bf16_f32 v82, v93, v92
	s_waitcnt lgkmcnt(1)
	v_mov_b32_e32 v93, v85
	v_lshlrev_b32_e32 v67, 1, v67
	v_bitop3_b32 v85, v35, v6, 24 bitop3:0x78
	v_mov_b32_e32 v92, v84
	v_add_u32_e32 v84, v5, v67
	v_lshlrev_b32_e32 v85, 1, v85
	v_cvt_pk_bf16_f32 v83, v95, v94
	s_waitcnt lgkmcnt(0)
	v_mov_b32_e32 v94, v88
	v_or_b32_e32 v84, v84, v1
	v_add_u32_e32 v88, v5, v85
	v_or_b32_e32 v88, v88, v1
	ds_read_b64 v[96:97], v84
	ds_read_b64 v[98:99], v88
	v_bitop3_b32 v84, v34, v10, 40 bitop3:0x78
	v_lshlrev_b32_e32 v113, 1, v84
	v_bitop3_b32 v88, v35, v10, 40 bitop3:0x78
	v_add_u32_e32 v84, v7, v113
	v_lshlrev_b32_e32 v114, 1, v88
	v_mov_b32_e32 v95, v89
	v_or_b32_e32 v84, v84, v1
	v_add_u32_e32 v88, v7, v114
	v_or_b32_e32 v88, v88, v1
	ds_read_b64 v[100:101], v84
	ds_read_b64 v[102:103], v88
	v_sub_f32_e32 v84, v21, v2
	v_bitop3_b32 v21, v34, v13, 56 bitop3:0x78
	s_waitcnt lgkmcnt(2)
; __device__ void attn_item(const Params& p, int id) {
;     ...
; #pragma unroll
;   for (int s2 = 0; s2 < 5; ++s2) {
;     const int a0 = 2 * s2, a1 = (s2 < 4) ? 2 * s2 + 1 : 2 * s2;
;     u32x4 pw;
;     pw[0] = pack2(s[a0][0], s[a0][1]);
;     pw[1] = pack2(s[a0][2], s[a0][3]);
;     if (s2 < 4) { pw[2] = pack2(s[a1][0], s[a1][1]); pw[3] = pack2(s[a1][2], s[a1][3]); }
;     else { pw[2] = 0u; pw[3] = 0u; }
;     bf16x8 pf = __builtin_bit_cast(bf16x8, pw);
;     const int key0 = 16 * w + 16 * a0 + 4 * fq, key1 = 16 * w + 16 * a1 + 4 * fq;
; #pragma unroll
;     for (int ct = 0; ct < 8; ++ct) {
;       const int c = 16 * ct + fr;
;       const int sw = (c >> 3) & 7;
;       u32x2 lo = *(const u32x2*)(VT + c * 264 + ((((key0 >> 3) ^ sw) << 3) | (key0 & 7)));
;       u32x2 hi = *(const u32x2*)(VT + c * 264 + ((((key1 >> 3) ^ sw) << 3) | (key1 & 7)));
;       u32x4 vw = {lo[0], lo[1], hi[0], hi[1]};
;       o[ct] = __builtin_amdgcn_mfma_f32_16x16x32_bf16(__builtin_bit_cast(bf16x8, vw), pf, o[ct], 0, 0, 0);
;     }
	v_mfma_f32_16x16x32_bf16 v[44:47], v[96:99], v[80:83], v[44:47]
	v_lshlrev_b32_e32 v96, 1, v21
	v_bitop3_b32 v34, v35, v13, 56 bitop3:0x78
	v_mul_f32_e32 v84, 0x3fb8aa3b, v84
	v_add_u32_e32 v21, v12, v96
	v_lshlrev_b32_e32 v97, 1, v34
	v_exp_f32_e32 v84, v84
	v_or_b32_e32 v21, v21, v1
	v_add_u32_e32 v34, v12, v97
	v_mfma_f32_16x16x32_bf16 v[40:43], v[92:95], v[80:83], v[40:43]
	v_or_b32_e32 v34, v34, v1
	ds_read_b64 v[92:93], v21
	ds_read_b64 v[94:95], v34
	v_mov_b32_e32 v88, v86
	v_mov_b32_e32 v89, v87
	v_cndmask_b32_e32 v115, 0, v84, vcc
	v_add_u32_e32 v21, v15, v67
	v_add_u32_e32 v34, v15, v85
	v_cmp_lt_f32_e32 vcc, s28, v20
	v_or_b32_e32 v21, v21, v1
	v_or_b32_e32 v34, v34, v1
	v_cndmask_b32_e32 v67, 0, v19, vcc
	ds_read_b64 v[84:85], v21
	ds_read_b64 v[86:87], v34
	s_waitcnt lgkmcnt(2)
	v_mfma_f32_16x16x32_bf16 v[52:55], v[92:95], v[80:83], v[52:55]
	v_add_f32_e32 v92, v67, v18
	v_add_u32_e32 v34, v11, v113
	v_add_u32_e32 v35, v11, v114
	v_mfma_f32_16x16x32_bf16 v[18:21], v[88:91], v[80:83], v[36:39]
	v_or_b32_e32 v34, v34, v1
	v_cmp_lt_f32_e32 vcc, s28, v22
	s_nop 0
	v_add_u32_e32 v38, v14, v96
	v_or_b32_e32 v36, v35, v1
	v_or_b32_e32 v38, v38, v1
	v_add_u32_e32 v39, v14, v97
	ds_read_b64 v[34:35], v34
	ds_read_b64 v[36:37], v36
	v_or_b32_e32 v39, v39, v1
	ds_read_b64 v[88:89], v38
	ds_read_b64 v[90:91], v39
	v_sub_f32_e32 v38, v23, v2
	v_mfma_f32_16x16x32_bf16 v[48:51], v[100:103], v[80:83], v[48:51]
	v_mul_f32_e32 v101, 0x3fb8aa3b, v38
	v_sub_f32_e32 v38, v22, v2
	v_mul_f32_e32 v38, 0x3fb8aa3b, v38
	v_add_u32_e32 v103, 64, v4
	v_exp_f32_e32 v102, v38
	v_bitop3_b32 v38, v103, v79, 8 bitop3:0x78
	v_lshl_add_u32 v38, v38, 1, v3
	v_or_b32_e32 v38, v38, v1
	s_waitcnt lgkmcnt(4)
	v_mfma_f32_16x16x32_bf16 v[56:59], v[84:87], v[80:83], v[56:59]
	v_add_f32_e32 v100, v115, v92
	s_waitcnt lgkmcnt(2)
	v_mfma_f32_16x16x32_bf16 v[34:37], v[34:37], v[80:83], v[60:63]
	s_waitcnt lgkmcnt(0)
	v_mfma_f32_16x16x32_bf16 v[30:33], v[88:91], v[80:83], v[30:33]
	s_nop 0
	v_cvt_pk_bf16_f32 v60, v105, v104
	v_add_u32_e32 v104, 0x50, v4
	ds_read2st64_b64 v[80:83], v38 offset1:66
	v_bitop3_b32 v38, v104, v79, 8 bitop3:0x78
	v_lshl_add_u32 v38, v38, 1, v3
	v_or_b32_e32 v38, v38, v1
	ds_read2st64_b64 v[84:87], v38 offset1:66
	v_bitop3_b32 v38, v103, v6, 24 bitop3:0x78
	s_waitcnt lgkmcnt(1)
	v_mov_b32_e32 v88, v80
	v_lshlrev_b32_e32 v80, 1, v38
	v_bitop3_b32 v39, v104, v6, 24 bitop3:0x78
	v_mov_b32_e32 v89, v81
	v_add_u32_e32 v38, v5, v80
	v_lshlrev_b32_e32 v81, 1, v39
	v_or_b32_e32 v38, v38, v1
	v_add_u32_e32 v39, v5, v81
	v_or_b32_e32 v39, v39, v1
	ds_read_b64 v[92:93], v38
	ds_read_b64 v[94:95], v39
	v_bitop3_b32 v38, v103, v10, 40 bitop3:0x78
	v_lshlrev_b32_e32 v105, 1, v38
	v_bitop3_b32 v39, v104, v10, 40 bitop3:0x78
	v_cvt_pk_bf16_f32 v61, v107, v106
	v_add_u32_e32 v38, v7, v105
	v_lshlrev_b32_e32 v106, 1, v39
	v_or_b32_e32 v38, v38, v1
	v_add_u32_e32 v39, v7, v106
	s_waitcnt lgkmcnt(2)
	v_mov_b32_e32 v90, v84
	v_mov_b32_e32 v91, v85
	v_or_b32_e32 v39, v39, v1
	ds_read_b64 v[96:97], v38
	ds_read_b64 v[98:99], v39
	v_cvt_pk_bf16_f32 v62, v109, v108
	v_cvt_pk_bf16_f32 v63, v111, v110
	v_exp_f32_e32 v84, v101
	v_cndmask_b32_e32 v101, 0, v102, vcc
	v_cmp_lt_f32_e32 vcc, s28, v23
	v_bitop3_b32 v23, v103, v13, 56 bitop3:0x78
	v_mfma_f32_16x16x32_bf16 v[38:41], v[88:91], v[60:63], v[40:43]
	v_lshlrev_b32_e32 v23, 1, v23
	v_cndmask_b32_e32 v22, 0, v84, vcc
	v_mov_b32_e32 v84, v82
	s_waitcnt lgkmcnt(2)
	v_mfma_f32_16x16x32_bf16 v[42:45], v[92:95], v[60:63], v[44:47]
	v_mov_b32_e32 v85, v83
	v_add_f32_e32 v100, v22, v100
	v_sub_f32_e32 v93, v26, v2
	s_waitcnt lgkmcnt(0)
	v_mfma_f32_16x16x32_bf16 v[46:49], v[96:99], v[60:63], v[48:51]
	v_add_u32_e32 v97, 0x70, v4
	v_mul_f32_e32 v98, 0x3fb8aa3b, v93
	v_cmp_lt_f32_e32 vcc, s28, v26
	v_bitop3_b32 v51, v104, v13, 56 bitop3:0x78
	v_add_u32_e32 v50, v12, v23
	v_lshlrev_b32_e32 v92, 1, v51
	v_or_b32_e32 v50, v50, v1
	v_add_u32_e32 v51, v12, v92
	v_or_b32_e32 v51, v51, v1
	ds_read_b64 v[88:89], v50
	ds_read_b64 v[90:91], v51
	v_add_u32_e32 v50, v15, v80
	v_or_b32_e32 v50, v50, v1
	v_add_u32_e32 v51, v15, v81
	v_or_b32_e32 v51, v51, v1
	ds_read_b64 v[80:81], v50
	ds_read_b64 v[82:83], v51
	s_waitcnt lgkmcnt(2)
	v_mfma_f32_16x16x32_bf16 v[50:53], v[88:91], v[60:63], v[52:55]
	v_add_u32_e32 v23, v14, v23
	v_or_b32_e32 v23, v23, v1
	s_nop 0
	v_sub_f32_e32 v54, v27, v2
	v_mul_f32_e32 v54, 0x3fb8aa3b, v54
	v_exp_f32_e32 v96, v54
	v_add_u32_e32 v54, v11, v105
	v_add_u32_e32 v55, v11, v106
	v_or_b32_e32 v54, v54, v1
	v_or_b32_e32 v55, v55, v1
	v_mfma_f32_16x16x32_bf16 v[18:21], v[84:87], v[60:63], v[18:21]
	ds_read_b64 v[84:85], v54
	ds_read_b64 v[86:87], v55
	s_waitcnt lgkmcnt(2)
	v_mfma_f32_16x16x32_bf16 v[54:57], v[80:83], v[60:63], v[56:59]
	s_nop 2
	v_add_u32_e32 v58, v14, v92
	v_or_b32_e32 v58, v58, v1
	ds_read_b64 v[80:81], v23
	ds_read_b64 v[82:83], v58
	v_add_u32_e32 v23, 0x60, v4
	v_bitop3_b32 v58, v23, v79, 8 bitop3:0x78
	v_lshl_add_u32 v58, v58, 1, v3
	v_or_b32_e32 v58, v58, v1
	s_waitcnt lgkmcnt(2)
	v_mfma_f32_16x16x32_bf16 v[34:37], v[84:87], v[60:63], v[34:37]
	ds_read2st64_b64 v[84:87], v58 offset1:66
	v_bitop3_b32 v58, v97, v79, 8 bitop3:0x78
	v_lshl_add_u32 v58, v58, 1, v3
	v_or_b32_e32 v58, v58, v1
	ds_read2st64_b64 v[88:91], v58 offset1:66
	s_waitcnt lgkmcnt(2)
	v_mfma_f32_16x16x32_bf16 v[30:33], v[80:83], v[60:63], v[30:33]
	s_waitcnt lgkmcnt(1)
	v_mov_b32_e32 v58, v84
	v_mov_b32_e32 v59, v85
	v_cvt_pk_bf16_f32 v80, v17, v16
	s_waitcnt lgkmcnt(0)
; __device__ void attn_item(const Params& p, int id) {
;     ...
;   l += __shfl_xor(l, 16);
;   l += __shfl_xor(l, 32);
;     ...
; #pragma unroll
;   for (int s2 = 0; s2 < 5; ++s2) {
;     const int a0 = 2 * s2, a1 = (s2 < 4) ? 2 * s2 + 1 : 2 * s2;
;     u32x4 pw;
;     pw[0] = pack2(s[a0][0], s[a0][1]);
;     pw[1] = pack2(s[a0][2], s[a0][3]);
;     if (s2 < 4) { pw[2] = pack2(s[a1][0], s[a1][1]); pw[3] = pack2(s[a1][2], s[a1][3]); }
;     else { pw[2] = 0u; pw[3] = 0u; }
;     bf16x8 pf = __builtin_bit_cast(bf16x8, pw);
;     const int key0 = 16 * w + 16 * a0 + 4 * fq, key1 = 16 * w + 16 * a1 + 4 * fq;
; #pragma unroll
;     for (int ct = 0; ct < 8; ++ct) {
;       const int c = 16 * ct + fr;
;       const int sw = (c >> 3) & 7;
;       u32x2 lo = *(const u32x2*)(VT + c * 264 + ((((key0 >> 3) ^ sw) << 3) | (key0 & 7)));
;       u32x2 hi = *(const u32x2*)(VT + c * 264 + ((((key1 >> 3) ^ sw) << 3) | (key1 & 7)));
;       u32x4 vw = {lo[0], lo[1], hi[0], hi[1]};
;       o[ct] = __builtin_amdgcn_mfma_f32_16x16x32_bf16(__builtin_bit_cast(bf16x8, vw), pf, o[ct], 0, 0, 0);
;     }
;   }
	v_mov_b32_e32 v60, v88
	v_mov_b32_e32 v61, v89
	v_bitop3_b32 v16, v23, v6, 24 bitop3:0x78
	v_cvt_pk_bf16_f32 v83, v22, v101
	v_lshlrev_b32_e32 v16, 1, v16
	v_bitop3_b32 v22, v97, v6, 24 bitop3:0x78
	v_add_u32_e32 v17, v5, v16
	v_lshlrev_b32_e32 v22, 1, v22
	v_cvt_pk_bf16_f32 v81, v24, v112
	v_cvt_pk_bf16_f32 v82, v67, v115
	v_or_b32_e32 v17, v17, v1
	v_add_u32_e32 v24, v5, v22
	v_mfma_f32_16x16x32_bf16 v[38:41], v[58:61], v[80:83], v[38:41]
	v_or_b32_e32 v24, v24, v1
	ds_read_b64 v[58:59], v17
	ds_read_b64 v[60:61], v24
	v_bitop3_b32 v17, v23, v10, 40 bitop3:0x78
	v_lshlrev_b32_e32 v24, 1, v17
	v_bitop3_b32 v62, v97, v10, 40 bitop3:0x78
	v_add_u32_e32 v17, v7, v24
	v_lshlrev_b32_e32 v62, 1, v62
	v_or_b32_e32 v17, v17, v1
	v_add_u32_e32 v63, v7, v62
	v_or_b32_e32 v63, v63, v1
	ds_read_b64 v[92:93], v17
	ds_read_b64 v[94:95], v63
	v_bitop3_b32 v17, v23, v13, 56 bitop3:0x78
	v_lshlrev_b32_e32 v63, 1, v17
	v_bitop3_b32 v23, v97, v13, 56 bitop3:0x78
	v_add_u32_e32 v17, v12, v63
	v_lshlrev_b32_e32 v67, 1, v23
	v_add_u32_e32 v16, v15, v16
	v_or_b32_e32 v17, v17, v1
	v_add_u32_e32 v23, v12, v67
	v_or_b32_e32 v16, v16, v1
	v_add_u32_e32 v22, v15, v22
	v_mov_b32_e32 v88, v86
	v_mov_b32_e32 v89, v87
	s_waitcnt lgkmcnt(2)
	v_mfma_f32_16x16x32_bf16 v[42:45], v[58:61], v[80:83], v[42:45]
	v_or_b32_e32 v23, v23, v1
	ds_read_b64 v[58:59], v17
	ds_read_b64 v[60:61], v23
	v_exp_f32_e32 v17, v98
	s_waitcnt lgkmcnt(2)
	v_mfma_f32_16x16x32_bf16 v[46:49], v[92:95], v[80:83], v[46:49]
	v_or_b32_e32 v22, v22, v1
	ds_read_b64 v[92:93], v16
	ds_read_b64 v[94:95], v22
	v_cndmask_b32_e32 v26, 0, v17, vcc
	v_mfma_f32_16x16x32_bf16 v[16:19], v[88:91], v[80:83], v[18:21]
	v_add_u32_e32 v24, v11, v24
	v_or_b32_e32 v24, v24, v1
	v_cmp_lt_f32_e32 vcc, s28, v27
	v_sub_f32_e32 v20, v9, v2
	v_mul_f32_e32 v84, 0x3fb8aa3b, v20
	s_waitcnt lgkmcnt(0)
	v_mfma_f32_16x16x32_bf16 v[20:23], v[92:95], v[80:83], v[54:57]
	v_cndmask_b32_e32 v27, 0, v96, vcc
	v_sub_f32_e32 v85, v8, v2
	v_cmp_lt_f32_e32 vcc, s28, v8
	v_add_u32_e32 v54, v11, v62
	v_or_b32_e32 v56, v54, v1
	ds_read_b64 v[54:55], v24
	ds_read_b64 v[56:57], v56
	v_add_u32_e32 v8, 0x80, v4
	v_bitop3_b32 v4, v8, v79, 8 bitop3:0x78
	v_mfma_f32_16x16x32_bf16 v[50:53], v[58:61], v[80:83], v[50:53]
	v_add_u32_e32 v24, v14, v63
	v_add_u32_e32 v58, v14, v67
	v_lshl_add_u32 v3, v4, 1, v3
	v_or_b32_e32 v24, v24, v1
	v_or_b32_e32 v60, v58, v1
	v_or_b32_e32 v3, v3, v1
	ds_read_b64 v[58:59], v24
	ds_read_b64 v[60:61], v60
	v_mul_f32_e32 v24, 0x3fb8aa3b, v85
	s_waitcnt lgkmcnt(2)
	v_mfma_f32_16x16x32_bf16 v[34:37], v[54:57], v[80:83], v[34:37]
	ds_read2st64_b64 v[54:57], v3 offset1:66
	v_bitop3_b32 v3, v8, v6, 24 bitop3:0x78
	v_bitop3_b32 v6, v8, v10, 40 bitop3:0x78
	v_exp_f32_e32 v24, v24
	v_lshlrev_b32_e32 v63, 1, v6
	v_lshlrev_b32_e32 v3, 1, v3
	v_add_u32_e32 v6, v7, v63
	v_bitop3_b32 v7, v8, v13, 56 bitop3:0x78
	v_exp_f32_e32 v62, v84
	v_add_u32_e32 v4, v5, v3
	v_lshlrev_b32_e32 v67, 1, v7
	v_add_u32_e32 v3, v15, v3
	v_or_b32_e32 v4, v4, v1
	v_or_b32_e32 v6, v6, v1
	v_add_u32_e32 v7, v12, v67
	v_or_b32_e32 v3, v3, v1
	v_cndmask_b32_e32 v24, 0, v24, vcc
	v_cmp_lt_f32_e32 vcc, s28, v9
	ds_read_b64 v[4:5], v4
	v_or_b32_e32 v7, v7, v1
	ds_read_b64 v[84:85], v6
	ds_read_b64 v[88:89], v7
	ds_read_b64 v[8:9], v3
	v_add_f32_e32 v3, v101, v100
	v_add_f32_e32 v3, v27, v3
	v_cndmask_b32_e32 v62, 0, v62, vcc
	v_add_f32_e32 v3, v26, v3
	v_add_f32_e32 v3, v62, v3
	v_add_f32_e32 v3, v24, v3
	s_waitcnt lgkmcnt(5)
	v_mfma_f32_16x16x32_bf16 v[30:33], v[58:61], v[80:83], v[30:33]
	v_cvt_pk_bf16_f32 v58, v27, v26
	ds_bpermute_b32 v26, v25, v3
	v_add_u32_e32 v11, v11, v63
	v_add_u32_e32 v14, v14, v67
	v_or_b32_e32 v11, v11, v1
	v_or_b32_e32 v1, v14, v1
	v_cvt_pk_bf16_f32 v59, v62, v24
	ds_read_b64 v[12:13], v11
	ds_read_b64 v[24:25], v1
	s_waitcnt lgkmcnt(2)
	v_add_f32_e32 v1, v3, v26
	ds_bpermute_b32 v0, v0, v1
	v_mov_b32_e32 v10, v8
	v_mov_b32_e32 v11, v9
	s_waitcnt lgkmcnt(1)
; __device__ void attn_item(const Params& p, int id) {
;     ...
;   const float inv = 1.f / l;
;   u16* og = p.OG + ((size_t)g * NTOK + tokq) * 1024 + h * 128;
; #pragma unroll
;   for (int ct = 0; ct < 8; ++ct) {
;     u32x2 ov;
;     ov[0] = pack2(o[ct][0] * inv, o[ct][1] * inv);
;     ov[1] = pack2(o[ct][2] * inv, o[ct][3] * inv);
;     *(u32x2*)(og + 16 * ct + 4 * fq) = ov;
;   }
;   if (fq == 0) p.LSE[((size_t)g * NTOK + tokq) * 8 + h] = mx + __logf(l);
	v_mov_b32_e32 v26, v24
	v_mov_b32_e32 v27, v25
	s_waitcnt lgkmcnt(0)
	v_add_f32_e32 v3, v1, v0
	v_mov_b32_e32 v60, v65
	v_mov_b32_e32 v61, v65
	v_mov_b32_e32 v6, v4
	v_mov_b32_e32 v7, v5
	v_mfma_f32_16x16x32_bf16 v[8:11], v[8:11], v[58:61], v[20:23]
	v_mov_b32_e32 v86, v84
	v_mov_b32_e32 v87, v85
	v_mov_b32_e32 v90, v88
	v_mfma_f32_16x16x32_bf16 v[20:23], v[24:27], v[58:61], v[30:33]
	v_mov_b32_e32 v91, v89
	v_mfma_f32_16x16x32_bf16 v[4:7], v[4:7], v[58:61], v[42:45]
	s_lshl_b64 s[0:1], s[8:9], 14
	v_mov_b32_e32 v80, v54
	v_mov_b32_e32 v81, v55
	v_mov_b32_e32 v82, v54
	v_mov_b32_e32 v83, v55
	v_mov_b32_e32 v54, v56
	v_mov_b32_e32 v55, v57
	v_rcp_f32_e32 v24, v3
	s_nop 0
	v_lshl_add_u64 v[0:1], s[0:1], 0, v[28:29]
	v_mfma_f32_16x16x32_bf16 v[42:45], v[84:87], v[58:61], v[46:49]
	v_lshlrev_b64 v[26:27], 11, v[0:1]
	v_lshl_add_u64 v[26:27], s[80:81], 0, v[26:27]
	s_lshl_b32 s8, s56, 1
	v_mfma_f32_16x16x32_bf16 v[46:49], v[88:91], v[58:61], v[50:53]
	v_lshl_add_u64 v[26:27], v[26:27], 0, s[8:9]
	v_pk_mul_f32 v[4:5], v[24:25], v[4:5] op_sel_hi:[0,1]
	v_pk_mul_f32 v[6:7], v[24:25], v[6:7] op_sel_hi:[0,1]
	v_mov_b32_e32 v14, v12
	v_mov_b32_e32 v15, v13
	v_lshl_add_u64 v[26:27], v[26:27], 0, v[64:65]
	v_cvt_pk_bf16_f32 v4, v4, v5
	v_cvt_pk_bf16_f32 v5, v6, v7
	v_mfma_f32_16x16x32_bf16 v[16:19], v[54:57], v[58:61], v[16:19]
	global_store_dwordx2 v[26:27], v[4:5], off offset:32
	v_pk_mul_f32 v[4:5], v[24:25], v[42:43] op_sel_hi:[0,1]
	v_pk_mul_f32 v[6:7], v[24:25], v[44:45] op_sel_hi:[0,1]
	v_cvt_pk_bf16_f32 v4, v4, v5
	v_cvt_pk_bf16_f32 v5, v6, v7
	global_store_dwordx2 v[26:27], v[4:5], off offset:64
	v_pk_mul_f32 v[4:5], v[24:25], v[46:47] op_sel_hi:[0,1]
	v_pk_mul_f32 v[6:7], v[24:25], v[48:49] op_sel_hi:[0,1]
	v_cvt_pk_bf16_f32 v4, v4, v5
	v_cvt_pk_bf16_f32 v5, v6, v7
	v_mfma_f32_16x16x32_bf16 v[12:15], v[12:15], v[58:61], v[34:37]
	global_store_dwordx2 v[26:27], v[4:5], off offset:96
	v_pk_mul_f32 v[4:5], v[24:25], v[16:17] op_sel_hi:[0,1]
	v_pk_mul_f32 v[6:7], v[24:25], v[18:19] op_sel_hi:[0,1]
	v_cvt_pk_bf16_f32 v4, v4, v5
	v_cvt_pk_bf16_f32 v5, v6, v7
	v_mfma_f32_16x16x32_bf16 v[38:41], v[80:83], v[58:61], v[38:41]
	global_store_dwordx2 v[26:27], v[4:5], off offset:128
	v_pk_mul_f32 v[4:5], v[24:25], v[8:9] op_sel_hi:[0,1]
	v_pk_mul_f32 v[6:7], v[24:25], v[10:11] op_sel_hi:[0,1]
	v_cvt_pk_bf16_f32 v4, v4, v5
	v_cvt_pk_bf16_f32 v5, v6, v7
	global_store_dwordx2 v[26:27], v[4:5], off offset:160
	v_pk_mul_f32 v[4:5], v[24:25], v[12:13] op_sel_hi:[0,1]
	v_pk_mul_f32 v[6:7], v[24:25], v[14:15] op_sel_hi:[0,1]
	v_cvt_pk_bf16_f32 v4, v4, v5
	v_cvt_pk_bf16_f32 v5, v6, v7
	v_pk_mul_f32 v[28:29], v[24:25], v[38:39] op_sel_hi:[0,1]
	v_pk_mul_f32 v[30:31], v[24:25], v[40:41] op_sel_hi:[0,1]
	global_store_dwordx2 v[26:27], v[4:5], off offset:192
	v_pk_mul_f32 v[4:5], v[24:25], v[20:21] op_sel_hi:[0,1]
	v_pk_mul_f32 v[6:7], v[24:25], v[22:23] op_sel_hi:[0,1]
	v_cvt_pk_bf16_f32 v28, v28, v29
	v_cvt_pk_bf16_f32 v29, v30, v31
	v_cvt_pk_bf16_f32 v4, v4, v5
	v_cvt_pk_bf16_f32 v5, v6, v7
	v_cmp_eq_u32_e32 vcc, 0, v66
	global_store_dwordx2 v[26:27], v[28:29], off
	global_store_dwordx2 v[26:27], v[4:5], off offset:224
	s_and_saveexec_b64 s[4:5], vcc
	s_cbranch_execz .LBB0_449
	v_cmp_gt_f32_e32 vcc, s34, v3
	v_lshlrev_b64 v[0:1], 5, v[0:1]
	v_lshl_add_u64 v[0:1], s[42:43], 0, v[0:1]
	v_cndmask_b32_e64 v4, 0, 32, vcc
	v_ldexp_f32 v3, v3, v4
	v_log_f32_e32 v3, v3
	s_lshl_b32 s8, s47, 2
	v_lshl_add_u64 v[0:1], v[0:1], 0, s[8:9]
	v_mul_f32_e32 v4, 0x3f317217, v3
	v_fma_f32 v4, v3, s35, -v4
	v_fmac_f32_e32 v4, 0x3377d1cf, v3
	v_fmac_f32_e32 v4, 0x3f317217, v3
	v_cmp_lt_f32_e64 s[0:1], |v3|, s46
	s_nop 1
	v_cndmask_b32_e64 v3, v3, v4, s[0:1]
	v_cndmask_b32_e32 v4, 0, v78, vcc
	v_sub_f32_e32 v3, v3, v4
	v_add_f32_e32 v2, v2, v3
	global_store_dword v[0:1], v2, off
	s_branch .LBB0_449

; __device__ __forceinline__ float bflo(u32 v) { return __uint_as_float(v << 16); }
; __device__ __forceinline__ float bfhi(u32 v) { return __uint_as_float(v & 0xffff0000u); }
; __device__ __forceinline__ float sigmoidf_(float x) { return 1.f / (1.f + __expf(-x)); }
; __device__ void phase2c(const Params& p) {
;     ...
;       const int hh = lane >> 3;
;       float l0 = p.LSE[((size_t)0 * NTOK + tok) * 8 + hh];
;       float l1 = p.LSE[((size_t)1 * NTOK + tok) * 8 + hh];
;       float l2 = p.LSE[((size_t)2 * NTOK + tok) * 8 + hh];
;       float mx = fmaxf(l0, fmaxf(l1, l2));
;       float w0 = __expf(l0 - mx), w1 = __expf(l1 - mx), w2 = __expf(l2 - mx);
;       float inv = 1.f / (w0 + w1 + w2);
;       w0 *= inv; w1 *= inv; w2 *= inv;
; #pragma unroll
;       for (int hf = 0; hf < 2; ++hf) {
;         const int col = 16 * lane + 8 * hf;
;         u32x4 o0 = *(const u32x4*)(p.OG + ((size_t)0 * NTOK + tok) * 1024 + col);
;         u32x4 o1 = *(const u32x4*)(p.OG + ((size_t)1 * NTOK + tok) * 1024 + col);
;         u32x4 o2 = *(const u32x4*)(p.OG + ((size_t)2 * NTOK + tok) * 1024 + col);
;         u32x4 zz = *(const u32x4*)(p.PROJ + (size_t)tok * NP + C_AZ + col);
;         u32x4 res;
; #pragma unroll
;         for (int i = 0; i < 4; ++i) {
;           float za = bflo(zz[i]), zb = bfhi(zz[i]);
;           float va = (w0 * bflo(o0[i]) + w1 * bflo(o1[i]) + w2 * bflo(o2[i])) * za * sigmoidf_(za);
;           float vb = (w0 * bfhi(o0[i]) + w1 * bfhi(o1[i]) + w2 * bfhi(o2[i])) * zb * sigmoidf_(zb);
;           res[i] = pack2(va, vb);
;         }
;         *(u32x4*)(p.YA + (size_t)tok * 1024 + col) = res;
;       }
.LBB0_513:
	v_ashrrev_i32_e32 v25, 31, v24
	v_lshl_add_u64 v[2:3], v[24:25], 0, s[12:13]
	v_lshlrev_b64 v[4:5], 5, v[2:3]
	v_lshl_add_u64 v[10:11], v[24:25], 0, s[14:15]
	v_lshl_add_u64 v[8:9], v[28:29], 0, v[4:5]
	v_lshlrev_b64 v[4:5], 5, v[10:11]
	v_lshlrev_b64 v[20:21], 11, v[24:25]
	v_lshlrev_b64 v[0:1], 5, v[24:25]
	v_lshl_add_u64 v[12:13], v[28:29], 0, v[4:5]
	v_lshl_add_u64 v[18:19], v[38:39], 0, v[20:21]
	v_lshl_add_u64 v[0:1], v[28:29], 0, v[0:1]
	global_load_dwordx4 v[4:7], v[18:19], off
	global_load_dword v57, v[0:1], off
	global_load_dword v60, v[8:9], off
	global_load_dword v61, v[12:13], off
	v_lshlrev_b64 v[12:13], 15, v[24:25]
	v_lshlrev_b64 v[0:1], 11, v[2:3]
	v_lshlrev_b64 v[2:3], 11, v[10:11]
	v_lshl_add_u64 v[16:17], s[74:75], 0, v[12:13]
	v_lshl_add_u64 v[22:23], v[38:39], 0, v[0:1]
	v_lshl_add_u64 v[46:47], v[38:39], 0, v[2:3]
	v_lshl_add_u64 v[48:49], v[16:17], 0, s[16:17]
	global_load_dwordx4 v[8:11], v[22:23], off
	global_load_dwordx4 v[0:3], v[46:47], off
	v_lshl_add_u64 v[12:13], v[48:49], 0, v[42:43]
	global_load_dwordx4 v[12:15], v[12:13], off
	s_waitcnt vmcnt(6)
	v_and_b32_e32 v51, 0xffff0000, v4
	v_lshlrev_b32_e32 v52, 16, v4
	v_and_b32_e32 v55, 0xffff0000, v5
	s_waitcnt vmcnt(3)
	v_max3_f32 v4, v57, v60, v61
	v_lshlrev_b32_e32 v56, 16, v5
	v_sub_f32_e32 v5, v60, v4
	s_waitcnt vmcnt(2)
	v_lshlrev_b32_e32 v50, 16, v8
	s_waitcnt vmcnt(1)
	v_lshlrev_b32_e32 v58, 16, v0
	v_and_b32_e32 v59, 0xffff0000, v0
	v_sub_f32_e32 v0, v57, v4
	v_and_b32_e32 v53, 0xffff0000, v8
	v_sub_f32_e32 v4, v61, v4
	s_waitcnt vmcnt(0)
	v_lshlrev_b32_e32 v60, 16, v12
	v_and_b32_e32 v61, 0xffff0000, v12
	v_mul_f32_e32 v0, 0x3fb8aa3b, v0
	v_mul_f32_e32 v8, 0x3fb8aa3b, v5
	v_mul_f32_e32 v57, 0x3fb8aa3b, v4
	v_mul_f32_e32 v62, 0xbfb8aa3b, v60
	v_mul_f32_e32 v63, 0xbfb8aa3b, v61
	v_exp_f32_e32 v5, v0
	v_exp_f32_e32 v4, v8
	v_exp_f32_e32 v62, v62
	v_exp_f32_e32 v63, v63
	v_exp_f32_e32 v0, v57
	v_add_f32_e32 v8, v5, v4
	v_lshlrev_b32_e32 v12, 16, v13
	v_pk_add_f32 v[62:63], v[62:63], 1.0 op_sel_hi:[1,0]
	v_add_f32_e32 v8, v0, v8
	v_and_b32_e32 v13, 0xffff0000, v13
	v_mul_f32_e32 v64, 0xbfb8aa3b, v12
	v_mul_f32_e32 v65, 0xbfb8aa3b, v13
	v_exp_f32_e32 v64, v64
	v_exp_f32_e32 v65, v65
	v_rcp_f32_e32 v8, v8
	s_nop 0
	v_pk_add_f32 v[64:65], v[64:65], 1.0 op_sel_hi:[1,0]
	v_pk_mul_f32 v[4:5], v[4:5], v[8:9] op_sel_hi:[1,0]
	s_mov_b64 vcc, s[0:1]
	v_pk_mul_f32 v[52:53], v[4:5], v[52:53] op_sel:[1,0] op_sel_hi:[0,1]
	v_mul_f32_e32 v0, v0, v8
	s_mov_b64 vcc, s[4:5]
	v_pk_fma_f32 v[50:51], v[4:5], v[50:51], v[52:53]
	v_pk_fma_f32 v[50:51], v[0:1], v[58:59], v[50:51] op_sel_hi:[0,1,1]
	v_rcp_f32_e32 v63, v63
	s_nop 0
	v_rcp_f32_e32 v62, v62
	s_nop 0
	v_pk_mul_f32 v[50:51], v[50:51], v[60:61]
	v_lshlrev_b32_e32 v54, 16, v9
	v_pk_mul_f32 v[50:51], v[62:63], v[50:51]
	v_and_b32_e32 v57, 0xffff0000, v9
	v_cvt_pk_bf16_f32 v8, v50, v51
	v_lshlrev_b32_e32 v50, 16, v1
	v_and_b32_e32 v51, 0xffff0000, v1
	v_rcp_f32_e32 v53, v65
	s_nop 0
	v_pk_mul_f32 v[56:57], v[4:5], v[56:57] op_sel:[1,0] op_sel_hi:[0,1]
	s_nop 0
	v_pk_fma_f32 v[54:55], v[4:5], v[54:55], v[56:57]
	v_rcp_f32_e32 v52, v64
	s_nop 0
	v_pk_fma_f32 v[50:51], v[0:1], v[50:51], v[54:55] op_sel_hi:[0,1,1]
	v_pk_mul_f32 v[12:13], v[50:51], v[12:13]
	v_lshlrev_b32_e32 v54, 16, v6
	v_pk_mul_f32 v[12:13], v[52:53], v[12:13]
	v_and_b32_e32 v53, 0xffff0000, v6
	v_cvt_pk_bf16_f32 v9, v12, v13
	v_lshlrev_b32_e32 v12, 16, v14
	v_and_b32_e32 v13, 0xffff0000, v14
	v_mul_f32_e32 v1, 0xbfb8aa3b, v12
	v_exp_f32_e32 v50, v1
	v_mul_f32_e32 v1, 0xbfb8aa3b, v13
	v_exp_f32_e32 v51, v1
	v_lshlrev_b32_e32 v56, 16, v2
	v_and_b32_e32 v57, 0xffff0000, v2
	v_lshlrev_b32_e32 v52, 16, v10
	v_pk_add_f32 v[50:51], v[50:51], 1.0 op_sel_hi:[1,0]
	v_and_b32_e32 v55, 0xffff0000, v10
	v_pk_mul_f32 v[54:55], v[4:5], v[54:55] op_sel:[1,0] op_sel_hi:[0,1]
	v_pk_fma_f32 v[52:53], v[4:5], v[52:53], v[54:55]
	v_rcp_f32_e32 v51, v51
	s_nop 0
	v_pk_fma_f32 v[52:53], v[0:1], v[56:57], v[52:53] op_sel_hi:[0,1,1]
	v_rcp_f32_e32 v50, v50
	s_nop 0
	v_pk_mul_f32 v[12:13], v[52:53], v[12:13]
	v_lshlrev_b32_e32 v14, 16, v11
	v_pk_mul_f32 v[12:13], v[50:51], v[12:13]
	v_lshlrev_b32_e32 v50, 16, v7
	v_cvt_pk_bf16_f32 v10, v12, v13
	v_lshlrev_b32_e32 v12, 16, v15
	v_and_b32_e32 v13, 0xffff0000, v15
	v_mul_f32_e32 v1, 0xbfb8aa3b, v12
	v_exp_f32_e32 v6, v1
	v_mul_f32_e32 v1, 0xbfb8aa3b, v13
	v_and_b32_e32 v15, 0xffff0000, v7
	v_exp_f32_e32 v7, v1
	v_and_b32_e32 v51, 0xffff0000, v11
	v_pk_mul_f32 v[50:51], v[4:5], v[50:51] op_sel:[1,0] op_sel_hi:[0,1]
	v_pk_fma_f32 v[14:15], v[4:5], v[14:15], v[50:51]
	v_pk_add_f32 v[6:7], v[6:7], 1.0 op_sel_hi:[1,0]
	v_lshlrev_b32_e32 v2, 16, v3
	v_and_b32_e32 v3, 0xffff0000, v3
	v_pk_fma_f32 v[2:3], v[0:1], v[2:3], v[14:15] op_sel_hi:[0,1,1]
	v_pk_mul_f32 v[2:3], v[2:3], v[12:13]
	v_rcp_f32_e32 v7, v7
	s_nop 0
	v_lshlrev_b64 v[56:57], 12, v[24:25]
	v_rcp_f32_e32 v6, v6
	s_nop 0
	v_pk_mul_f32 v[2:3], v[6:7], v[2:3]
	v_lshl_add_u64 v[6:7], v[48:49], 0, v[44:45]
	v_cvt_pk_bf16_f32 v11, v2, v3
	v_lshl_add_u64 v[2:3], v[40:41], 0, v[20:21]
	global_store_dwordx4 v[2:3], v[8:11], off
	global_load_dwordx4 v[6:9], v[6:7], off
	s_nop 0
	global_load_dwordx4 v[10:13], v[22:23], off offset:16
	s_nop 0
	global_load_dwordx4 v[18:21], v[18:19], off offset:16
	s_nop 0
	global_load_dwordx4 v[46:49], v[46:47], off offset:16
	v_add_u32_e32 v24, s2, v24
	s_waitcnt vmcnt(3)
	v_lshlrev_b32_e32 v14, 16, v6
	v_and_b32_e32 v15, 0xffff0000, v6
	v_mul_f32_e32 v1, 0xbfb8aa3b, v14
	v_exp_f32_e32 v22, v1
	v_mul_f32_e32 v1, 0xbfb8aa3b, v15
	v_exp_f32_e32 v23, v1
	s_waitcnt vmcnt(2)
	v_lshlrev_b32_e32 v50, 16, v10
	v_and_b32_e32 v53, 0xffff0000, v10
	s_waitcnt vmcnt(1)
; __device__ __forceinline__ float bflo(u32 v) { return __uint_as_float(v << 16); }
; __device__ __forceinline__ float bfhi(u32 v) { return __uint_as_float(v & 0xffff0000u); }
; __device__ void phase2c(const Params& p) {
;     ...
; #pragma unroll
;         for (int i = 0; i < 4; ++i) {
;           float za = bflo(zz[i]), zb = bfhi(zz[i]);
;           float va = (w0 * bflo(o0[i]) + w1 * bflo(o1[i]) + w2 * bflo(o2[i])) * za * sigmoidf_(za);
;           float vb = (w0 * bfhi(o0[i]) + w1 * bfhi(o1[i]) + w2 * bfhi(o2[i])) * zb * sigmoidf_(zb);
;           res[i] = pack2(va, vb);
;         }
;         *(u32x4*)(p.YA + (size_t)tok * 1024 + col) = res;
;       }
;     }
;     {
;       const int col0 = 32 * lane;
;       f32x4 v[8];
;       float ss = 0.f;
; #pragma unroll
;       for (int i = 0; i < 4; ++i) {
;         u32x4 a = *(const u32x4*)(p.OF + (size_t)tok * 2048 + col0 + 8 * i);
;         u32x4 b = *(const u32x4*)(p.OB + (size_t)tok * 2048 + col0 + 8 * i);
;         v[2 * i] = f32x4{bflo(a[0]) + bflo(b[0]), bfhi(a[0]) + bfhi(b[0]), bflo(a[1]) + bflo(b[1]), bfhi(a[1]) + bfhi(b[1])};
;         v[2 * i + 1] = f32x4{bflo(a[2]) + bflo(b[2]), bfhi(a[2]) + bfhi(b[2]), bflo(a[3]) + bflo(b[3]), bfhi(a[3]) + bfhi(b[3])};
;       }
; #pragma unroll
;       for (int i = 0; i < 8; ++i) ss += v[i][0] * v[i][0] + v[i][1] * v[i][1] + v[i][2] * v[i][2] + v[i][3] * v[i][3];
;       ss += __shfl_xor(ss, 1);
;       ss += __shfl_xor(ss, 2);
;       ss += __shfl_xor(ss, 4);
;       ss += __shfl_xor(ss, 8);
;       const float r = rsqrtf(ss * (1.f / 512.f) + EPS);
; #pragma unroll
;       for (int i = 0; i < 4; ++i) {
;         u32x4 zz = *(const u32x4*)(p.PROJ + (size_t)tok * NP + C_GZ + col0 + 8 * i);
;         f32x4 g0 = *(const f32x4*)(p.gla_g + ((col0 + 8 * i) & 511));
;         f32x4 g1 = *(const f32x4*)(p.gla_g + ((col0 + 8 * i + 4) & 511));
;         u32x4 res;
; #pragma unroll
;         for (int q = 0; q < 4; ++q) {
;           float za = bflo(zz[q]), zb = bfhi(zz[q]);
;           float ga = (q < 2) ? g0[2 * q] : g1[2 * q - 4];
;           float gb = (q < 2) ? g0[2 * q + 1] : g1[2 * q - 3];
;           float xa = (q < 2) ? v[2 * i][2 * q] : v[2 * i + 1][2 * q - 4];
;           float xb = (q < 2) ? v[2 * i][2 * q + 1] : v[2 * i + 1][2 * q - 3];
;           res[q] = pack2(xa * r * ga * za * sigmoidf_(za), xb * r * gb * zb * sigmoidf_(zb));
	v_lshlrev_b32_e32 v52, 16, v18
	v_pk_add_f32 v[22:23], v[22:23], 1.0 op_sel_hi:[1,0]
	v_and_b32_e32 v51, 0xffff0000, v18
	v_pk_mul_f32 v[52:53], v[4:5], v[52:53] op_sel:[1,0] op_sel_hi:[0,1]
	v_pk_fma_f32 v[50:51], v[4:5], v[50:51], v[52:53]
	s_waitcnt vmcnt(0)
	v_lshlrev_b32_e32 v52, 16, v46
	v_and_b32_e32 v53, 0xffff0000, v46
	v_pk_fma_f32 v[50:51], v[0:1], v[52:53], v[50:51] op_sel_hi:[0,1,1]
	v_rcp_f32_e32 v23, v23
	s_nop 0
	v_pk_mul_f32 v[14:15], v[50:51], v[14:15]
	v_rcp_f32_e32 v22, v22
	s_nop 0
	v_pk_mul_f32 v[14:15], v[14:15], v[22:23]
	v_lshlrev_b32_e32 v22, 16, v11
	v_cvt_pk_bf16_f32 v6, v14, v15
	v_lshlrev_b32_e32 v14, 16, v7
	v_and_b32_e32 v15, 0xffff0000, v7
	v_mul_f32_e32 v1, 0xbfb8aa3b, v14
	v_exp_f32_e32 v10, v1
	v_mul_f32_e32 v1, 0xbfb8aa3b, v15
	v_and_b32_e32 v23, 0xffff0000, v19
	v_lshlrev_b32_e32 v18, 16, v19
	v_and_b32_e32 v19, 0xffff0000, v11
	v_exp_f32_e32 v11, v1
	v_pk_mul_f32 v[18:19], v[4:5], v[18:19] op_sel:[1,0] op_sel_hi:[0,1]
	v_pk_fma_f32 v[18:19], v[4:5], v[22:23], v[18:19]
	v_lshlrev_b32_e32 v22, 16, v47
	v_pk_add_f32 v[10:11], v[10:11], 1.0 op_sel_hi:[1,0]
	v_and_b32_e32 v23, 0xffff0000, v47
	v_pk_fma_f32 v[18:19], v[0:1], v[22:23], v[18:19] op_sel_hi:[0,1,1]
	v_pk_mul_f32 v[14:15], v[18:19], v[14:15]
	v_and_b32_e32 v23, 0xffff0000, v12
	v_rcp_f32_e32 v11, v11
	s_nop 0
	v_rcp_f32_e32 v10, v10
	s_nop 0
	v_pk_mul_f32 v[10:11], v[14:15], v[10:11]
	v_lshlrev_b32_e32 v22, 16, v20
	v_cvt_pk_bf16_f32 v7, v10, v11
	v_lshlrev_b32_e32 v10, 16, v8
	v_and_b32_e32 v11, 0xffff0000, v8
	v_mul_f32_e32 v1, 0xbfb8aa3b, v10
	v_exp_f32_e32 v14, v1
	v_mul_f32_e32 v1, 0xbfb8aa3b, v11
	v_exp_f32_e32 v15, v1
	v_lshlrev_b32_e32 v18, 16, v12
	v_and_b32_e32 v19, 0xffff0000, v20
	v_pk_mul_f32 v[22:23], v[4:5], v[22:23] op_sel:[1,0] op_sel_hi:[0,1]
	v_pk_add_f32 v[14:15], v[14:15], 1.0 op_sel_hi:[1,0]
	v_pk_fma_f32 v[18:19], v[4:5], v[18:19], v[22:23]
	v_lshlrev_b32_e32 v22, 16, v48
	v_and_b32_e32 v23, 0xffff0000, v48
	v_pk_fma_f32 v[18:19], v[0:1], v[22:23], v[18:19] op_sel_hi:[0,1,1]
	v_pk_mul_f32 v[10:11], v[18:19], v[10:11]
	v_rcp_f32_e32 v15, v15
	s_nop 0
	v_rcp_f32_e32 v14, v14
	s_nop 0
	v_pk_mul_f32 v[10:11], v[10:11], v[14:15]
	v_lshlrev_b32_e32 v14, 16, v13
	v_cvt_pk_bf16_f32 v8, v10, v11
	v_lshlrev_b32_e32 v10, 16, v9
	v_and_b32_e32 v11, 0xffff0000, v9
	v_mul_f32_e32 v1, 0xbfb8aa3b, v10
	v_exp_f32_e32 v12, v1
	v_mul_f32_e32 v1, 0xbfb8aa3b, v11
	v_and_b32_e32 v19, 0xffff0000, v13
	v_exp_f32_e32 v13, v1
	v_lshlrev_b32_e32 v18, 16, v21
	v_and_b32_e32 v15, 0xffff0000, v21
	v_pk_mul_f32 v[18:19], v[4:5], v[18:19] op_sel:[1,0] op_sel_hi:[0,1]
	v_pk_add_f32 v[12:13], v[12:13], 1.0 op_sel_hi:[1,0]
	v_pk_fma_f32 v[4:5], v[4:5], v[14:15], v[18:19]
	v_lshlrev_b32_e32 v14, 16, v49
	v_and_b32_e32 v15, 0xffff0000, v49
	v_pk_fma_f32 v[0:1], v[0:1], v[14:15], v[4:5] op_sel_hi:[0,1,1]
	v_pk_mul_f32 v[0:1], v[0:1], v[10:11]
	v_rcp_f32_e32 v5, v13
	s_nop 0
	v_lshl_add_u64 v[18:19], v[32:33], 0, v[56:57]
	v_rcp_f32_e32 v4, v12
	s_nop 0
	v_pk_mul_f32 v[0:1], v[0:1], v[4:5]
	v_lshl_add_u64 v[10:11], v[16:17], 0, v[26:27]
	v_cvt_pk_bf16_f32 v9, v0, v1
	global_store_dwordx4 v[2:3], v[6:9], off offset:16
	v_add_co_u32_e32 v54, vcc, s3, v10
	s_nop 0
	v_lshl_add_u64 v[8:9], v[30:31], 0, v[56:57]
	global_load_dwordx4 v[0:3], v[8:9], off offset:48
	global_load_dwordx4 v[4:7], v[18:19], off offset:48
	global_load_dwordx4 v[66:69], v[8:9], off
	global_load_dwordx4 v[88:91], v[18:19], off
	v_addc_co_u32_e32 v55, vcc, 0, v11, vcc
	global_load_dwordx4 v[92:95], v[54:55], off
	global_load_dwordx4 v[12:15], v[8:9], off offset:32
	global_load_dwordx4 v[20:23], v[8:9], off offset:16
	s_nop 0
	global_load_dwordx4 v[8:11], v[18:19], off offset:32
	s_nop 0
	global_load_dwordx4 v[16:19], v[18:19], off offset:16
	s_waitcnt vmcnt(7)
	v_lshlrev_b32_e32 v49, 16, v4
	s_waitcnt vmcnt(6)
	v_lshlrev_b32_e32 v58, 16, v69
	v_and_b32_e32 v59, 0xffff0000, v69
	s_waitcnt vmcnt(5)
	v_lshlrev_b32_e32 v60, 16, v91
	v_and_b32_e32 v61, 0xffff0000, v91
	v_pk_add_f32 v[58:59], v[58:59], v[60:61]
	s_waitcnt vmcnt(4)
	v_lshlrev_b32_e32 v60, 16, v94
	v_and_b32_e32 v61, 0xffff0000, v94
	v_mul_f32_e32 v25, 0xbfb8aa3b, v60
	v_exp_f32_e32 v62, v25
	v_mul_f32_e32 v25, 0xbfb8aa3b, v61
	v_exp_f32_e32 v63, v25
	v_lshlrev_b32_e32 v72, 16, v68
	v_and_b32_e32 v73, 0xffff0000, v68
	v_lshlrev_b32_e32 v68, 16, v90
	v_pk_add_f32 v[76:77], v[62:63], 1.0 op_sel_hi:[1,0]
	v_and_b32_e32 v69, 0xffff0000, v90
	v_pk_add_f32 v[62:63], v[72:73], v[68:69]
	v_and_b32_e32 v79, 0xffff0000, v67
	v_lshlrev_b32_e32 v80, 16, v89
	v_rcp_f32_e32 v69, v77
	s_nop 0
	v_lshlrev_b32_e32 v78, 16, v67
	v_lshlrev_b32_e32 v72, 16, v93
	v_rcp_f32_e32 v68, v76
	s_nop 0
	v_and_b32_e32 v73, 0xffff0000, v93
	v_mul_f32_e32 v25, 0xbfb8aa3b, v72
	v_exp_f32_e32 v76, v25
	v_mul_f32_e32 v25, 0xbfb8aa3b, v73
	v_exp_f32_e32 v77, v25
	v_and_b32_e32 v81, 0xffff0000, v89
	v_lshlrev_b32_e32 v47, 16, v0
	v_lshlrev_b32_e32 v46, 16, v2
	v_pk_add_f32 v[90:91], v[76:77], 1.0 op_sel_hi:[1,0]
	v_pk_add_f32 v[76:77], v[78:79], v[80:81]
	v_lshlrev_b32_e32 v48, 16, v6
	v_pk_add_f32 v[50:51], v[46:47], v[48:49]
	v_and_b32_e32 v47, 0xffff0000, v0
	v_rcp_f32_e32 v79, v91
	s_nop 0
	v_and_b32_e32 v46, 0xffff0000, v2
	v_lshlrev_b32_e32 v80, 16, v92
	v_rcp_f32_e32 v78, v90
	s_nop 0
	v_and_b32_e32 v81, 0xffff0000, v92
	v_mul_f32_e32 v25, 0xbfb8aa3b, v80
	v_exp_f32_e32 v90, v25
	v_mul_f32_e32 v25, 0xbfb8aa3b, v81
	v_and_b32_e32 v49, 0xffff0000, v4
	v_and_b32_e32 v48, 0xffff0000, v6
	v_exp_f32_e32 v91, v25
	v_pk_add_f32 v[52:53], v[46:47], v[48:49]
	v_lshlrev_b32_e32 v47, 16, v1
	v_lshlrev_b32_e32 v46, 16, v3
	v_lshlrev_b32_e32 v49, 16, v5
	v_lshlrev_b32_e32 v48, 16, v7
	v_and_b32_e32 v1, 0xffff0000, v1
	v_and_b32_e32 v0, 0xffff0000, v3
	v_and_b32_e32 v3, 0xffff0000, v5
	v_and_b32_e32 v2, 0xffff0000, v7
	v_pk_add_f32 v[46:47], v[46:47], v[48:49]
	v_pk_add_f32 v[48:49], v[0:1], v[2:3]
	v_pk_mul_f32 v[0:1], v[52:53], v[52:53]
	v_pk_add_f32 v[90:91], v[90:91], 1.0 op_sel_hi:[1,0]
	v_pk_fma_f32 v[0:1], v[50:51], v[50:51], v[0:1]
	v_pk_fma_f32 v[0:1], v[46:47], v[46:47], v[0:1]
	v_pk_fma_f32 v[64:65], v[48:49], v[48:49], v[0:1]
	global_load_dwordx4 v[0:3], v[34:35], off offset:16
	global_load_dwordx4 v[4:7], v[34:35], off
	v_lshlrev_b32_e32 v92, 16, v66
	v_and_b32_e32 v93, 0xffff0000, v66
	v_lshlrev_b32_e32 v66, 16, v88
	v_and_b32_e32 v67, 0xffff0000, v88
	v_pk_add_f32 v[88:89], v[92:93], v[66:67]
	v_rcp_f32_e32 v91, v91
	s_nop 0
	v_lshlrev_b32_e32 v94, 16, v95
	v_and_b32_e32 v95, 0xffff0000, v95
	v_mul_f32_e32 v66, 0xbfb8aa3b, v94
	v_mul_f32_e32 v67, 0xbfb8aa3b, v95
	v_exp_f32_e32 v66, v66
	v_exp_f32_e32 v67, v67
	s_nop 0
	v_pk_add_f32 v[98:99], v[66:67], 1.0 op_sel_hi:[1,0]
	s_waitcnt vmcnt(4)
; __device__ __forceinline__ float bflo(u32 v) { return __uint_as_float(v << 16); }
; __device__ __forceinline__ float bfhi(u32 v) { return __uint_as_float(v & 0xffff0000u); }
; __device__ __forceinline__ float sigmoidf_(float x) { return 1.f / (1.f + __expf(-x)); }
; __device__ void phase2c(const Params& p) {
;     ...
;       for (int i = 0; i < 8; ++i) ss += v[i][0] * v[i][0] + v[i][1] * v[i][1] + v[i][2] * v[i][2] + v[i][3] * v[i][3];
;       ss += __shfl_xor(ss, 1);
;       ss += __shfl_xor(ss, 2);
;       ss += __shfl_xor(ss, 4);
;       ss += __shfl_xor(ss, 8);
;       const float r = rsqrtf(ss * (1.f / 512.f) + EPS);
; #pragma unroll
;       for (int i = 0; i < 4; ++i) {
;         u32x4 zz = *(const u32x4*)(p.PROJ + (size_t)tok * NP + C_GZ + col0 + 8 * i);
;         f32x4 g0 = *(const f32x4*)(p.gla_g + ((col0 + 8 * i) & 511));
;         f32x4 g1 = *(const f32x4*)(p.gla_g + ((col0 + 8 * i + 4) & 511));
;         u32x4 res;
; #pragma unroll
;         for (int q = 0; q < 4; ++q) {
;           float za = bflo(zz[q]), zb = bfhi(zz[q]);
;           float ga = (q < 2) ? g0[2 * q] : g1[2 * q - 4];
;           float gb = (q < 2) ? g0[2 * q + 1] : g1[2 * q - 3];
;           float xa = (q < 2) ? v[2 * i][2 * q] : v[2 * i + 1][2 * q - 4];
;           float xb = (q < 2) ? v[2 * i][2 * q + 1] : v[2 * i + 1][2 * q - 3];
;           res[q] = pack2(xa * r * ga * za * sigmoidf_(za), xb * r * gb * zb * sigmoidf_(zb));
;         }
;         *(u32x4*)(p.YB + (size_t)tok * 2048 + col0 + 8 * i) = res;
	v_lshlrev_b32_e32 v66, 16, v23
	v_and_b32_e32 v67, 0xffff0000, v23
	s_waitcnt vmcnt(2)
	v_lshlrev_b32_e32 v100, 16, v19
	v_and_b32_e32 v101, 0xffff0000, v19
	v_pk_add_f32 v[66:67], v[66:67], v[100:101]
	v_lshlrev_b32_e32 v100, 16, v22
	v_and_b32_e32 v101, 0xffff0000, v22
	v_lshlrev_b32_e32 v22, 16, v18
	v_and_b32_e32 v23, 0xffff0000, v18
	v_pk_add_f32 v[22:23], v[100:101], v[22:23]
	v_lshlrev_b32_e32 v18, 16, v21
	v_and_b32_e32 v19, 0xffff0000, v21
	v_lshlrev_b32_e32 v100, 16, v17
	v_and_b32_e32 v101, 0xffff0000, v17
	v_pk_add_f32 v[100:101], v[18:19], v[100:101]
	v_lshlrev_b32_e32 v18, 16, v20
	v_and_b32_e32 v19, 0xffff0000, v20
	v_lshlrev_b32_e32 v20, 16, v16
	v_and_b32_e32 v21, 0xffff0000, v16
	v_pk_add_f32 v[20:21], v[18:19], v[20:21]
	v_mov_b32_e32 v104, v23
	v_mov_b32_e32 v105, v21
	v_mov_b32_e32 v102, v22
	v_mov_b32_e32 v103, v20
	v_pk_mul_f32 v[104:105], v[104:105], v[104:105]
	v_mov_b32_e32 v16, v66
	v_mov_b32_e32 v17, v100
	v_pk_fma_f32 v[102:103], v[102:103], v[102:103], v[104:105]
	v_mov_b32_e32 v18, v67
	v_mov_b32_e32 v19, v101
	v_pk_fma_f32 v[16:17], v[16:17], v[16:17], v[102:103]
	v_pk_mul_f32 v[74:75], v[62:63], v[62:63]
	v_pk_fma_f32 v[102:103], v[18:19], v[18:19], v[16:17]
	v_lshlrev_b32_e32 v16, 16, v15
	v_and_b32_e32 v17, 0xffff0000, v15
	v_lshlrev_b32_e32 v18, 16, v11
	v_and_b32_e32 v19, 0xffff0000, v11
	v_pk_add_f32 v[16:17], v[16:17], v[18:19]
	v_lshlrev_b32_e32 v18, 16, v14
	v_and_b32_e32 v19, 0xffff0000, v14
	v_lshlrev_b32_e32 v14, 16, v10
	v_and_b32_e32 v15, 0xffff0000, v10
	v_pk_add_f32 v[14:15], v[18:19], v[14:15]
	v_lshlrev_b32_e32 v10, 16, v13
	v_and_b32_e32 v11, 0xffff0000, v13
	v_lshlrev_b32_e32 v18, 16, v9
	v_and_b32_e32 v19, 0xffff0000, v9
	v_pk_add_f32 v[18:19], v[10:11], v[18:19]
	v_lshlrev_b32_e32 v10, 16, v12
	v_and_b32_e32 v11, 0xffff0000, v12
	v_lshlrev_b32_e32 v12, 16, v8
	v_and_b32_e32 v13, 0xffff0000, v8
	v_pk_add_f32 v[12:13], v[10:11], v[12:13]
	v_mov_b32_e32 v106, v15
	v_mov_b32_e32 v107, v13
	v_mov_b32_e32 v104, v14
	v_mov_b32_e32 v105, v12
	v_pk_mul_f32 v[106:107], v[106:107], v[106:107]
	v_mov_b32_e32 v8, v16
	v_mov_b32_e32 v9, v18
	v_pk_fma_f32 v[104:105], v[104:105], v[104:105], v[106:107]
	v_pk_mul_f32 v[92:93], v[88:89], v[88:89]
	v_mov_b32_e32 v10, v17
	v_mov_b32_e32 v11, v19
	v_pk_fma_f32 v[8:9], v[8:9], v[8:9], v[104:105]
	v_pk_mul_f32 v[70:71], v[58:59], v[58:59]
	v_pk_mul_f32 v[96:97], v[76:77], v[76:77]
	v_pk_fma_f32 v[8:9], v[10:11], v[10:11], v[8:9]
	v_add_f32_e32 v10, v74, v75
	v_add_f32_e32 v11, v92, v93
	v_add_f32_e32 v10, v70, v10
	v_add_f32_e32 v11, v96, v11
	v_add_f32_e32 v10, v71, v10
	v_add_f32_e32 v11, v97, v11
	v_add_f32_e32 v10, v11, v10
	v_add_f32_e32 v10, v10, v103
	v_add_f32_e32 v10, v102, v10
	v_add_f32_e32 v9, v10, v9
	v_add_f32_e32 v8, v8, v9
	v_add_f32_e32 v8, v8, v65
	v_add_f32_e32 v8, v64, v8
	ds_bpermute_b32 v9, v82, v8
	v_rcp_f32_e32 v90, v90
	s_nop 0
	s_waitcnt lgkmcnt(0)
	v_add_f32_e32 v8, v8, v9
	ds_bpermute_b32 v9, v83, v8
	s_waitcnt lgkmcnt(0)
	v_add_f32_e32 v8, v8, v9
	ds_bpermute_b32 v9, v84, v8
	s_waitcnt lgkmcnt(0)
	v_add_f32_e32 v8, v8, v9
	ds_bpermute_b32 v9, v85, v8
	v_rcp_f32_e32 v65, v99
	s_nop 0
	s_waitcnt lgkmcnt(0)
	v_add_f32_e32 v8, v8, v9
	v_fmamk_f32 v8, v8, 0x3b000000, v86
	v_mul_f32_e32 v9, 0x4b800000, v8
	v_cmp_gt_f32_e64 s[0:1], s11, v8
	s_nop 1
	v_cndmask_b32_e64 v8, v8, v9, s[0:1]
	v_rsq_f32_e32 v11, v8
	v_rcp_f32_e32 v64, v98
	s_nop 0
	v_lshl_add_u64 v[8:9], v[36:37], 0, v[56:57]
	v_mul_f32_e32 v10, 0x45800000, v11
	v_cndmask_b32_e64 v10, v11, v10, s[0:1]
	v_pk_mul_f32 v[56:57], v[88:89], v[10:11] op_sel_hi:[1,0]
	s_waitcnt vmcnt(0)
	v_pk_mul_f32 v[4:5], v[4:5], v[56:57]
	v_pk_mul_f32 v[56:57], v[76:77], v[10:11] op_sel_hi:[1,0]
	v_pk_mul_f32 v[4:5], v[4:5], v[80:81]
	v_pk_mul_f32 v[6:7], v[6:7], v[56:57]
	v_pk_mul_f32 v[4:5], v[90:91], v[4:5]
	v_pk_mul_f32 v[6:7], v[6:7], v[72:73]
	v_cvt_pk_bf16_f32 v4, v4, v5
	v_pk_mul_f32 v[6:7], v[78:79], v[6:7]
	s_nop 0
	v_cvt_pk_bf16_f32 v5, v6, v7
	v_pk_mul_f32 v[6:7], v[62:63], v[10:11] op_sel_hi:[1,0]
	s_nop 0
	v_pk_mul_f32 v[0:1], v[0:1], v[6:7]
	s_nop 0
	v_pk_mul_f32 v[0:1], v[0:1], v[60:61]
	s_nop 0
	v_pk_mul_f32 v[0:1], v[68:69], v[0:1]
	s_nop 0
	v_cvt_pk_bf16_f32 v6, v0, v1
	v_pk_mul_f32 v[0:1], v[58:59], v[10:11] op_sel_hi:[1,0]
	s_nop 0
	v_pk_mul_f32 v[0:1], v[2:3], v[0:1]
	s_nop 0
	v_pk_mul_f32 v[0:1], v[0:1], v[94:95]
	s_nop 0
	v_pk_mul_f32 v[0:1], v[64:65], v[0:1]
	s_nop 0
	v_cvt_pk_bf16_f32 v7, v0, v1
	global_store_dwordx4 v[8:9], v[4:7], off
	global_load_dwordx4 v[0:3], v[54:55], off offset:16
	s_nop 0
	global_load_dwordx4 v[4:7], v[34:35], off offset:32
	global_load_dwordx4 v[56:59], v[34:35], off offset:48
	s_waitcnt vmcnt(2)
	v_lshlrev_b32_e32 v60, 16, v0
	v_and_b32_e32 v61, 0xffff0000, v0
	v_mul_f32_e32 v0, 0xbfb8aa3b, v60
	v_exp_f32_e32 v62, v0
	v_mul_f32_e32 v0, 0xbfb8aa3b, v61
	v_exp_f32_e32 v63, v0
	s_nop 0
	v_pk_add_f32 v[62:63], v[62:63], 1.0 op_sel_hi:[1,0]
	s_nop 0
	s_nop 0
	v_pk_mul_f32 v[20:21], v[20:21], v[10:11] op_sel_hi:[1,0]
	s_waitcnt vmcnt(1)
	v_pk_mul_f32 v[4:5], v[4:5], v[20:21]
	v_rcp_f32_e32 v21, v63
	s_nop 0
	v_pk_mul_f32 v[4:5], v[4:5], v[60:61]
	v_lshlrev_b32_e32 v60, 16, v1
	v_and_b32_e32 v61, 0xffff0000, v1
	v_mul_f32_e32 v1, 0xbfb8aa3b, v60
	v_exp_f32_e32 v64, v1
	v_mul_f32_e32 v1, 0xbfb8aa3b, v61
	v_exp_f32_e32 v65, v1
	v_rcp_f32_e32 v20, v62
	s_nop 0
	v_pk_mul_f32 v[0:1], v[20:21], v[4:5]
	v_pk_add_f32 v[4:5], v[64:65], 1.0 op_sel_hi:[1,0]
	v_cvt_pk_bf16_f32 v0, v0, v1
	s_nop 0
	v_pk_mul_f32 v[20:21], v[100:101], v[10:11] op_sel_hi:[1,0]
	s_nop 0
	v_pk_mul_f32 v[6:7], v[6:7], v[20:21]
	v_rcp_f32_e32 v5, v5
	s_nop 0
	v_pk_mul_f32 v[6:7], v[6:7], v[60:61]
	v_lshlrev_b32_e32 v20, 16, v2
	v_and_b32_e32 v21, 0xffff0000, v2
	v_mul_f32_e32 v2, 0xbfb8aa3b, v20
	v_exp_f32_e32 v60, v2
	v_mul_f32_e32 v2, 0xbfb8aa3b, v21
	v_exp_f32_e32 v61, v2
	v_rcp_f32_e32 v4, v4
	s_nop 0
	v_pk_mul_f32 v[4:5], v[4:5], v[6:7]
	s_nop 0
	v_cvt_pk_bf16_f32 v1, v4, v5
	v_pk_add_f32 v[4:5], v[60:61], 1.0 op_sel_hi:[1,0]
	s_nop 0
	s_nop 0
	v_pk_mul_f32 v[6:7], v[22:23], v[10:11] op_sel_hi:[1,0]
	s_waitcnt vmcnt(0)
; __device__ __forceinline__ float bflo(u32 v) { return __uint_as_float(v << 16); }
; __device__ __forceinline__ float bfhi(u32 v) { return __uint_as_float(v & 0xffff0000u); }
; __device__ __forceinline__ float sigmoidf_(float x) { return 1.f / (1.f + __expf(-x)); }
; __device__ void phase2c(const Params& p) {
;     ...
; #pragma unroll
;       for (int i = 0; i < 4; ++i) {
;         u32x4 zz = *(const u32x4*)(p.PROJ + (size_t)tok * NP + C_GZ + col0 + 8 * i);
;         f32x4 g0 = *(const f32x4*)(p.gla_g + ((col0 + 8 * i) & 511));
;         f32x4 g1 = *(const f32x4*)(p.gla_g + ((col0 + 8 * i + 4) & 511));
;         u32x4 res;
; #pragma unroll
;         for (int q = 0; q < 4; ++q) {
;           float za = bflo(zz[q]), zb = bfhi(zz[q]);
;           float ga = (q < 2) ? g0[2 * q] : g1[2 * q - 4];
;           float gb = (q < 2) ? g0[2 * q + 1] : g1[2 * q - 3];
;           float xa = (q < 2) ? v[2 * i][2 * q] : v[2 * i + 1][2 * q - 4];
;           float xb = (q < 2) ? v[2 * i][2 * q + 1] : v[2 * i + 1][2 * q - 3];
;           res[q] = pack2(xa * r * ga * za * sigmoidf_(za), xb * r * gb * zb * sigmoidf_(zb));
;         }
;         *(u32x4*)(p.YB + (size_t)tok * 2048 + col0 + 8 * i) = res;
;       }
;     }
;   }
	v_pk_mul_f32 v[6:7], v[56:57], v[6:7]
	s_nop 0
	v_pk_mul_f32 v[6:7], v[6:7], v[20:21]
	v_rcp_f32_e32 v5, v5
	s_nop 0
	v_lshlrev_b32_e32 v20, 16, v3
	v_and_b32_e32 v21, 0xffff0000, v3
	v_mul_f32_e32 v3, 0xbfb8aa3b, v20
	v_exp_f32_e32 v22, v3
	v_mul_f32_e32 v3, 0xbfb8aa3b, v21
	v_exp_f32_e32 v23, v3
	v_rcp_f32_e32 v4, v4
	s_nop 0
	v_pk_mul_f32 v[2:3], v[4:5], v[6:7]
	v_pk_add_f32 v[4:5], v[22:23], 1.0 op_sel_hi:[1,0]
	v_cvt_pk_bf16_f32 v2, v2, v3
	s_nop 0
	v_pk_mul_f32 v[6:7], v[66:67], v[10:11] op_sel_hi:[1,0]
	s_nop 0
	v_pk_mul_f32 v[6:7], v[58:59], v[6:7]
	s_nop 0
	v_pk_mul_f32 v[6:7], v[6:7], v[20:21]
	v_rcp_f32_e32 v5, v5
	s_nop 0
	v_rcp_f32_e32 v4, v4
	s_nop 0
	v_pk_mul_f32 v[4:5], v[4:5], v[6:7]
	s_nop 0
	v_cvt_pk_bf16_f32 v3, v4, v5
	global_store_dwordx4 v[8:9], v[0:3], off offset:16
	global_load_dwordx4 v[0:3], v[54:55], off offset:32
	s_nop 0
	global_load_dwordx4 v[4:7], v[34:35], off offset:64
	global_load_dwordx4 v[20:23], v[34:35], off offset:80
	s_waitcnt vmcnt(2)
	v_lshlrev_b32_e32 v56, 16, v0
	v_and_b32_e32 v57, 0xffff0000, v0
	v_mul_f32_e32 v0, 0xbfb8aa3b, v56
	v_exp_f32_e32 v58, v0
	v_mul_f32_e32 v0, 0xbfb8aa3b, v57
	v_exp_f32_e32 v59, v0
	s_nop 0
	v_pk_add_f32 v[58:59], v[58:59], 1.0 op_sel_hi:[1,0]
	s_nop 0
	s_nop 0
	v_pk_mul_f32 v[12:13], v[12:13], v[10:11] op_sel_hi:[1,0]
	s_waitcnt vmcnt(1)
	v_pk_mul_f32 v[4:5], v[4:5], v[12:13]
	v_rcp_f32_e32 v13, v59
	s_nop 0
	v_pk_mul_f32 v[4:5], v[4:5], v[56:57]
	v_lshlrev_b32_e32 v56, 16, v1
	v_and_b32_e32 v57, 0xffff0000, v1
	v_mul_f32_e32 v1, 0xbfb8aa3b, v56
	v_exp_f32_e32 v60, v1
	v_mul_f32_e32 v1, 0xbfb8aa3b, v57
	v_exp_f32_e32 v61, v1
	v_rcp_f32_e32 v12, v58
	s_nop 0
	v_pk_mul_f32 v[0:1], v[12:13], v[4:5]
	v_pk_add_f32 v[4:5], v[60:61], 1.0 op_sel_hi:[1,0]
	v_cvt_pk_bf16_f32 v0, v0, v1
	s_nop 0
	v_pk_mul_f32 v[12:13], v[18:19], v[10:11] op_sel_hi:[1,0]
	s_nop 0
	v_pk_mul_f32 v[6:7], v[6:7], v[12:13]
	v_rcp_f32_e32 v5, v5
	s_nop 0
	v_pk_mul_f32 v[6:7], v[6:7], v[56:57]
	v_lshlrev_b32_e32 v12, 16, v2
	v_and_b32_e32 v13, 0xffff0000, v2
	v_mul_f32_e32 v2, 0xbfb8aa3b, v12
	v_exp_f32_e32 v18, v2
	v_mul_f32_e32 v2, 0xbfb8aa3b, v13
	v_exp_f32_e32 v19, v2
	v_rcp_f32_e32 v4, v4
	s_nop 0
	v_pk_mul_f32 v[4:5], v[4:5], v[6:7]
	s_nop 0
	v_cvt_pk_bf16_f32 v1, v4, v5
	v_pk_add_f32 v[4:5], v[18:19], 1.0 op_sel_hi:[1,0]
	s_nop 0
	s_nop 0
	v_pk_mul_f32 v[6:7], v[14:15], v[10:11] op_sel_hi:[1,0]
	s_waitcnt vmcnt(0)
	v_pk_mul_f32 v[6:7], v[20:21], v[6:7]
	v_mov_b32_e32 v20, v51
	v_pk_mul_f32 v[6:7], v[6:7], v[12:13]
	v_rcp_f32_e32 v5, v5
	s_nop 0
	v_mov_b32_e32 v21, v53
	v_lshlrev_b32_e32 v12, 16, v3
	v_and_b32_e32 v13, 0xffff0000, v3
	v_mul_f32_e32 v3, 0xbfb8aa3b, v12
	v_exp_f32_e32 v14, v3
	v_mul_f32_e32 v3, 0xbfb8aa3b, v13
	v_exp_f32_e32 v15, v3
	v_rcp_f32_e32 v4, v4
	s_nop 0
	v_pk_mul_f32 v[2:3], v[4:5], v[6:7]
	v_mov_b32_e32 v51, v52
	v_pk_add_f32 v[4:5], v[14:15], 1.0 op_sel_hi:[1,0]
	v_cvt_pk_bf16_f32 v2, v2, v3
	s_nop 0
	v_pk_mul_f32 v[6:7], v[16:17], v[10:11] op_sel_hi:[1,0]
	s_nop 0
	v_pk_mul_f32 v[6:7], v[22:23], v[6:7]
	s_nop 0
	v_pk_mul_f32 v[6:7], v[6:7], v[12:13]
	v_rcp_f32_e32 v5, v5
	s_nop 0
	v_rcp_f32_e32 v4, v4
	s_nop 0
	v_pk_mul_f32 v[4:5], v[4:5], v[6:7]
	s_nop 0
	v_cvt_pk_bf16_f32 v3, v4, v5
	global_store_dwordx4 v[8:9], v[0:3], off offset:32
	global_load_dwordx4 v[0:3], v[54:55], off offset:48
	s_nop 0
	global_load_dwordx4 v[4:7], v[34:35], off offset:96
	global_load_dwordx4 v[12:15], v[34:35], off offset:112
	s_waitcnt vmcnt(2)
	v_lshlrev_b32_e32 v16, 16, v0
	v_and_b32_e32 v17, 0xffff0000, v0
	v_mul_f32_e32 v0, 0xbfb8aa3b, v16
	v_exp_f32_e32 v18, v0
	v_mul_f32_e32 v0, 0xbfb8aa3b, v17
	v_exp_f32_e32 v19, v0
	s_nop 0
	v_pk_add_f32 v[18:19], v[18:19], 1.0 op_sel_hi:[1,0]
	s_nop 0
	s_nop 0
	v_pk_mul_f32 v[20:21], v[20:21], v[10:11] op_sel_hi:[1,0]
	s_waitcnt vmcnt(1)
	v_pk_mul_f32 v[4:5], v[4:5], v[20:21]
	s_nop 0
	v_pk_mul_f32 v[4:5], v[4:5], v[16:17]
	v_rcp_f32_e32 v17, v19
	s_nop 0
	v_rcp_f32_e32 v16, v18
	s_nop 0
	v_pk_mul_f32 v[4:5], v[16:17], v[4:5]
	v_lshlrev_b32_e32 v16, 16, v1
	v_and_b32_e32 v17, 0xffff0000, v1
	v_mul_f32_e32 v0, 0xbfb8aa3b, v16
	v_exp_f32_e32 v18, v0
	v_mul_f32_e32 v0, 0xbfb8aa3b, v17
	v_exp_f32_e32 v19, v0
	v_cvt_pk_bf16_f32 v0, v4, v5
	v_mov_b32_e32 v4, v47
	v_mov_b32_e32 v5, v49
	v_pk_add_f32 v[18:19], v[18:19], 1.0 op_sel_hi:[1,0]
	v_mov_b32_e32 v47, v48
	s_nop 0
	v_pk_mul_f32 v[4:5], v[4:5], v[10:11] op_sel_hi:[1,0]
	s_nop 0
	v_pk_mul_f32 v[4:5], v[6:7], v[4:5]
	v_pk_mul_f32 v[4:5], v[4:5], v[16:17]
	v_rcp_f32_e32 v7, v19
	s_nop 0
	v_lshlrev_b32_e32 v16, 16, v2
	v_rcp_f32_e32 v6, v18
	s_nop 0
	v_and_b32_e32 v17, 0xffff0000, v2
	v_mul_f32_e32 v1, 0xbfb8aa3b, v16
	v_exp_f32_e32 v18, v1
	v_mul_f32_e32 v1, 0xbfb8aa3b, v17
	v_exp_f32_e32 v19, v1
	v_pk_mul_f32 v[4:5], v[6:7], v[4:5]
	s_nop 0
	v_cvt_pk_bf16_f32 v1, v4, v5
	v_pk_add_f32 v[4:5], v[18:19], 1.0 op_sel_hi:[1,0]
	s_nop 0
	s_nop 0
	v_pk_mul_f32 v[6:7], v[50:51], v[10:11] op_sel_hi:[1,0]
	s_waitcnt vmcnt(0)
	v_pk_mul_f32 v[6:7], v[12:13], v[6:7]
	v_pk_mul_f32 v[6:7], v[6:7], v[16:17]
	v_rcp_f32_e32 v5, v5
	s_nop 0
	v_lshlrev_b32_e32 v12, 16, v3
	v_rcp_f32_e32 v4, v4
	s_nop 0
	v_and_b32_e32 v13, 0xffff0000, v3
	v_mul_f32_e32 v2, 0xbfb8aa3b, v12
	v_exp_f32_e32 v16, v2
	v_mul_f32_e32 v2, 0xbfb8aa3b, v13
	v_exp_f32_e32 v17, v2
	v_pk_mul_f32 v[2:3], v[4:5], v[6:7]
	v_pk_add_f32 v[4:5], v[16:17], 1.0 op_sel_hi:[1,0]
	v_cvt_pk_bf16_f32 v2, v2, v3
	s_nop 0
	v_pk_mul_f32 v[6:7], v[46:47], v[10:11] op_sel_hi:[1,0]
	v_pk_mul_f32 v[6:7], v[14:15], v[6:7]
	v_pk_mul_f32 v[6:7], v[6:7], v[12:13]
	v_rcp_f32_e32 v5, v5
	s_nop 0
	v_rcp_f32_e32 v4, v4
	s_nop 0
	v_pk_mul_f32 v[4:5], v[4:5], v[6:7]
	v_cmp_lt_i32_e32 vcc, s18, v24
	v_cvt_pk_bf16_f32 v3, v4, v5
	s_or_b64 s[8:9], vcc, s[8:9]
	global_store_dwordx4 v[8:9], v[0:3], off offset:48
	s_andn2_b64 exec, exec, s[8:9]
	s_cbranch_execnz .LBB0_513

; __device__ __forceinline__ float bflo(u32 v) { return __uint_as_float(v << 16); }
; __device__ __forceinline__ float bfhi(u32 v) { return __uint_as_float(v & 0xffff0000u); }
; __device__ __forceinline__ void gemm_prologue(const u16* __restrict__ A, const u16* __restrict__ Bt, const int K,
;                                               const int brow, const int bcol) {
;   int tid = threadIdx.x;
;   asm volatile("" : "+v"(tid));
;   const int tid16 = tid * 16;
;   int goff0, goff1;
;   { int R, C; stage_rc(tid16, R, C); goff0 = R * K + C; stage_rc(tid16 + 8192, R, C); goff1 = R * K + C; }
;   STAGE(SB(0, 0), Bt, bcol, 0); STAGE(SA(0, 0), A, brow, 0);
;   STAGE(SB(0, 1), Bt, bcol + HALF, 0); STAGE(SA(0, 1), A, brow + HALF, 0);
; }
; __device__ void phase3(const Params& p) {
;     ...
;     const char* gta = p.GT + (size_t)((pm * 16 + pn) * 2) * 131072 + tid * 16;
;     const char* gtb = gta + 131072;
;     {
;       int koff = 0;
; #pragma unroll
;       for (int ai = 0; ai < 2; ++ai)
; #pragma unroll
;         for (int bj = 0; bj < 2; ++bj) {
;           asm volatile("" : "+v"(koff));
;           u32x4 sa[4], sb[4];
; #pragma unroll
;           for (int m = 0; m < 4; ++m) {
;             sa[m] = __builtin_nontemporal_load((const u32x4*)(gta + koff + ((ai * 2 + bj) * 4 + m) * 8192));
;             sb[m] = __builtin_nontemporal_load((const u32x4*)(gtb + koff + ((ai * 2 + bj) * 4 + m) * 8192));
;           }
; #pragma unroll
;           for (int m = 0; m < 4; ++m)
; #pragma unroll
;             for (int n = 0; n < 2; ++n) {
;               const u32x4 A4 = sa[m], B4 = sb[m];
;               acc[ai][bj][m][n][0] *= bflo(A4[2 * n]) / bflo(B4[2 * n]);
;               acc[ai][bj][m][n][1] *= bfhi(A4[2 * n]) / bfhi(B4[2 * n]);
;               acc[ai][bj][m][n][2] *= bflo(A4[2 * n + 1]) / bflo(B4[2 * n + 1]);
;               acc[ai][bj][m][n][3] *= bfhi(A4[2 * n + 1]) / bfhi(B4[2 * n + 1]);
.LBB0_562:
	s_or_b64 exec, exec, s[56:57]
	v_mov_b32_e32 v124, v248
	s_waitcnt vmcnt(0)
	s_barrier
	s_lshl_b64 s[48:49], s[48:49], 1
	v_ashrrev_i32_e32 v125, 31, v124
	v_lshrrev_b32_e32 v125, 26, v125
	v_lshlrev_b32_e32 v130, 4, v124
	v_add_u32_e32 v125, v124, v125
	v_bfe_i32 v124, v124, 27, 1
	v_lshrrev_b32_e32 v124, 22, v124
	v_add_u32_e32 v124, v130, v124
	v_and_b32_e32 v124, 0xfffffc00, v124
	v_sub_u32_e32 v124, v130, v124
	v_lshrrev_b32_e32 v126, 4, v124
	v_bitop3_b32 v124, v126, v124, 32 bitop3:0x6c
	v_ashrrev_i32_e32 v127, 31, v124
	v_ashrrev_i32_e32 v125, 6, v125
	v_lshrrev_b32_e32 v127, 26, v127
	v_lshlrev_b32_e32 v126, 3, v125
	v_add_u32_e32 v127, v124, v127
	v_and_b32_e32 v126, 0x1ffff0, v126
	v_lshrrev_b32_e32 v128, 6, v127
	v_lshlrev_b32_e32 v125, 5, v125
	v_and_b32_e32 v127, 0xc0, v127
	v_add_u32_e32 v126, v128, v126
	v_and_b32_e32 v125, 32, v125
	v_sub_u32_e32 v124, v124, v127
	v_ashrrev_i16_sdwa v124, v251, sext(v124) dst_sel:DWORD dst_unused:UNUSED_PAD src0_sel:DWORD src1_sel:BYTE_0
	v_lshl_or_b32 v125, v126, 11, v125
	v_add_u32_e32 v131, 0x2000, v130
	v_add_u32_sdwa v124, v125, sext(v124) dst_sel:DWORD dst_unused:UNUSED_PAD src0_sel:DWORD src1_sel:WORD_0
	v_ashrrev_i32_e32 v125, 31, v131
	v_lshrrev_b32_e32 v125, 22, v125
	v_add_u32_e32 v125, v131, v125
	v_ashrrev_i32_e32 v125, 10, v125
	v_mul_i32_i24_e32 v126, 0x400, v125
	v_sub_u32_e32 v126, v131, v126
	v_lshrrev_b32_e32 v127, 4, v126
	v_bitop3_b32 v126, v127, v126, 32 bitop3:0x6c
	v_ashrrev_i32_e32 v128, 31, v126
	v_lshrrev_b32_e32 v128, 26, v128
	v_lshlrev_b32_e32 v127, 3, v125
	v_add_u32_e32 v128, v126, v128
	v_and_b32_e32 v127, 0x1ffff0, v127
	v_lshrrev_b32_e32 v129, 6, v128
	v_lshlrev_b32_e32 v125, 5, v125
	v_and_b32_e32 v128, 0xc0, v128
	v_add_u32_e32 v127, v129, v127
	v_and_b32_e32 v125, 32, v125
	v_sub_u32_e32 v126, v126, v128
	v_ashrrev_i16_sdwa v126, v251, sext(v126) dst_sel:DWORD dst_unused:UNUSED_PAD src0_sel:DWORD src1_sel:BYTE_0
	v_lshl_or_b32 v125, v127, 11, v125
	v_add_u32_sdwa v126, v125, sext(v126) dst_sel:DWORD dst_unused:UNUSED_PAD src0_sel:DWORD src1_sel:WORD_0
	s_add_u32 s56, s68, s48
	v_ashrrev_i32_e32 v125, 31, v124
	v_add_u32_e32 v127, 0x10000, v130
	s_addc_u32 s57, s69, s49
	v_lshlrev_b64 v[124:125], 1, v[124:125]
	v_readfirstlane_b32 s48, v127
	v_ashrrev_i32_e32 v127, 31, v126
	v_add_u32_e32 v132, 0x12000, v130
	s_lshl_b32 s5, s5, 1
	v_lshl_add_u64 v[128:129], s[56:57], 0, v[124:125]
	s_mov_b32 m0, s48
	v_lshlrev_b64 v[126:127], 1, v[126:127]
	v_readfirstlane_b32 s48, v132
	s_add_u32 s58, s78, s5
	global_load_lds_dwordx4 v[128:129], off
	v_lshl_add_u64 v[128:129], s[56:57], 0, v[126:127]
	s_mov_b32 m0, s48
	s_addc_u32 s59, s79, 0
	v_readfirstlane_b32 s5, v130
	s_lshl_b64 s[48:49], s[60:61], 1
	global_load_lds_dwordx4 v[128:129], off
	v_lshl_add_u64 v[128:129], s[58:59], 0, v[124:125]
	s_mov_b32 m0, s5
	v_readfirstlane_b32 s5, v131
	s_add_u32 s60, s68, s48
	v_add_u32_e32 v131, 0x14000, v130
	global_load_lds_dwordx4 v[128:129], off
	v_lshl_add_u64 v[128:129], s[58:59], 0, v[126:127]
	s_mov_b32 m0, s5
	s_addc_u32 s61, s69, s49
	v_readfirstlane_b32 s5, v131
	v_add_u32_e32 v131, 0x16000, v130
	global_load_lds_dwordx4 v[128:129], off
	v_lshl_add_u64 v[128:129], s[60:61], 0, v[124:125]
	s_mov_b32 m0, s5
	v_readfirstlane_b32 s5, v131
	global_load_lds_dwordx4 v[128:129], off
	v_lshl_add_u64 v[128:129], s[60:61], 0, v[126:127]
	s_mov_b32 m0, s5
	s_lshl_b32 s5, s63, 1
	global_load_lds_dwordx4 v[128:129], off
	s_add_u32 s48, s78, s5
	v_add_u32_e32 v128, 0x4000, v130
	s_addc_u32 s49, s79, 0
	v_readfirstlane_b32 s5, v128
	v_lshl_add_u64 v[124:125], s[48:49], 0, v[124:125]
	s_mov_b32 m0, s5
	s_lshl_b32 s62, s62, 1
	global_load_lds_dwordx4 v[124:125], off
	v_lshl_add_u64 v[124:125], s[48:49], 0, v[126:127]
	v_add_u32_e32 v126, 0x6000, v130
	v_mov_b32_e32 v166, 0
	v_readfirstlane_b32 s5, v126
	s_mov_b32 m0, s5
	s_lshl_b32 s5, s2, 5
	s_add_i32 s62, s5, s62
	s_ashr_i32 s63, s62, 31
	s_lshl_b64 s[62:63], s[62:63], 17
	global_load_lds_dwordx4 v[124:125], off
	v_lshl_add_u64 v[132:133], v[244:245], 0, s[62:63]
	v_lshl_add_u64 v[246:247], v[132:133], 0, s[30:31]
	v_ashrrev_i32_e32 v167, 31, v166
	v_lshl_add_u64 v[124:125], v[132:133], 0, v[166:167]
	v_lshl_add_u64 v[128:129], v[246:247], 0, v[166:167]
	global_load_dwordx4 v[204:207], v[124:125], off nt
	global_load_dwordx4 v[200:203], v[128:129], off nt
	v_add_co_u32_e32 v126, vcc, s64, v124
	s_waitcnt vmcnt(0)
	v_and_b32_e32 v135, 0xffff0000, v204
	v_addc_co_u32_e32 v127, vcc, 0, v125, vcc
	global_load_dwordx4 v[174:177], v[126:127], off nt
	v_add_co_u32_e32 v126, vcc, s64, v128
	v_and_b32_e32 v137, 0xffff0000, v200
	s_nop 0
	v_addc_co_u32_e32 v127, vcc, 0, v129, vcc
	global_load_dwordx4 v[178:181], v[126:127], off nt
	v_add_co_u32_e32 v126, vcc, s87, v124
	s_nop 0
	s_nop 0
	v_addc_co_u32_e32 v127, vcc, 0, v125, vcc
	global_load_dwordx4 v[140:143], v[126:127], off nt
	v_add_co_u32_e32 v126, vcc, s87, v128
	s_nop 0
	s_nop 0
	v_addc_co_u32_e32 v127, vcc, 0, v129, vcc
	v_add_co_u32_e32 v124, vcc, s88, v124
	s_nop 0
	s_nop 0
	v_addc_co_u32_e32 v125, vcc, 0, v125, vcc
	v_add_co_u32_e32 v128, vcc, s88, v128
	s_nop 0
	s_nop 0
	v_addc_co_u32_e32 v129, vcc, 0, v129, vcc
	v_lshlrev_b32_e32 v134, 16, v204
	v_lshlrev_b32_e32 v136, 16, v200
	v_rcp_f32_e32 v138, v137
	s_nop 0
	v_mul_f32_e32 v135, v135, v138
	global_load_dwordx4 v[144:147], v[126:127], off nt
	v_rcp_f32_e32 v137, v136
	s_nop 0
	v_mul_f32_e32 v134, v134, v137
	v_pk_mul_f32 v[0:1], v[0:1], v[134:135]
	v_and_b32_e32 v135, 0xffff0000, v205
	v_and_b32_e32 v137, 0xffff0000, v201
	v_lshlrev_b32_e32 v134, 16, v205
	v_lshlrev_b32_e32 v136, 16, v201
	global_load_dwordx4 v[124:127], v[124:125], off nt
	v_rcp_f32_e32 v138, v137
	s_nop 0
	v_mul_f32_e32 v135, v135, v138
	global_load_dwordx4 v[128:131], v[128:129], off nt
	v_rcp_f32_e32 v137, v136
	s_nop 0
	v_mul_f32_e32 v134, v134, v137
	v_pk_mul_f32 v[2:3], v[2:3], v[134:135]
	s_waitcnt vmcnt(0)
; __device__ __forceinline__ float bflo(u32 v) { return __uint_as_float(v << 16); }
; __device__ __forceinline__ float bfhi(u32 v) { return __uint_as_float(v & 0xffff0000u); }
; __device__ void phase3(const Params& p) {
;     ...
;       for (int ai = 0; ai < 2; ++ai)
; #pragma unroll
;         for (int bj = 0; bj < 2; ++bj) {
;           asm volatile("" : "+v"(koff));
;           u32x4 sa[4], sb[4];
; #pragma unroll
;           for (int m = 0; m < 4; ++m) {
;             sa[m] = __builtin_nontemporal_load((const u32x4*)(gta + koff + ((ai * 2 + bj) * 4 + m) * 8192));
;             sb[m] = __builtin_nontemporal_load((const u32x4*)(gtb + koff + ((ai * 2 + bj) * 4 + m) * 8192));
;           }
; #pragma unroll
;           for (int m = 0; m < 4; ++m)
; #pragma unroll
;             for (int n = 0; n < 2; ++n) {
;               const u32x4 A4 = sa[m], B4 = sb[m];
;               acc[ai][bj][m][n][0] *= bflo(A4[2 * n]) / bflo(B4[2 * n]);
;               acc[ai][bj][m][n][1] *= bfhi(A4[2 * n]) / bfhi(B4[2 * n]);
;               acc[ai][bj][m][n][2] *= bflo(A4[2 * n + 1]) / bflo(B4[2 * n + 1]);
;               acc[ai][bj][m][n][3] *= bfhi(A4[2 * n + 1]) / bfhi(B4[2 * n + 1]);
	v_and_b32_e32 v135, 0xffff0000, v176
	v_and_b32_e32 v137, 0xffff0000, v180
	v_lshlrev_b32_e32 v134, 16, v176
	v_lshlrev_b32_e32 v136, 16, v180
	v_rcp_f32_e32 v138, v137
	s_nop 0
	v_mul_f32_e32 v135, v135, v138
	s_nop 0
	v_rcp_f32_e32 v137, v136
	s_nop 0
	v_mul_f32_e32 v134, v134, v137
	v_pk_mul_f32 v[4:5], v[4:5], v[134:135]
	v_and_b32_e32 v135, 0xffff0000, v177
	v_and_b32_e32 v137, 0xffff0000, v181
	v_lshlrev_b32_e32 v134, 16, v177
	v_lshlrev_b32_e32 v136, 16, v181
	v_rcp_f32_e32 v138, v137
	s_nop 0
	v_mul_f32_e32 v135, v135, v138
	s_nop 0
	v_rcp_f32_e32 v137, v136
	s_nop 0
	v_mul_f32_e32 v134, v134, v137
	v_pk_mul_f32 v[6:7], v[6:7], v[134:135]
	v_and_b32_e32 v135, 0xffff0000, v140
	v_and_b32_e32 v137, 0xffff0000, v144
	v_lshlrev_b32_e32 v134, 16, v140
	v_lshlrev_b32_e32 v136, 16, v144
	v_rcp_f32_e32 v138, v137
	s_nop 0
	v_mul_f32_e32 v135, v135, v138
	s_nop 0
	v_rcp_f32_e32 v137, v136
	s_nop 0
	v_mul_f32_e32 v134, v134, v137
	v_pk_mul_f32 v[8:9], v[8:9], v[134:135]
	v_and_b32_e32 v135, 0xffff0000, v141
	v_and_b32_e32 v137, 0xffff0000, v145
	v_lshlrev_b32_e32 v134, 16, v141
	v_lshlrev_b32_e32 v136, 16, v145
	v_rcp_f32_e32 v138, v137
	s_nop 0
	v_mul_f32_e32 v135, v135, v138
	s_nop 0
	v_rcp_f32_e32 v137, v136
	s_nop 0
	v_mul_f32_e32 v134, v134, v137
	v_pk_mul_f32 v[10:11], v[10:11], v[134:135]
	v_lshlrev_b32_e32 v134, 16, v126
	v_and_b32_e32 v126, 0xffff0000, v126
	v_lshlrev_b32_e32 v136, 16, v130
	v_and_b32_e32 v130, 0xffff0000, v130
	s_nop 0
	v_rcp_f32_e32 v135, v130
	s_nop 0
	v_mul_f32_e32 v135, v126, v135
	s_nop 0
	v_rcp_f32_e32 v126, v136
	s_nop 0
	v_mul_f32_e32 v134, v134, v126
	v_lshlrev_b32_e32 v126, 16, v127
	v_and_b32_e32 v127, 0xffff0000, v127
	v_lshlrev_b32_e32 v130, 16, v131
	v_and_b32_e32 v131, 0xffff0000, v131
	v_pk_mul_f32 v[12:13], v[12:13], v[134:135]
	s_nop 0
	v_rcp_f32_e32 v134, v131
	s_nop 0
	v_mul_f32_e32 v127, v127, v134
	s_nop 0
	v_rcp_f32_e32 v131, v130
	s_nop 0
	v_mul_f32_e32 v126, v126, v131
	v_pk_mul_f32 v[14:15], v[14:15], v[126:127]
	s_nop 0
	s_nop 0
	v_ashrrev_i32_e32 v167, 31, v166
	v_lshl_add_u64 v[126:127], v[132:133], 0, v[166:167]
	v_add_co_u32_e32 v134, vcc, s67, v126
	v_lshl_add_u64 v[130:131], v[246:247], 0, v[166:167]
	s_nop 0
	v_addc_co_u32_e32 v135, vcc, 0, v127, vcc
	global_load_dwordx4 v[214:217], v[134:135], off nt
	v_add_co_u32_e32 v134, vcc, s67, v130
	s_nop 1
	v_addc_co_u32_e32 v135, vcc, 0, v131, vcc
	global_load_dwordx4 v[218:221], v[134:135], off nt
	v_add_co_u32_e32 v134, vcc, s72, v126
	s_nop 1
	v_addc_co_u32_e32 v135, vcc, 0, v127, vcc
	global_load_dwordx4 v[188:191], v[134:135], off nt
	v_add_co_u32_e32 v134, vcc, s72, v130
	s_nop 1
	v_addc_co_u32_e32 v135, vcc, 0, v131, vcc
	global_load_dwordx4 v[192:195], v[134:135], off nt
	v_add_co_u32_e32 v134, vcc, s81, v126
	s_nop 1
	v_addc_co_u32_e32 v135, vcc, 0, v127, vcc
	global_load_dwordx4 v[158:161], v[134:135], off nt
	v_add_co_u32_e32 v134, vcc, s81, v130
	s_nop 1
	v_addc_co_u32_e32 v135, vcc, 0, v131, vcc
	v_add_co_u32_e32 v126, vcc, s84, v126
	global_load_dwordx4 v[162:165], v[134:135], off nt
	s_nop 0
	v_addc_co_u32_e32 v127, vcc, 0, v127, vcc
	global_load_dwordx4 v[134:137], v[126:127], off nt
	v_add_co_u32_e32 v126, vcc, s84, v130
	s_waitcnt vmcnt(0)
	v_lshlrev_b32_e32 v130, 16, v218
	v_addc_co_u32_e32 v127, vcc, 0, v131, vcc
	global_load_dwordx4 v[138:141], v[126:127], off nt
	v_and_b32_e32 v127, 0xffff0000, v214
	v_and_b32_e32 v131, 0xffff0000, v218
	v_lshlrev_b32_e32 v126, 16, v214
	v_rcp_f32_e32 v144, v131
	s_nop 0
	v_mul_f32_e32 v127, v127, v144
	s_nop 0
	v_rcp_f32_e32 v131, v130
	s_nop 0
	v_mul_f32_e32 v126, v126, v131
	v_pk_mul_f32 v[20:21], v[20:21], v[126:127]
	v_and_b32_e32 v127, 0xffff0000, v215
	v_and_b32_e32 v131, 0xffff0000, v219
	v_lshlrev_b32_e32 v126, 16, v215
	v_lshlrev_b32_e32 v130, 16, v219
	v_rcp_f32_e32 v144, v131
	s_nop 0
	v_mul_f32_e32 v127, v127, v144
	s_nop 0
	v_rcp_f32_e32 v131, v130
	s_nop 0
	v_mul_f32_e32 v126, v126, v131
	v_pk_mul_f32 v[22:23], v[22:23], v[126:127]
	v_and_b32_e32 v127, 0xffff0000, v190
	v_and_b32_e32 v131, 0xffff0000, v194
	v_lshlrev_b32_e32 v126, 16, v190
	v_lshlrev_b32_e32 v130, 16, v194
	v_rcp_f32_e32 v144, v131
	s_nop 0
	v_mul_f32_e32 v127, v127, v144
	s_nop 0
	v_rcp_f32_e32 v131, v130
	s_nop 0
	v_mul_f32_e32 v126, v126, v131
	v_pk_mul_f32 v[28:29], v[28:29], v[126:127]
	v_and_b32_e32 v127, 0xffff0000, v191
	v_and_b32_e32 v131, 0xffff0000, v195
	v_lshlrev_b32_e32 v126, 16, v191
	v_lshlrev_b32_e32 v130, 16, v195
	v_rcp_f32_e32 v144, v131
	s_nop 0
	v_mul_f32_e32 v127, v127, v144
	s_nop 0
	v_rcp_f32_e32 v131, v130
	s_nop 0
	v_mul_f32_e32 v126, v126, v131
	v_pk_mul_f32 v[30:31], v[30:31], v[126:127]
	v_and_b32_e32 v127, 0xffff0000, v158
	v_and_b32_e32 v131, 0xffff0000, v162
	v_lshlrev_b32_e32 v126, 16, v158
	v_lshlrev_b32_e32 v130, 16, v162
	v_rcp_f32_e32 v144, v131
	s_nop 0
	v_mul_f32_e32 v127, v127, v144
	s_nop 0
	v_rcp_f32_e32 v131, v130
	s_nop 0
	v_mul_f32_e32 v126, v126, v131
	v_pk_mul_f32 v[36:37], v[36:37], v[126:127]
	v_and_b32_e32 v127, 0xffff0000, v159
	v_and_b32_e32 v131, 0xffff0000, v163
	v_lshlrev_b32_e32 v126, 16, v159
	v_lshlrev_b32_e32 v130, 16, v163
	v_rcp_f32_e32 v144, v131
	s_nop 0
	v_mul_f32_e32 v127, v127, v144
	s_nop 0
	v_rcp_f32_e32 v131, v130
	s_nop 0
	v_mul_f32_e32 v126, v126, v131
	v_pk_mul_f32 v[38:39], v[38:39], v[126:127]
	v_and_b32_e32 v127, 0xffff0000, v136
	s_waitcnt vmcnt(0)
; __device__ __forceinline__ float bflo(u32 v) { return __uint_as_float(v << 16); }
; __device__ __forceinline__ float bfhi(u32 v) { return __uint_as_float(v & 0xffff0000u); }
; __device__ void phase3(const Params& p) {
;     ...
;       for (int ai = 0; ai < 2; ++ai)
; #pragma unroll
;         for (int bj = 0; bj < 2; ++bj) {
;           asm volatile("" : "+v"(koff));
;           u32x4 sa[4], sb[4];
; #pragma unroll
;           for (int m = 0; m < 4; ++m) {
;             sa[m] = __builtin_nontemporal_load((const u32x4*)(gta + koff + ((ai * 2 + bj) * 4 + m) * 8192));
;             sb[m] = __builtin_nontemporal_load((const u32x4*)(gtb + koff + ((ai * 2 + bj) * 4 + m) * 8192));
;           }
; #pragma unroll
;           for (int m = 0; m < 4; ++m)
; #pragma unroll
;             for (int n = 0; n < 2; ++n) {
;               const u32x4 A4 = sa[m], B4 = sb[m];
;               acc[ai][bj][m][n][0] *= bflo(A4[2 * n]) / bflo(B4[2 * n]);
;               acc[ai][bj][m][n][1] *= bfhi(A4[2 * n]) / bfhi(B4[2 * n]);
;               acc[ai][bj][m][n][2] *= bflo(A4[2 * n + 1]) / bflo(B4[2 * n + 1]);
;               acc[ai][bj][m][n][3] *= bfhi(A4[2 * n + 1]) / bfhi(B4[2 * n + 1]);
	v_and_b32_e32 v131, 0xffff0000, v140
	v_lshlrev_b32_e32 v126, 16, v136
	v_lshlrev_b32_e32 v130, 16, v140
	s_nop 0
	v_rcp_f32_e32 v136, v131
	s_nop 0
	v_mul_f32_e32 v127, v127, v136
	s_nop 0
	v_rcp_f32_e32 v131, v130
	s_nop 0
	v_mul_f32_e32 v126, v126, v131
	v_pk_mul_f32 v[44:45], v[44:45], v[126:127]
	v_and_b32_e32 v127, 0xffff0000, v137
	v_and_b32_e32 v131, 0xffff0000, v141
	v_lshlrev_b32_e32 v126, 16, v137
	v_lshlrev_b32_e32 v130, 16, v141
	v_rcp_f32_e32 v136, v131
	s_nop 0
	v_mul_f32_e32 v127, v127, v136
	s_nop 0
	v_rcp_f32_e32 v131, v130
	s_nop 0
	v_mul_f32_e32 v126, v126, v131
	v_pk_mul_f32 v[46:47], v[46:47], v[126:127]
	s_nop 0
	s_nop 0
	v_ashrrev_i32_e32 v167, 31, v166
	v_lshl_add_u64 v[126:127], v[132:133], 0, v[166:167]
	v_add_co_u32_e32 v136, vcc, s75, v126
	v_lshl_add_u64 v[130:131], v[246:247], 0, v[166:167]
	s_nop 0
	v_addc_co_u32_e32 v137, vcc, 0, v127, vcc
	global_load_dwordx4 v[228:231], v[136:137], off nt
	v_add_co_u32_e32 v136, vcc, s75, v130
	s_nop 1
	v_addc_co_u32_e32 v137, vcc, 0, v131, vcc
	global_load_dwordx4 v[232:235], v[136:137], off nt
	v_add_co_u32_e32 v136, vcc, s85, v126
	s_nop 1
	v_addc_co_u32_e32 v137, vcc, 0, v127, vcc
	global_load_dwordx4 v[208:211], v[136:137], off nt
	v_add_co_u32_e32 v136, vcc, s85, v130
	s_nop 1
	v_addc_co_u32_e32 v137, vcc, 0, v131, vcc
	global_load_dwordx4 v[212:215], v[136:137], off nt
	v_add_co_u32_e32 v136, vcc, s80, v126
	s_nop 1
	v_addc_co_u32_e32 v137, vcc, 0, v127, vcc
	global_load_dwordx4 v[180:183], v[136:137], off nt
	v_add_co_u32_e32 v136, vcc, s80, v130
	s_nop 1
	v_addc_co_u32_e32 v137, vcc, 0, v131, vcc
	v_add_co_u32_e32 v126, vcc, s86, v126
	global_load_dwordx4 v[184:187], v[136:137], off nt
	s_nop 0
	v_addc_co_u32_e32 v127, vcc, 0, v127, vcc
	global_load_dwordx4 v[152:155], v[126:127], off nt
	v_add_co_u32_e32 v126, vcc, s86, v130
	s_waitcnt vmcnt(0)
	v_lshlrev_b32_e32 v130, 16, v232
	v_addc_co_u32_e32 v127, vcc, 0, v131, vcc
	global_load_dwordx4 v[156:159], v[126:127], off nt
	v_and_b32_e32 v127, 0xffff0000, v228
	v_and_b32_e32 v131, 0xffff0000, v232
	v_lshlrev_b32_e32 v126, 16, v228
	v_rcp_f32_e32 v136, v131
	s_nop 0
	v_mul_f32_e32 v127, v127, v136
	s_nop 0
	v_rcp_f32_e32 v131, v130
	s_nop 0
	v_mul_f32_e32 v126, v126, v131
	v_pk_mul_f32 v[52:53], v[52:53], v[126:127]
	v_and_b32_e32 v127, 0xffff0000, v229
	v_and_b32_e32 v131, 0xffff0000, v233
	v_lshlrev_b32_e32 v126, 16, v229
	v_lshlrev_b32_e32 v130, 16, v233
	v_rcp_f32_e32 v136, v131
	s_nop 0
	v_mul_f32_e32 v127, v127, v136
	s_nop 0
	v_rcp_f32_e32 v131, v130
	s_nop 0
	v_mul_f32_e32 v126, v126, v131
	v_pk_mul_f32 v[54:55], v[54:55], v[126:127]
	v_and_b32_e32 v127, 0xffff0000, v210
	v_and_b32_e32 v131, 0xffff0000, v214
	v_lshlrev_b32_e32 v126, 16, v210
	v_lshlrev_b32_e32 v130, 16, v214
	v_rcp_f32_e32 v136, v131
	s_nop 0
	v_mul_f32_e32 v127, v127, v136
	s_nop 0
	v_rcp_f32_e32 v131, v130
	s_nop 0
	v_mul_f32_e32 v126, v126, v131
	v_pk_mul_f32 v[60:61], v[60:61], v[126:127]
	v_and_b32_e32 v127, 0xffff0000, v211
	v_and_b32_e32 v131, 0xffff0000, v215
	v_lshlrev_b32_e32 v126, 16, v211
	v_lshlrev_b32_e32 v130, 16, v215
	v_rcp_f32_e32 v136, v131
	s_nop 0
	v_mul_f32_e32 v127, v127, v136
	s_nop 0
	v_rcp_f32_e32 v131, v130
	s_nop 0
	v_mul_f32_e32 v126, v126, v131
	v_pk_mul_f32 v[62:63], v[62:63], v[126:127]
	v_and_b32_e32 v127, 0xffff0000, v180
	v_and_b32_e32 v131, 0xffff0000, v184
	v_lshlrev_b32_e32 v126, 16, v180
	v_lshlrev_b32_e32 v130, 16, v184
	v_rcp_f32_e32 v136, v131
	s_nop 0
	v_mul_f32_e32 v127, v127, v136
	s_nop 0
	v_rcp_f32_e32 v131, v130
	s_nop 0
	v_mul_f32_e32 v126, v126, v131
	v_pk_mul_f32 v[68:69], v[68:69], v[126:127]
	v_and_b32_e32 v127, 0xffff0000, v181
	v_and_b32_e32 v131, 0xffff0000, v185
	v_lshlrev_b32_e32 v126, 16, v181
	v_lshlrev_b32_e32 v130, 16, v185
	v_rcp_f32_e32 v136, v131
	s_nop 0
	v_mul_f32_e32 v127, v127, v136
	s_nop 0
	v_rcp_f32_e32 v131, v130
	s_nop 0
	v_mul_f32_e32 v126, v126, v131
	v_pk_mul_f32 v[70:71], v[70:71], v[126:127]
	v_and_b32_e32 v127, 0xffff0000, v154
	s_waitcnt vmcnt(0)
	v_and_b32_e32 v131, 0xffff0000, v158
	v_lshlrev_b32_e32 v126, 16, v154
	v_lshlrev_b32_e32 v130, 16, v158
	v_rcp_f32_e32 v136, v131
	s_nop 0
	v_mul_f32_e32 v127, v127, v136
	s_nop 0
	v_rcp_f32_e32 v131, v130
	s_nop 0
	v_mul_f32_e32 v126, v126, v131
	v_pk_mul_f32 v[76:77], v[76:77], v[126:127]
	v_and_b32_e32 v127, 0xffff0000, v155
	v_and_b32_e32 v131, 0xffff0000, v159
	v_lshlrev_b32_e32 v126, 16, v155
	v_lshlrev_b32_e32 v130, 16, v159
	v_rcp_f32_e32 v136, v131
	s_nop 0
	v_mul_f32_e32 v127, v127, v136
	s_nop 0
	v_rcp_f32_e32 v131, v130
	s_nop 0
	v_mul_f32_e32 v126, v126, v131
	v_pk_mul_f32 v[78:79], v[78:79], v[126:127]
	s_nop 0
	s_nop 0
	v_ashrrev_i32_e32 v167, 31, v166
	v_lshl_add_u64 v[126:127], v[132:133], 0, v[166:167]
	v_add_co_u32_e32 v132, vcc, s65, v126
	v_lshl_add_u64 v[130:131], v[246:247], 0, v[166:167]
	s_nop 0
	v_addc_co_u32_e32 v133, vcc, 0, v127, vcc
	global_load_dwordx4 v[236:239], v[132:133], off nt
	v_add_co_u32_e32 v132, vcc, s65, v130
	s_nop 1
	v_addc_co_u32_e32 v133, vcc, 0, v131, vcc
	global_load_dwordx4 v[240:243], v[132:133], off nt
	v_add_co_u32_e32 v132, vcc, s66, v126
	s_nop 1
	v_addc_co_u32_e32 v133, vcc, 0, v127, vcc
	global_load_dwordx4 v[222:225], v[132:133], off nt
	v_add_co_u32_e32 v132, vcc, s66, v130
	s_nop 1
	v_addc_co_u32_e32 v133, vcc, 0, v131, vcc
	global_load_dwordx4 v[226:229], v[132:133], off nt
	v_add_co_u32_e32 v132, vcc, s73, v126
	s_nop 1
	v_addc_co_u32_e32 v133, vcc, 0, v127, vcc
	global_load_dwordx4 v[194:197], v[132:133], off nt
	v_add_co_u32_e32 v132, vcc, s73, v130
	s_nop 1
	v_addc_co_u32_e32 v133, vcc, 0, v131, vcc
	v_add_co_u32_e32 v126, vcc, s74, v126
	global_load_dwordx4 v[198:201], v[132:133], off nt
	s_nop 0
	v_addc_co_u32_e32 v127, vcc, 0, v127, vcc
	global_load_dwordx4 v[166:169], v[126:127], off nt
	v_add_co_u32_e32 v126, vcc, s74, v130
	s_waitcnt vmcnt(0)
; __device__ __forceinline__ float bflo(u32 v) { return __uint_as_float(v << 16); }
; __device__ __forceinline__ float bfhi(u32 v) { return __uint_as_float(v & 0xffff0000u); }
; #define WAIT_V(n) asm volatile("s_waitcnt vmcnt(" #n ")" ::: "memory")
; #define BAR __builtin_amdgcn_s_barrier()
; __device__ __forceinline__ void gemm_main(const u16* __restrict__ A, const u16* __restrict__ Bt, const int K, const int Klen,
;                                           const int brow, const int bcol, f32x4 (&acc)[2][2][4][2]) {
;     ...
;   if (wr == 1) BAR;
;   WAIT_V(4); BAR;
; __device__ void phase3(const Params& p) {
;     ...
;           for (int m = 0; m < 4; ++m)
; #pragma unroll
;             for (int n = 0; n < 2; ++n) {
;               const u32x4 A4 = sa[m], B4 = sb[m];
;               acc[ai][bj][m][n][0] *= bflo(A4[2 * n]) / bflo(B4[2 * n]);
;               acc[ai][bj][m][n][1] *= bfhi(A4[2 * n]) / bfhi(B4[2 * n]);
;               acc[ai][bj][m][n][2] *= bflo(A4[2 * n + 1]) / bflo(B4[2 * n + 1]);
;               acc[ai][bj][m][n][3] *= bfhi(A4[2 * n + 1]) / bfhi(B4[2 * n + 1]);
	v_lshlrev_b32_e32 v130, 16, v240
	v_addc_co_u32_e32 v127, vcc, 0, v131, vcc
	global_load_dwordx4 v[170:173], v[126:127], off nt
	v_and_b32_e32 v127, 0xffff0000, v236
	v_and_b32_e32 v131, 0xffff0000, v240
	v_lshlrev_b32_e32 v126, 16, v236
	v_rcp_f32_e32 v132, v131
	s_nop 0
	v_mul_f32_e32 v127, v127, v132
	s_nop 0
	v_rcp_f32_e32 v131, v130
	s_nop 0
	v_mul_f32_e32 v126, v126, v131
	v_pk_mul_f32 v[88:89], v[88:89], v[126:127]
	v_and_b32_e32 v127, 0xffff0000, v237
	v_and_b32_e32 v131, 0xffff0000, v241
	v_lshlrev_b32_e32 v126, 16, v237
	v_lshlrev_b32_e32 v130, 16, v241
	v_rcp_f32_e32 v132, v131
	s_nop 0
	v_mul_f32_e32 v127, v127, v132
	s_nop 0
	v_rcp_f32_e32 v131, v130
	s_nop 0
	v_mul_f32_e32 v126, v126, v131
	v_pk_mul_f32 v[90:91], v[90:91], v[126:127]
	v_and_b32_e32 v127, 0xffff0000, v224
	v_and_b32_e32 v131, 0xffff0000, v228
	v_lshlrev_b32_e32 v126, 16, v224
	v_lshlrev_b32_e32 v130, 16, v228
	v_rcp_f32_e32 v132, v131
	s_nop 0
	v_mul_f32_e32 v127, v127, v132
	s_nop 0
	v_rcp_f32_e32 v131, v130
	s_nop 0
	v_mul_f32_e32 v126, v126, v131
	v_pk_mul_f32 v[96:97], v[96:97], v[126:127]
	v_and_b32_e32 v127, 0xffff0000, v225
	v_and_b32_e32 v131, 0xffff0000, v229
	v_lshlrev_b32_e32 v126, 16, v225
	v_lshlrev_b32_e32 v130, 16, v229
	v_rcp_f32_e32 v132, v131
	s_nop 0
	v_mul_f32_e32 v127, v127, v132
	s_nop 0
	v_rcp_f32_e32 v131, v130
	s_nop 0
	v_mul_f32_e32 v126, v126, v131
	v_pk_mul_f32 v[98:99], v[98:99], v[126:127]
	v_and_b32_e32 v127, 0xffff0000, v194
	v_and_b32_e32 v131, 0xffff0000, v198
	v_lshlrev_b32_e32 v126, 16, v194
	v_lshlrev_b32_e32 v130, 16, v198
	v_rcp_f32_e32 v132, v131
	s_nop 0
	v_mul_f32_e32 v127, v127, v132
	s_nop 0
	v_rcp_f32_e32 v131, v130
	s_nop 0
	v_mul_f32_e32 v126, v126, v131
	v_pk_mul_f32 v[104:105], v[104:105], v[126:127]
	v_and_b32_e32 v127, 0xffff0000, v195
	v_and_b32_e32 v131, 0xffff0000, v199
	v_lshlrev_b32_e32 v126, 16, v195
	v_lshlrev_b32_e32 v130, 16, v199
	v_rcp_f32_e32 v132, v131
	s_nop 0
	v_mul_f32_e32 v127, v127, v132
	s_nop 0
	v_rcp_f32_e32 v131, v130
	s_nop 0
	v_mul_f32_e32 v126, v126, v131
	v_pk_mul_f32 v[106:107], v[106:107], v[126:127]
	v_and_b32_e32 v127, 0xffff0000, v168
	s_waitcnt vmcnt(0)
	v_and_b32_e32 v131, 0xffff0000, v172
	v_lshlrev_b32_e32 v126, 16, v168
	v_lshlrev_b32_e32 v130, 16, v172
	v_rcp_f32_e32 v132, v131
	s_nop 0
	v_mul_f32_e32 v127, v127, v132
	s_nop 0
	v_rcp_f32_e32 v131, v130
	s_nop 0
	v_mul_f32_e32 v126, v126, v131
	v_pk_mul_f32 v[112:113], v[112:113], v[126:127]
	v_and_b32_e32 v127, 0xffff0000, v169
	v_and_b32_e32 v131, 0xffff0000, v173
	v_lshlrev_b32_e32 v126, 16, v169
	v_lshlrev_b32_e32 v130, 16, v173
	v_rcp_f32_e32 v132, v131
	s_nop 0
	v_mul_f32_e32 v127, v127, v132
	v_mov_b32_e32 v140, v248
	v_rcp_f32_e32 v131, v130
	s_nop 0
	v_mul_f32_e32 v126, v126, v131
	v_pk_mul_f32 v[114:115], v[114:115], v[126:127]
	s_nop 0
	s_nop 0
	v_ashrrev_i32_e32 v136, 8, v140
	v_cmp_eq_u32_e32 vcc, 1, v136
	s_and_saveexec_b64 s[62:63], vcc
	s_cbranch_execz .LBB0_564
	s_barrier
.LBB0_564:
	s_or_b64 exec, exec, s[62:63]
	v_and_b32_e32 v127, 0xffff0000, v206
	v_and_b32_e32 v131, 0xffff0000, v202
	v_lshlrev_b32_e32 v126, 16, v206
	v_lshlrev_b32_e32 v130, 16, v202
	s_lshl_b32 s5, s11, 1
	v_rcp_f32_e32 v132, v131
	s_nop 0
	v_mul_f32_e32 v127, v127, v132
	s_waitcnt vmcnt(4)
	s_barrier
	s_lshl_b64 s[46:47], s[46:47], 12
	v_rcp_f32_e32 v131, v130
	s_nop 0
	v_mul_f32_e32 v126, v126, v131
	v_pk_mul_f32 v[130:131], v[148:149], v[126:127]
	v_and_b32_e32 v127, 0xffff0000, v207
	v_and_b32_e32 v133, 0xffff0000, v203
	v_lshlrev_b32_e32 v126, 16, v207
	v_lshlrev_b32_e32 v132, 16, v203
	s_add_u32 s46, s68, s46
	v_rcp_f32_e32 v137, v133
	s_nop 0
	v_mul_f32_e32 v127, v127, v137
	s_addc_u32 s47, s69, s47
	v_rcp_f32_e32 v133, v132
	s_nop 0
	v_mul_f32_e32 v126, v126, v133
	v_pk_mul_f32 v[132:133], v[150:151], v[126:127]
	v_and_b32_e32 v127, 0xffff0000, v174
	v_and_b32_e32 v141, 0xffff0000, v178
	v_lshlrev_b32_e32 v126, 16, v174
	v_lshlrev_b32_e32 v137, 16, v178
	v_rcp_f32_e32 v144, v141
	s_nop 0
	v_mul_f32_e32 v127, v127, v144
	s_nop 0
	v_rcp_f32_e32 v141, v137
	s_nop 0
	v_mul_f32_e32 v126, v126, v141
	v_pk_mul_f32 v[120:121], v[120:121], v[126:127]
	v_and_b32_e32 v127, 0xffff0000, v175
	v_and_b32_e32 v141, 0xffff0000, v179
	v_lshlrev_b32_e32 v126, 16, v175
	v_lshlrev_b32_e32 v137, 16, v179
	v_rcp_f32_e32 v144, v141
	s_nop 0
	v_mul_f32_e32 v127, v127, v144
	s_nop 0
	v_rcp_f32_e32 v141, v137
	s_nop 0
	v_mul_f32_e32 v126, v126, v141
	v_pk_mul_f32 v[122:123], v[122:123], v[126:127]
	v_and_b32_e32 v127, 0xffff0000, v142
	v_and_b32_e32 v141, 0xffff0000, v146
	v_lshlrev_b32_e32 v126, 16, v142
	v_lshlrev_b32_e32 v137, 16, v146
	v_and_b32_e32 v149, 48, v140
	v_rcp_f32_e32 v142, v141
	s_nop 0
	v_mul_f32_e32 v127, v127, v142
	s_nop 0
	v_rcp_f32_e32 v141, v137
	s_nop 0
	v_mul_f32_e32 v126, v126, v141
	v_pk_mul_f32 v[116:117], v[116:117], v[126:127]
	v_and_b32_e32 v127, 0xffff0000, v143
	v_and_b32_e32 v141, 0xffff0000, v147
	v_lshlrev_b32_e32 v126, 16, v143
	v_lshlrev_b32_e32 v137, 16, v147
	v_rcp_f32_e32 v142, v141
	s_nop 0
	v_mul_f32_e32 v127, v127, v142
	s_nop 0
	v_rcp_f32_e32 v141, v137
	s_nop 0
	v_mul_f32_e32 v126, v126, v141
	v_pk_mul_f32 v[118:119], v[118:119], v[126:127]
	v_lshlrev_b32_e32 v126, 16, v124
	v_and_b32_e32 v124, 0xffff0000, v124
	v_and_b32_e32 v127, 0xffff0000, v128
	v_lshlrev_b32_e32 v137, 16, v128
	s_nop 0
	v_rcp_f32_e32 v128, v127
	s_nop 0
	v_mul_f32_e32 v127, v124, v128
	s_nop 0
	v_rcp_f32_e32 v124, v137
	s_nop 0
	v_mul_f32_e32 v126, v126, v124
	v_pk_mul_f32 v[108:109], v[108:109], v[126:127]
	v_lshlrev_b32_e32 v124, 16, v125
	v_and_b32_e32 v125, 0xffff0000, v125
	v_and_b32_e32 v127, 0xffff0000, v129
; __device__ __forceinline__ float bflo(u32 v) { return __uint_as_float(v << 16); }
; __device__ __forceinline__ float bfhi(u32 v) { return __uint_as_float(v & 0xffff0000u); }
; __device__ void phase3(const Params& p) {
;     ...
;           for (int m = 0; m < 4; ++m)
; #pragma unroll
;             for (int n = 0; n < 2; ++n) {
;               const u32x4 A4 = sa[m], B4 = sb[m];
;               acc[ai][bj][m][n][0] *= bflo(A4[2 * n]) / bflo(B4[2 * n]);
;               acc[ai][bj][m][n][1] *= bfhi(A4[2 * n]) / bfhi(B4[2 * n]);
;               acc[ai][bj][m][n][2] *= bflo(A4[2 * n + 1]) / bflo(B4[2 * n + 1]);
;               acc[ai][bj][m][n][3] *= bfhi(A4[2 * n + 1]) / bfhi(B4[2 * n + 1]);
	v_lshlrev_b32_e32 v126, 16, v129
	s_nop 0
	v_rcp_f32_e32 v128, v127
	s_nop 0
	v_mul_f32_e32 v125, v125, v128
	s_nop 0
	v_rcp_f32_e32 v127, v126
	s_nop 0
	v_mul_f32_e32 v124, v124, v127
	v_pk_mul_f32 v[110:111], v[110:111], v[124:125]
	v_and_b32_e32 v125, 0xffff0000, v216
	v_and_b32_e32 v127, 0xffff0000, v220
	v_lshlrev_b32_e32 v124, 16, v216
	v_lshlrev_b32_e32 v126, 16, v220
	v_rcp_f32_e32 v128, v127
	s_nop 0
	v_mul_f32_e32 v125, v125, v128
	s_nop 0
	v_rcp_f32_e32 v127, v126
	s_nop 0
	v_mul_f32_e32 v124, v124, v127
	v_pk_mul_f32 v[100:101], v[100:101], v[124:125]
	v_and_b32_e32 v125, 0xffff0000, v217
	v_and_b32_e32 v127, 0xffff0000, v221
	v_lshlrev_b32_e32 v124, 16, v217
	v_lshlrev_b32_e32 v126, 16, v221
	v_rcp_f32_e32 v128, v127
	s_nop 0
	v_mul_f32_e32 v125, v125, v128
	s_nop 0
	v_rcp_f32_e32 v127, v126
	s_nop 0
	v_mul_f32_e32 v124, v124, v127
	v_pk_mul_f32 v[102:103], v[102:103], v[124:125]
	v_and_b32_e32 v125, 0xffff0000, v188
	v_and_b32_e32 v127, 0xffff0000, v192
	v_lshlrev_b32_e32 v124, 16, v188
	v_lshlrev_b32_e32 v126, 16, v192
	v_rcp_f32_e32 v128, v127
	s_nop 0
	v_mul_f32_e32 v125, v125, v128
	s_nop 0
	v_rcp_f32_e32 v127, v126
	s_nop 0
	v_mul_f32_e32 v124, v124, v127
	v_pk_mul_f32 v[92:93], v[92:93], v[124:125]
	v_and_b32_e32 v125, 0xffff0000, v189
	v_and_b32_e32 v127, 0xffff0000, v193
	v_lshlrev_b32_e32 v124, 16, v189
	v_lshlrev_b32_e32 v126, 16, v193
	v_rcp_f32_e32 v128, v127
	s_nop 0
	v_mul_f32_e32 v125, v125, v128
	s_nop 0
	v_rcp_f32_e32 v127, v126
	s_nop 0
	v_mul_f32_e32 v124, v124, v127
	v_pk_mul_f32 v[94:95], v[94:95], v[124:125]
	v_and_b32_e32 v125, 0xffff0000, v160
	v_and_b32_e32 v127, 0xffff0000, v164
	v_lshlrev_b32_e32 v124, 16, v160
	v_lshlrev_b32_e32 v126, 16, v164
	v_lshlrev_b32_e32 v164, 13, v136
	v_rcp_f32_e32 v128, v127
	s_nop 0
	v_mul_f32_e32 v125, v125, v128
	s_nop 0
	v_rcp_f32_e32 v127, v126
	s_nop 0
	v_mul_f32_e32 v124, v124, v127
	v_pk_mul_f32 v[84:85], v[84:85], v[124:125]
	v_and_b32_e32 v125, 0xffff0000, v161
	v_and_b32_e32 v127, 0xffff0000, v165
	v_lshlrev_b32_e32 v124, 16, v161
	v_lshlrev_b32_e32 v126, 16, v165
	v_or_b32_e32 v165, 0x800, v164
	v_rcp_f32_e32 v128, v127
	s_nop 0
	v_mul_f32_e32 v125, v125, v128
	s_nop 0
	v_rcp_f32_e32 v127, v126
	s_nop 0
	v_mul_f32_e32 v124, v124, v127
	v_pk_mul_f32 v[86:87], v[86:87], v[124:125]
	v_and_b32_e32 v125, 0xffff0000, v134
	v_and_b32_e32 v127, 0xffff0000, v138
	v_lshlrev_b32_e32 v124, 16, v134
	v_lshlrev_b32_e32 v126, 16, v138
	v_lshlrev_b32_e32 v141, 4, v140
	v_rcp_f32_e32 v128, v127
	s_nop 0
	v_mul_f32_e32 v125, v125, v128
	v_add_u32_e32 v142, 0x2000, v141
	v_add_u32_e32 v143, 0x18000, v141
	v_add_u32_e32 v144, 0x1a000, v141
	v_rcp_f32_e32 v127, v126
	s_nop 0
	v_mul_f32_e32 v124, v124, v127
	v_pk_mul_f32 v[80:81], v[80:81], v[124:125]
	v_and_b32_e32 v125, 0xffff0000, v135
	v_and_b32_e32 v127, 0xffff0000, v139
	v_lshlrev_b32_e32 v124, 16, v135
	v_lshlrev_b32_e32 v126, 16, v139
	v_readfirstlane_b32 s11, v143
	v_rcp_f32_e32 v128, v127
	s_nop 0
	v_mul_f32_e32 v125, v125, v128
	s_mov_b32 m0, s11
	v_readfirstlane_b32 s11, v144
	v_add_u32_e32 v145, 0x8000, v141
	v_rcp_f32_e32 v127, v126
	s_nop 0
	v_mul_f32_e32 v124, v124, v127
	v_pk_mul_f32 v[82:83], v[82:83], v[124:125]
	v_and_b32_e32 v125, 0xffff0000, v230
	v_and_b32_e32 v127, 0xffff0000, v234
	v_lshlrev_b32_e32 v124, 16, v230
	v_lshlrev_b32_e32 v126, 16, v234
	v_add_u32_e32 v146, 0xa000, v141
	v_rcp_f32_e32 v128, v127
	s_nop 0
	v_mul_f32_e32 v125, v125, v128
	v_add_u32_e32 v147, 0x1c000, v141
	v_add_u32_e32 v148, 0x1e000, v141
	v_rcp_f32_e32 v127, v126
	s_nop 0
	v_mul_f32_e32 v124, v124, v127
	v_pk_mul_f32 v[72:73], v[72:73], v[124:125]
	v_and_b32_e32 v125, 0xffff0000, v231
	v_and_b32_e32 v127, 0xffff0000, v235
	v_lshlrev_b32_e32 v124, 16, v231
	v_lshlrev_b32_e32 v126, 16, v235
	v_rcp_f32_e32 v128, v127
	s_nop 0
	v_mul_f32_e32 v125, v125, v128
	s_nop 0
	v_rcp_f32_e32 v127, v126
	s_nop 0
	v_mul_f32_e32 v124, v124, v127
	v_pk_mul_f32 v[74:75], v[74:75], v[124:125]
	v_and_b32_e32 v125, 0xffff0000, v208
	v_and_b32_e32 v127, 0xffff0000, v212
	v_lshlrev_b32_e32 v124, 16, v208
	v_lshlrev_b32_e32 v126, 16, v212
	v_rcp_f32_e32 v128, v127
	s_nop 0
	v_mul_f32_e32 v125, v125, v128
	s_nop 0
	v_rcp_f32_e32 v127, v126
	s_nop 0
	v_mul_f32_e32 v124, v124, v127
	v_pk_mul_f32 v[64:65], v[64:65], v[124:125]
	v_and_b32_e32 v125, 0xffff0000, v209
	v_and_b32_e32 v127, 0xffff0000, v213
	v_lshlrev_b32_e32 v124, 16, v209
	v_lshlrev_b32_e32 v126, 16, v213
	v_rcp_f32_e32 v128, v127
	s_nop 0
	v_mul_f32_e32 v125, v125, v128
	s_nop 0
	v_rcp_f32_e32 v127, v126
	s_nop 0
	v_mul_f32_e32 v124, v124, v127
	v_pk_mul_f32 v[66:67], v[66:67], v[124:125]
	v_and_b32_e32 v125, 0xffff0000, v182
	v_and_b32_e32 v127, 0xffff0000, v186
	v_lshlrev_b32_e32 v124, 16, v182
	v_lshlrev_b32_e32 v126, 16, v186
	v_rcp_f32_e32 v128, v127
	s_nop 0
	v_mul_f32_e32 v125, v125, v128
	s_nop 0
	v_rcp_f32_e32 v127, v126
	s_nop 0
	v_mul_f32_e32 v124, v124, v127
	v_pk_mul_f32 v[56:57], v[56:57], v[124:125]
	v_and_b32_e32 v125, 0xffff0000, v183
	v_and_b32_e32 v127, 0xffff0000, v187
	v_lshlrev_b32_e32 v124, 16, v183
	v_lshlrev_b32_e32 v126, 16, v187
	v_rcp_f32_e32 v128, v127
	s_nop 0
	v_mul_f32_e32 v125, v125, v128
	s_nop 0
	v_rcp_f32_e32 v127, v126
	s_nop 0
	v_mul_f32_e32 v124, v124, v127
	v_pk_mul_f32 v[58:59], v[58:59], v[124:125]
	v_and_b32_e32 v125, 0xffff0000, v152
	v_and_b32_e32 v127, 0xffff0000, v156
	v_lshlrev_b32_e32 v124, 16, v152
	v_lshlrev_b32_e32 v126, 16, v156
	v_rcp_f32_e32 v128, v127
	s_nop 0
	v_mul_f32_e32 v125, v125, v128
	s_nop 0
	v_rcp_f32_e32 v127, v126
	s_nop 0
	v_mul_f32_e32 v124, v124, v127
	v_pk_mul_f32 v[48:49], v[48:49], v[124:125]
	v_and_b32_e32 v125, 0xffff0000, v153
; __device__ __forceinline__ float bflo(u32 v) { return __uint_as_float(v << 16); }
; __device__ __forceinline__ float bfhi(u32 v) { return __uint_as_float(v & 0xffff0000u); }
; __device__ __forceinline__ void gemm_main(const u16* __restrict__ A, const u16* __restrict__ Bt, const int K, const int Klen,
;                                           const int brow, const int bcol, f32x4 (&acc)[2][2][4][2]) {
;     ...
;   const int wid = tid >> 6, lane = tid & 63, wr = wid >> 2, wc = wid & 3, fr = lane & 15, fq = lane >> 4;
;   const int tid16 = tid * 16;
;   int goff0, goff1;
;   { int R, C; stage_rc(tid16, R, C); goff0 = R * K + C; stage_rc(tid16 + 8192, R, C); goff1 = R * K + C; }
; __device__ void phase3(const Params& p) {
;     ...
;           for (int m = 0; m < 4; ++m)
; #pragma unroll
;             for (int n = 0; n < 2; ++n) {
;               const u32x4 A4 = sa[m], B4 = sb[m];
;               acc[ai][bj][m][n][0] *= bflo(A4[2 * n]) / bflo(B4[2 * n]);
;               acc[ai][bj][m][n][1] *= bfhi(A4[2 * n]) / bfhi(B4[2 * n]);
;               acc[ai][bj][m][n][2] *= bflo(A4[2 * n + 1]) / bflo(B4[2 * n + 1]);
;               acc[ai][bj][m][n][3] *= bfhi(A4[2 * n + 1]) / bfhi(B4[2 * n + 1]);
	v_and_b32_e32 v127, 0xffff0000, v157
	v_lshlrev_b32_e32 v124, 16, v153
	v_lshlrev_b32_e32 v126, 16, v157
	v_rcp_f32_e32 v128, v127
	s_nop 0
	v_mul_f32_e32 v125, v125, v128
	s_nop 0
	v_rcp_f32_e32 v127, v126
	s_nop 0
	v_mul_f32_e32 v124, v124, v127
	v_pk_mul_f32 v[50:51], v[50:51], v[124:125]
	v_and_b32_e32 v125, 0xffff0000, v238
	v_and_b32_e32 v127, 0xffff0000, v242
	v_lshlrev_b32_e32 v124, 16, v238
	v_lshlrev_b32_e32 v126, 16, v242
	v_rcp_f32_e32 v128, v127
	s_nop 0
	v_mul_f32_e32 v125, v125, v128
	s_nop 0
	v_rcp_f32_e32 v127, v126
	s_nop 0
	v_mul_f32_e32 v124, v124, v127
	v_pk_mul_f32 v[40:41], v[40:41], v[124:125]
	v_and_b32_e32 v125, 0xffff0000, v239
	v_and_b32_e32 v127, 0xffff0000, v243
	v_lshlrev_b32_e32 v124, 16, v239
	v_lshlrev_b32_e32 v126, 16, v243
	v_rcp_f32_e32 v128, v127
	s_nop 0
	v_mul_f32_e32 v125, v125, v128
	s_nop 0
	v_rcp_f32_e32 v127, v126
	s_nop 0
	v_mul_f32_e32 v124, v124, v127
	v_pk_mul_f32 v[42:43], v[42:43], v[124:125]
	v_and_b32_e32 v125, 0xffff0000, v222
	v_and_b32_e32 v127, 0xffff0000, v226
	v_lshlrev_b32_e32 v124, 16, v222
	v_lshlrev_b32_e32 v126, 16, v226
	v_rcp_f32_e32 v128, v127
	s_nop 0
	v_mul_f32_e32 v125, v125, v128
	s_nop 0
	v_rcp_f32_e32 v127, v126
	s_nop 0
	v_mul_f32_e32 v124, v124, v127
	v_pk_mul_f32 v[32:33], v[32:33], v[124:125]
	v_and_b32_e32 v125, 0xffff0000, v223
	v_and_b32_e32 v127, 0xffff0000, v227
	v_lshlrev_b32_e32 v124, 16, v223
	v_lshlrev_b32_e32 v126, 16, v227
	v_rcp_f32_e32 v128, v127
	s_nop 0
	v_mul_f32_e32 v125, v125, v128
	s_nop 0
	v_rcp_f32_e32 v127, v126
	s_nop 0
	v_mul_f32_e32 v124, v124, v127
	v_pk_mul_f32 v[34:35], v[34:35], v[124:125]
	v_and_b32_e32 v125, 0xffff0000, v196
	v_and_b32_e32 v127, 0xffff0000, v200
	v_lshlrev_b32_e32 v124, 16, v196
	v_lshlrev_b32_e32 v126, 16, v200
	v_rcp_f32_e32 v128, v127
	s_nop 0
	v_mul_f32_e32 v125, v125, v128
	s_nop 0
	v_rcp_f32_e32 v127, v126
	s_nop 0
	v_mul_f32_e32 v124, v124, v127
	v_pk_mul_f32 v[24:25], v[24:25], v[124:125]
	v_and_b32_e32 v125, 0xffff0000, v197
	v_and_b32_e32 v127, 0xffff0000, v201
	v_lshlrev_b32_e32 v124, 16, v197
	v_lshlrev_b32_e32 v126, 16, v201
	v_rcp_f32_e32 v128, v127
	s_nop 0
	v_mul_f32_e32 v125, v125, v128
	s_nop 0
	v_rcp_f32_e32 v127, v126
	s_nop 0
	v_mul_f32_e32 v124, v124, v127
	v_pk_mul_f32 v[26:27], v[26:27], v[124:125]
	v_and_b32_e32 v125, 0xffff0000, v166
	v_and_b32_e32 v127, 0xffff0000, v170
	v_lshlrev_b32_e32 v124, 16, v166
	v_lshlrev_b32_e32 v126, 16, v170
	v_or_b32_e32 v166, 0x1000, v164
	v_rcp_f32_e32 v128, v127
	s_nop 0
	v_mul_f32_e32 v125, v125, v128
	s_nop 0
	v_rcp_f32_e32 v127, v126
	s_nop 0
	v_mul_f32_e32 v124, v124, v127
	v_pk_mul_f32 v[16:17], v[16:17], v[124:125]
	v_and_b32_e32 v125, 0xffff0000, v167
	v_and_b32_e32 v127, 0xffff0000, v171
	v_lshlrev_b32_e32 v124, 16, v167
	v_lshlrev_b32_e32 v126, 16, v171
	v_or_b32_e32 v167, 0x1800, v164
	v_rcp_f32_e32 v128, v127
	s_nop 0
	v_mul_f32_e32 v125, v125, v128
	v_and_b32_e32 v137, 15, v140
	v_rcp_f32_e32 v127, v126
	s_nop 0
	v_mul_f32_e32 v124, v124, v127
	v_pk_mul_f32 v[18:19], v[18:19], v[124:125]
	v_ashrrev_i32_e32 v124, 31, v140
	v_lshrrev_b32_e32 v124, 26, v124
	v_add_u32_e32 v124, v140, v124
	v_ashrrev_i32_e32 v150, 6, v124
	v_bfe_i32 v124, v140, 27, 1
	v_lshrrev_b32_e32 v124, 22, v124
	v_add_u32_e32 v124, v141, v124
	v_and_b32_e32 v124, 0xfffffc00, v124
	v_sub_u32_e32 v124, v141, v124
	v_lshrrev_b32_e32 v125, 4, v124
	v_bitop3_b32 v124, v125, v124, 32 bitop3:0x6c
	v_ashrrev_i32_e32 v126, 31, v124
	v_lshrrev_b32_e32 v126, 26, v126
	v_lshlrev_b32_e32 v125, 3, v150
	v_add_u32_e32 v126, v124, v126
	v_and_b32_e32 v125, 0x1ffff0, v125
	v_ashrrev_i32_e32 v151, 6, v126
	v_lshlrev_b32_e32 v127, 5, v150
	v_and_b32_e32 v126, 0xc0, v126
	v_add_u32_e32 v125, v151, v125
	v_and_b32_e32 v152, 32, v127
	v_sub_u32_e32 v124, v124, v126
	v_ashrrev_i16_sdwa v153, v251, sext(v124) dst_sel:DWORD dst_unused:UNUSED_PAD src0_sel:DWORD src1_sel:BYTE_0
	v_lshl_or_b32 v124, v125, 11, v152
	v_ashrrev_i32_e32 v125, 31, v142
; #define WAIT_V(n) asm volatile("s_waitcnt vmcnt(" #n ")" ::: "memory")
; #define BAR __builtin_amdgcn_s_barrier()
; __device__ __forceinline__ void gemm_main(const u16* __restrict__ A, const u16* __restrict__ Bt, const int K, const int Klen,
;                                           const int brow, const int bcol, f32x4 (&acc)[2][2][4][2]) {
;     ...
;   const int wid = tid >> 6, lane = tid & 63, wr = wid >> 2, wc = wid & 3, fr = lane & 15, fq = lane >> 4;
;   const int tid16 = tid * 16;
;   int goff0, goff1;
;   { int R, C; stage_rc(tid16, R, C); goff0 = R * K + C; stage_rc(tid16 + 8192, R, C); goff1 = R * K + C; }
;   bf16x8 At[4][2], B0[2][2], B1[2][2];
;   const int nt = Klen / BK;
;   if (wr == 1) BAR;
;   WAIT_V(4); BAR;
;   STAGE(SB(1, 0), Bt, bcol, 1); STAGE(SA(1, 0), A, brow, 1); STAGE(SB(1, 1), Bt, bcol + HALF, 1);
;   WAIT_V(6); BAR;
	v_lshrrev_b32_e32 v125, 22, v125
	v_add_u32_e32 v125, v142, v125
	v_ashrrev_i32_e32 v154, 10, v125
	v_mul_i32_i24_e32 v125, 0x400, v154
	v_sub_u32_e32 v125, v142, v125
	v_lshrrev_b32_e32 v126, 4, v125
	v_bitop3_b32 v125, v126, v125, 32 bitop3:0x6c
	v_ashrrev_i32_e32 v127, 31, v125
	v_lshrrev_b32_e32 v127, 26, v127
	v_lshlrev_b32_e32 v126, 3, v154
	v_add_u32_e32 v127, v125, v127
	v_and_b32_e32 v126, 0x1ffff0, v126
	v_ashrrev_i32_e32 v155, 6, v127
	v_lshlrev_b32_e32 v128, 5, v154
	v_and_b32_e32 v127, 0xc0, v127
	v_add_u32_e32 v126, v155, v126
	v_and_b32_e32 v156, 32, v128
	v_sub_u32_e32 v125, v125, v127
	v_add_u32_sdwa v124, v124, sext(v153) dst_sel:DWORD dst_unused:UNUSED_PAD src0_sel:DWORD src1_sel:WORD_0
	v_ashrrev_i16_sdwa v157, v251, sext(v125) dst_sel:DWORD dst_unused:UNUSED_PAD src0_sel:DWORD src1_sel:BYTE_0
	v_lshl_or_b32 v125, v126, 11, v156
	v_add_u32_sdwa v126, v125, sext(v157) dst_sel:DWORD dst_unused:UNUSED_PAD src0_sel:DWORD src1_sel:WORD_0
	v_ashrrev_i32_e32 v125, 31, v124
	v_lshlrev_b64 v[128:129], 1, v[124:125]
	v_lshl_add_u64 v[134:135], s[56:57], 0, v[128:129]
	v_lshl_add_u64 v[134:135], v[134:135], 0, s[8:9]
	v_ashrrev_i32_e32 v127, 31, v126
	global_load_lds_dwordx4 v[134:135], off
	v_lshlrev_b64 v[134:135], 1, v[126:127]
	v_lshl_add_u64 v[138:139], s[56:57], 0, v[134:135]
	v_lshl_add_u64 v[138:139], v[138:139], 0, s[8:9]
	s_mov_b32 m0, s11
	v_readfirstlane_b32 s11, v145
	global_load_lds_dwordx4 v[138:139], off
	v_lshl_add_u64 v[138:139], s[58:59], 0, v[128:129]
	v_lshl_add_u64 v[138:139], v[138:139], 0, s[8:9]
	s_mov_b32 m0, s11
	v_readfirstlane_b32 s11, v146
	global_load_lds_dwordx4 v[138:139], off
	v_lshl_add_u64 v[138:139], s[58:59], 0, v[134:135]
	v_lshl_add_u64 v[138:139], v[138:139], 0, s[8:9]
	s_mov_b32 m0, s11
	v_lshl_add_u64 v[128:129], s[60:61], 0, v[128:129]
	v_readfirstlane_b32 s11, v147
	global_load_lds_dwordx4 v[138:139], off
	v_lshl_add_u64 v[128:129], v[128:129], 0, s[8:9]
	s_mov_b32 m0, s11
	v_readfirstlane_b32 s11, v148
	global_load_lds_dwordx4 v[128:129], off
	v_lshl_add_u64 v[128:129], s[60:61], 0, v[134:135]
	v_lshl_add_u64 v[128:129], v[128:129], 0, s[8:9]
	s_mov_b32 m0, s11
	v_lshlrev_b32_e32 v134, 2, v140
	global_load_lds_dwordx4 v[128:129], off
	v_lshlrev_b32_e32 v128, 6, v137
	v_and_b32_e32 v134, 32, v134
	v_or_b32_e32 v129, v128, v149
	v_bitop3_b32 v158, v128, v134, v149 bitop3:0x36
	v_lshlrev_b32_e32 v128, 6, v140
	v_and_b32_e32 v163, 0x3000, v128
	v_and_b32_e32 v128, 0x3c0, v128
	v_bitop3_b32 v159, v129, s75, v134 bitop3:0xde
	v_bitop3_b32 v160, v129, s80, v134 bitop3:0xde
	v_bitop3_b32 v161, v129, s65, v134 bitop3:0xde
	v_bitop3_b32 v162, v129, s73, v134 bitop3:0xde
	v_bitop3_b32 v149, v128, v134, v149 bitop3:0x36
	v_lshlrev_b32_e32 v128, 14, v150
	v_lshlrev_b32_e32 v134, 14, v154
	v_and_b32_e32 v128, 0xffff8000, v128
	v_and_b32_e32 v134, 0xffff8000, v134
	v_lshl_add_u32 v128, v151, 11, v128
	v_lshl_add_u32 v134, v155, 11, v134
	v_or_b32_e32 v128, v128, v152
	v_or_b32_e32 v134, v134, v156
	v_add_u32_sdwa v128, v128, sext(v153) dst_sel:DWORD dst_unused:UNUSED_PAD src0_sel:DWORD src1_sel:WORD_0
	v_add_u32_sdwa v134, v134, sext(v157) dst_sel:DWORD dst_unused:UNUSED_PAD src0_sel:DWORD src1_sel:WORD_0
	v_ashrrev_i32_e32 v129, 31, v128
	v_ashrrev_i32_e32 v135, 31, v134
	v_lshlrev_b64 v[136:137], 1, v[128:129]
	v_lshlrev_b64 v[138:139], 1, v[134:135]
	s_waitcnt vmcnt(6)
	v_lshl_add_u64 v[128:129], s[46:47], 0, v[136:137]
	v_lshl_add_u64 v[134:135], s[46:47], 0, v[138:139]
	s_add_u32 s46, s78, s5
	s_addc_u32 s47, s79, 0
	v_lshl_add_u64 v[136:137], s[46:47], 0, v[136:137]
	v_lshl_add_u64 v[138:139], s[46:47], 0, v[138:139]
	s_mov_b32 s5, -2
	s_mov_b64 s[46:47], 0
	v_add_u32_e32 v156, v159, v163
	v_add_u32_e32 v152, v158, v164
	v_add_u32_e32 v151, v149, v165
	v_add_u32_e32 v150, v149, v166
	v_add_u32_e32 v149, v149, v167
	v_add_u32_e32 v155, v160, v163
	v_add_u32_e32 v154, v161, v163
	v_add_u32_e32 v153, v162, v163
	s_barrier

; __global__ void __launch_bounds__(NTHREADS) fwd_megakernel(Params p) {
;   cg::grid_group grid = cg::this_grid();
	.amdhsa_kernel _Z14fwd_megakernel6Params
		.amdhsa_group_segment_fixed_size 163840
		.amdhsa_private_segment_fixed_size 0
		.amdhsa_kernarg_size 536
		.amdhsa_user_sgpr_count 2
		.amdhsa_user_sgpr_dispatch_ptr 0
		.amdhsa_user_sgpr_queue_ptr 0
		.amdhsa_user_sgpr_kernarg_segment_ptr 1
		.amdhsa_user_sgpr_dispatch_id 0
		.amdhsa_user_sgpr_kernarg_preload_length 0
		.amdhsa_user_sgpr_kernarg_preload_offset 0
		.amdhsa_user_sgpr_private_segment_size 0
		.amdhsa_uses_dynamic_stack 0
		.amdhsa_enable_private_segment 0
		.amdhsa_system_sgpr_workgroup_id_x 1
		.amdhsa_system_sgpr_workgroup_id_y 0
		.amdhsa_system_sgpr_workgroup_id_z 0
		.amdhsa_system_sgpr_workgroup_info 0
		.amdhsa_system_vgpr_workitem_id 2
		.amdhsa_next_free_vgpr 256
		.amdhsa_next_free_sgpr 102
		.amdhsa_accum_offset 256
		.amdhsa_reserve_vcc 1
		.amdhsa_float_round_mode_32 0
		.amdhsa_float_round_mode_16_64 0
		.amdhsa_float_denorm_mode_32 3
		.amdhsa_float_denorm_mode_16_64 3
		.amdhsa_dx10_clamp 1
		.amdhsa_ieee_mode 1
		.amdhsa_fp16_overflow 0
		.amdhsa_tg_split 0
		.amdhsa_exception_fp_ieee_invalid_op 0
		.amdhsa_exception_fp_denorm_src 0
		.amdhsa_exception_fp_ieee_div_zero 0
		.amdhsa_exception_fp_ieee_overflow 0
		.amdhsa_exception_fp_ieee_underflow 0
		.amdhsa_exception_fp_ieee_inexact 0
		.amdhsa_exception_int_div_zero 0
	.end_amdhsa_kernel

; __global__ void __launch_bounds__(NTHREADS) fwd_megakernel(Params p) {
;   cg::grid_group grid = cg::this_grid();
amdhsa.kernels:
  - .agpr_count:     0
    .args:
      - .offset:         0
        .size:           280
        .value_kind:     by_value
      - .offset:         280
        .size:           4
        .value_kind:     hidden_block_count_x
      - .offset:         284
        .size:           4
        .value_kind:     hidden_block_count_y
      - .offset:         288
        .size:           4
        .value_kind:     hidden_block_count_z
      - .offset:         292
        .size:           2
        .value_kind:     hidden_group_size_x
      - .offset:         294
        .size:           2
        .value_kind:     hidden_group_size_y
      - .offset:         296
        .size:           2
        .value_kind:     hidden_group_size_z
      - .offset:         298
        .size:           2
        .value_kind:     hidden_remainder_x
      - .offset:         300
        .size:           2
        .value_kind:     hidden_remainder_y
      - .offset:         302
        .size:           2
        .value_kind:     hidden_remainder_z
      - .offset:         320
        .size:           8
        .value_kind:     hidden_global_offset_x
      - .offset:         328
        .size:           8
        .value_kind:     hidden_global_offset_y
      - .offset:         336
        .size:           8
        .value_kind:     hidden_global_offset_z
      - .offset:         344
        .size:           2
        .value_kind:     hidden_grid_dims
      - .offset:         368
        .size:           8
        .value_kind:     hidden_multigrid_sync_arg
    .group_segment_fixed_size: 163840
    .kernarg_segment_align: 8
    .kernarg_segment_size: 536
    .language:       OpenCL C
    .language_version:
      - 2
      - 0
    .max_flat_workgroup_size: 512
    .name:           _Z14fwd_megakernel6Params
    .private_segment_fixed_size: 0
    .sgpr_count:     108
    .sgpr_spill_count: 12
    .symbol:         _Z14fwd_megakernel6Params.kd
    .uniform_work_group_size: 1
    .uses_dynamic_stack: false
    .vgpr_count:     256
    .vgpr_spill_count: 0
    .wavefront_size: 64
